# instruction selection: accumulator zeroing and staging copies as v_mov_b64 (one issue slot per register pair)
# speedup vs baseline: 1.0128x; 1.0128x over previous
; __device__ __forceinline__ void gemv_item(const Params& p, unsigned long long* MOD, int it, LAS float* scr, int lane) {
;     ...
;     const float* W = p.ada_w + (size_t)mat * DM * 6144 + (size_t)k0 * 6144 + n0;
;     f32x4 a0 = {0, 0, 0, 0}, a1 = a0, a2 = a0, a3 = a0;
; #pragma unroll 16
;     for (int kk = 0; kk < 32; ++kk) { const f32x4 w = *(const f32x4*)(W + (size_t)kk * 6144);
;         a0 += w * scr[kk]; a1 += w * scr[32 + kk]; a2 += w * scr[64 + kk]; a3 += w * scr[96 + kk]; }
;     if (ks == 0) { const f32x4 bv = *(const f32x4*)(p.ada_b + mat * 6144 + n0); a0 += bv; a1 += bv; a2 += bv; a3 += bv; }
.LBB0_61:
	v_lshl_add_u64 v[44:45], v[18:19], 0, s[10:11]
	global_load_dwordx4 v[148:151], v[44:45], off nt
	v_add_co_u32_e32 v218, vcc, s20, v44
	s_nop 1
	v_addc_co_u32_e32 v219, vcc, 0, v45, vcc
	global_load_dwordx4 v[152:155], v[218:219], off nt
	v_add_co_u32_e32 v218, vcc, s22, v44
	s_nop 1
	v_addc_co_u32_e32 v219, vcc, 0, v45, vcc
	global_load_dwordx4 v[156:159], v[218:219], off nt
	v_add_co_u32_e32 v218, vcc, s35, v44
	s_nop 1
	v_addc_co_u32_e32 v219, vcc, 0, v45, vcc
	global_load_dwordx4 v[160:163], v[218:219], off nt
	v_add_co_u32_e32 v218, vcc, s23, v44
	s_nop 1
	v_addc_co_u32_e32 v219, vcc, 0, v45, vcc
	global_load_dwordx4 v[164:167], v[218:219], off nt
	v_add_co_u32_e32 v218, vcc, s36, v44
	s_nop 1
	v_addc_co_u32_e32 v219, vcc, 0, v45, vcc
	global_load_dwordx4 v[168:171], v[218:219], off nt
	v_add_co_u32_e32 v218, vcc, s43, v44
	s_nop 1
	v_addc_co_u32_e32 v219, vcc, 0, v45, vcc
	global_load_dwordx4 v[172:175], v[218:219], off nt
	v_add_co_u32_e32 v218, vcc, s44, v44
	s_nop 1
	v_addc_co_u32_e32 v219, vcc, 0, v45, vcc
	global_load_dwordx4 v[176:179], v[218:219], off nt
	v_add_co_u32_e32 v218, vcc, s25, v44
	s_nop 1
	v_addc_co_u32_e32 v219, vcc, 0, v45, vcc
	global_load_dwordx4 v[180:183], v[218:219], off nt
	v_add_co_u32_e32 v218, vcc, s45, v44
	s_nop 1
	v_addc_co_u32_e32 v219, vcc, 0, v45, vcc
	global_load_dwordx4 v[184:187], v[218:219], off nt
	v_add_co_u32_e32 v218, vcc, s46, v44
	s_nop 1
	v_addc_co_u32_e32 v219, vcc, 0, v45, vcc
	global_load_dwordx4 v[188:191], v[218:219], off nt
	v_add_co_u32_e32 v218, vcc, s47, v44
	s_nop 1
	v_addc_co_u32_e32 v219, vcc, 0, v45, vcc
	global_load_dwordx4 v[192:195], v[218:219], off nt
	v_add_co_u32_e32 v218, vcc, s27, v44
	s_nop 1
	v_addc_co_u32_e32 v219, vcc, 0, v45, vcc
	global_load_dwordx4 v[202:205], v[218:219], off nt
	v_add_co_u32_e32 v218, vcc, s48, v44
	s_nop 1
	v_addc_co_u32_e32 v219, vcc, 0, v45, vcc
	global_load_dwordx4 v[206:209], v[218:219], off nt
	v_add_co_u32_e32 v218, vcc, s49, v44
	s_nop 1
	v_addc_co_u32_e32 v219, vcc, 0, v45, vcc
	global_load_dwordx4 v[210:213], v[218:219], off nt
	v_add_co_u32_e32 v218, vcc, s50, v44
	s_nop 1
	v_addc_co_u32_e32 v219, vcc, 0, v45, vcc
	global_load_dwordx4 v[214:217], v[218:219], off nt
	s_waitcnt vmcnt(15)
	v_mov_b64_e32 v[20:21], v[148:149]
	v_mov_b64_e32 v[22:23], v[150:151]
	v_mov_b32_e32 v54, s54
	ds_read_b128 v[24:27], v54
	ds_read_b128 v[28:31], v54 offset:16
	ds_read_b128 v[32:35], v54 offset:32
	ds_read_b128 v[36:39], v54 offset:48
	ds_read_b128 v[40:43], v54 offset:128
	s_add_u32 s10, s10, 0x60000
	s_addc_u32 s11, s11, 0
	s_add_i32 s54, s54, 64
	s_cmp_eq_u32 s10, 0xc0000
	s_waitcnt lgkmcnt(4)
	v_pk_fma_f32 v[46:47], v[22:23], v[24:25], v[4:5] op_sel_hi:[1,0,1]
	v_pk_fma_f32 v[48:49], v[20:21], v[24:25], v[14:15] op_sel_hi:[1,0,1]
	s_waitcnt lgkmcnt(0)
	v_pk_fma_f32 v[50:51], v[22:23], v[40:41], v[2:3] op_sel_hi:[1,0,1]
	v_pk_fma_f32 v[52:53], v[20:21], v[40:41], v[12:13] op_sel_hi:[1,0,1]
	ds_read_b128 v[2:5], v54 offset:256
	ds_read_b128 v[12:15], v54 offset:384
	s_waitcnt lgkmcnt(1)
	v_pk_fma_f32 v[16:17], v[20:21], v[2:3], v[16:17] op_sel_hi:[1,0,1]
	s_waitcnt lgkmcnt(0)
	v_pk_fma_f32 v[10:11], v[20:21], v[12:13], v[10:11] op_sel_hi:[1,0,1]
	v_add_co_u32_e32 v20, vcc, s20, v44
	v_pk_fma_f32 v[6:7], v[22:23], v[2:3], v[6:7] op_sel_hi:[1,0,1]
	s_nop 0
	v_addc_co_u32_e32 v21, vcc, 0, v45, vcc
	v_pk_fma_f32 v[0:1], v[22:23], v[12:13], v[0:1] op_sel_hi:[1,0,1]
	s_waitcnt vmcnt(14)
	v_mov_b64_e32 v[20:21], v[152:153]
	v_mov_b64_e32 v[22:23], v[154:155]
	v_pk_fma_f32 v[10:11], v[20:21], v[12:13], v[10:11] op_sel:[0,1,0]
	v_pk_fma_f32 v[12:13], v[22:23], v[12:13], v[0:1] op_sel:[0,1,0]
	v_add_co_u32_e32 v0, vcc, s22, v44
	v_pk_fma_f32 v[16:17], v[20:21], v[2:3], v[16:17] op_sel:[0,1,0]
	s_nop 0
	v_addc_co_u32_e32 v1, vcc, 0, v45, vcc
	v_pk_fma_f32 v[6:7], v[22:23], v[2:3], v[6:7] op_sel:[0,1,0]
	s_waitcnt vmcnt(13)
	v_mov_b64_e32 v[0:1], v[156:157]
	v_mov_b64_e32 v[2:3], v[158:159]
	v_pk_fma_f32 v[48:49], v[20:21], v[24:25], v[48:49] op_sel:[0,1,0]
	v_pk_fma_f32 v[24:25], v[22:23], v[24:25], v[46:47] op_sel:[0,1,0]
	v_pk_fma_f32 v[46:47], v[20:21], v[40:41], v[52:53] op_sel:[0,1,0]
	v_pk_fma_f32 v[40:41], v[22:23], v[40:41], v[50:51] op_sel:[0,1,0]
	v_pk_fma_f32 v[20:21], v[2:3], v[26:27], v[24:25] op_sel_hi:[1,0,1]
	v_pk_fma_f32 v[22:23], v[0:1], v[26:27], v[48:49] op_sel_hi:[1,0,1]
	v_pk_fma_f32 v[24:25], v[2:3], v[42:43], v[40:41] op_sel_hi:[1,0,1]
	v_pk_fma_f32 v[40:41], v[0:1], v[42:43], v[46:47] op_sel_hi:[1,0,1]
	v_pk_fma_f32 v[16:17], v[0:1], v[4:5], v[16:17] op_sel_hi:[1,0,1]
	v_pk_fma_f32 v[10:11], v[0:1], v[14:15], v[10:11] op_sel_hi:[1,0,1]
	v_add_co_u32_e32 v0, vcc, s35, v44
	v_pk_fma_f32 v[6:7], v[2:3], v[4:5], v[6:7] op_sel_hi:[1,0,1]
	s_nop 0
	v_addc_co_u32_e32 v1, vcc, 0, v45, vcc
	v_pk_fma_f32 v[12:13], v[2:3], v[14:15], v[12:13] op_sel_hi:[1,0,1]
	s_waitcnt vmcnt(12)
	v_mov_b64_e32 v[0:1], v[160:161]
	v_mov_b64_e32 v[2:3], v[162:163]
	v_mov_b32_e32 v4, v27
	v_pk_fma_f32 v[20:21], v[2:3], v[4:5], v[20:21] op_sel_hi:[1,0,1]
	v_pk_fma_f32 v[22:23], v[0:1], v[4:5], v[22:23] op_sel_hi:[1,0,1]
	v_mov_b32_e32 v4, v43
	v_pk_fma_f32 v[24:25], v[2:3], v[4:5], v[24:25] op_sel_hi:[1,0,1]
	v_pk_fma_f32 v[26:27], v[0:1], v[4:5], v[40:41] op_sel_hi:[1,0,1]
	v_mov_b32_e32 v4, v5
	v_pk_fma_f32 v[40:41], v[2:3], v[4:5], v[6:7] op_sel_hi:[1,0,1]
	v_pk_fma_f32 v[16:17], v[0:1], v[4:5], v[16:17] op_sel_hi:[1,0,1]
	v_mov_b32_e32 v4, v15
	v_pk_fma_f32 v[46:47], v[0:1], v[4:5], v[10:11] op_sel_hi:[1,0,1]
	v_add_co_u32_e32 v0, vcc, s23, v44
	v_pk_fma_f32 v[42:43], v[2:3], v[4:5], v[12:13] op_sel_hi:[1,0,1]
	s_nop 0
	v_addc_co_u32_e32 v1, vcc, 0, v45, vcc
	s_waitcnt vmcnt(11)
; __device__ __forceinline__ void gemv_item(const Params& p, unsigned long long* MOD, int it, LAS float* scr, int lane) {
;     ...
;     for (int kk = 0; kk < 32; ++kk) { const f32x4 w = *(const f32x4*)(W + (size_t)kk * 6144);
;         a0 += w * scr[kk]; a1 += w * scr[32 + kk]; a2 += w * scr[64 + kk]; a3 += w * scr[96 + kk]; }
	v_mov_b64_e32 v[0:1], v[164:165]
	v_mov_b64_e32 v[2:3], v[166:167]
	ds_read_b128 v[4:7], v54 offset:144
	ds_read_b128 v[10:13], v54 offset:272
	s_waitcnt lgkmcnt(0)
	v_pk_fma_f32 v[48:49], v[0:1], v[10:11], v[16:17] op_sel_hi:[1,0,1]
	ds_read_b128 v[14:17], v54 offset:400
	v_pk_fma_f32 v[22:23], v[0:1], v[28:29], v[22:23] op_sel_hi:[1,0,1]
	v_pk_fma_f32 v[26:27], v[0:1], v[4:5], v[26:27] op_sel_hi:[1,0,1]
	v_pk_fma_f32 v[20:21], v[2:3], v[28:29], v[20:21] op_sel_hi:[1,0,1]
	v_pk_fma_f32 v[24:25], v[2:3], v[4:5], v[24:25] op_sel_hi:[1,0,1]
	s_waitcnt lgkmcnt(0)
	v_pk_fma_f32 v[46:47], v[0:1], v[14:15], v[46:47] op_sel_hi:[1,0,1]
	v_add_co_u32_e32 v0, vcc, s36, v44
	v_pk_fma_f32 v[40:41], v[2:3], v[10:11], v[40:41] op_sel_hi:[1,0,1]
	s_nop 0
	v_addc_co_u32_e32 v1, vcc, 0, v45, vcc
	v_pk_fma_f32 v[42:43], v[2:3], v[14:15], v[42:43] op_sel_hi:[1,0,1]
	s_waitcnt vmcnt(10)
	v_mov_b64_e32 v[0:1], v[168:169]
	v_mov_b64_e32 v[2:3], v[170:171]
	v_pk_fma_f32 v[20:21], v[2:3], v[28:29], v[20:21] op_sel:[0,1,0]
	v_pk_fma_f32 v[22:23], v[0:1], v[28:29], v[22:23] op_sel:[0,1,0]
	v_pk_fma_f32 v[24:25], v[2:3], v[4:5], v[24:25] op_sel:[0,1,0]
	v_pk_fma_f32 v[4:5], v[0:1], v[4:5], v[26:27] op_sel:[0,1,0]
	v_pk_fma_f32 v[26:27], v[2:3], v[10:11], v[40:41] op_sel:[0,1,0]
	v_pk_fma_f32 v[10:11], v[0:1], v[10:11], v[48:49] op_sel:[0,1,0]
	v_pk_fma_f32 v[28:29], v[2:3], v[14:15], v[42:43] op_sel:[0,1,0]
	v_pk_fma_f32 v[14:15], v[0:1], v[14:15], v[46:47] op_sel:[0,1,0]
	v_add_co_u32_e32 v0, vcc, s43, v44
	s_nop 1
	v_addc_co_u32_e32 v1, vcc, 0, v45, vcc
	s_waitcnt vmcnt(9)
	v_mov_b64_e32 v[0:1], v[172:173]
	v_mov_b64_e32 v[2:3], v[174:175]
	v_pk_fma_f32 v[22:23], v[0:1], v[30:31], v[22:23] op_sel_hi:[1,0,1]
	v_pk_fma_f32 v[4:5], v[0:1], v[6:7], v[4:5] op_sel_hi:[1,0,1]
	v_pk_fma_f32 v[10:11], v[0:1], v[12:13], v[10:11] op_sel_hi:[1,0,1]
	v_pk_fma_f32 v[14:15], v[0:1], v[16:17], v[14:15] op_sel_hi:[1,0,1]
	v_add_co_u32_e32 v0, vcc, s44, v44
	v_pk_fma_f32 v[20:21], v[2:3], v[30:31], v[20:21] op_sel_hi:[1,0,1]
	s_nop 0
	v_addc_co_u32_e32 v1, vcc, 0, v45, vcc
	v_pk_fma_f32 v[24:25], v[2:3], v[6:7], v[24:25] op_sel_hi:[1,0,1]
	v_pk_fma_f32 v[26:27], v[2:3], v[12:13], v[26:27] op_sel_hi:[1,0,1]
	v_pk_fma_f32 v[28:29], v[2:3], v[16:17], v[28:29] op_sel_hi:[1,0,1]
	s_waitcnt vmcnt(8)
	v_mov_b64_e32 v[0:1], v[176:177]
	v_mov_b64_e32 v[2:3], v[178:179]
	v_mov_b32_e32 v6, v31
	v_pk_fma_f32 v[20:21], v[2:3], v[6:7], v[20:21] op_sel_hi:[1,0,1]
	v_pk_fma_f32 v[22:23], v[0:1], v[6:7], v[22:23] op_sel_hi:[1,0,1]
	v_mov_b32_e32 v6, v7
	v_pk_fma_f32 v[30:31], v[0:1], v[6:7], v[4:5] op_sel_hi:[1,0,1]
	v_mov_b32_e32 v4, v13
	v_pk_fma_f32 v[26:27], v[2:3], v[4:5], v[26:27] op_sel_hi:[1,0,1]
	v_pk_fma_f32 v[40:41], v[0:1], v[4:5], v[10:11] op_sel_hi:[1,0,1]
	v_mov_b32_e32 v4, v17
	v_pk_fma_f32 v[42:43], v[0:1], v[4:5], v[14:15] op_sel_hi:[1,0,1]
	v_add_co_u32_e32 v0, vcc, s25, v44
	v_pk_fma_f32 v[24:25], v[2:3], v[6:7], v[24:25] op_sel_hi:[1,0,1]
	s_nop 0
	v_addc_co_u32_e32 v1, vcc, 0, v45, vcc
	v_pk_fma_f32 v[28:29], v[2:3], v[4:5], v[28:29] op_sel_hi:[1,0,1]
	s_waitcnt vmcnt(7)
	v_mov_b64_e32 v[0:1], v[180:181]
	v_mov_b64_e32 v[2:3], v[182:183]
	ds_read_b128 v[4:7], v54 offset:160
	ds_read_b128 v[10:13], v54 offset:288
	ds_read_b128 v[14:17], v54 offset:416
	v_pk_fma_f32 v[22:23], v[0:1], v[32:33], v[22:23] op_sel_hi:[1,0,1]
	s_waitcnt lgkmcnt(2)
	v_pk_fma_f32 v[30:31], v[0:1], v[4:5], v[30:31] op_sel_hi:[1,0,1]
	s_waitcnt lgkmcnt(1)
	v_pk_fma_f32 v[40:41], v[0:1], v[10:11], v[40:41] op_sel_hi:[1,0,1]
	s_waitcnt lgkmcnt(0)
	v_pk_fma_f32 v[42:43], v[0:1], v[14:15], v[42:43] op_sel_hi:[1,0,1]
	v_add_co_u32_e32 v0, vcc, s45, v44
	v_pk_fma_f32 v[20:21], v[2:3], v[32:33], v[20:21] op_sel_hi:[1,0,1]
	s_nop 0
	v_addc_co_u32_e32 v1, vcc, 0, v45, vcc
	v_pk_fma_f32 v[24:25], v[2:3], v[4:5], v[24:25] op_sel_hi:[1,0,1]
	v_pk_fma_f32 v[26:27], v[2:3], v[10:11], v[26:27] op_sel_hi:[1,0,1]
	v_pk_fma_f32 v[28:29], v[2:3], v[14:15], v[28:29] op_sel_hi:[1,0,1]
	s_waitcnt vmcnt(6)
	v_mov_b64_e32 v[0:1], v[184:185]
	v_mov_b64_e32 v[2:3], v[186:187]
	v_pk_fma_f32 v[22:23], v[0:1], v[32:33], v[22:23] op_sel:[0,1,0]
	v_pk_fma_f32 v[24:25], v[2:3], v[4:5], v[24:25] op_sel:[0,1,0]
	v_pk_fma_f32 v[4:5], v[0:1], v[4:5], v[30:31] op_sel:[0,1,0]
	v_pk_fma_f32 v[26:27], v[2:3], v[10:11], v[26:27] op_sel:[0,1,0]
	v_pk_fma_f32 v[10:11], v[0:1], v[10:11], v[40:41] op_sel:[0,1,0]
	v_pk_fma_f32 v[28:29], v[2:3], v[14:15], v[28:29] op_sel:[0,1,0]
	v_pk_fma_f32 v[14:15], v[0:1], v[14:15], v[42:43] op_sel:[0,1,0]
	v_add_co_u32_e32 v0, vcc, s46, v44
	v_pk_fma_f32 v[20:21], v[2:3], v[32:33], v[20:21] op_sel:[0,1,0]
	s_nop 0
	v_addc_co_u32_e32 v1, vcc, 0, v45, vcc
	s_waitcnt vmcnt(5)
; __device__ __forceinline__ void gemv_item(const Params& p, unsigned long long* MOD, int it, LAS float* scr, int lane) {
;     ...
;     for (int kk = 0; kk < 32; ++kk) { const f32x4 w = *(const f32x4*)(W + (size_t)kk * 6144);
;         a0 += w * scr[kk]; a1 += w * scr[32 + kk]; a2 += w * scr[64 + kk]; a3 += w * scr[96 + kk]; }
;     if (ks == 0) { const f32x4 bv = *(const f32x4*)(p.ada_b + mat * 6144 + n0); a0 += bv; a1 += bv; a2 += bv; a3 += bv; }
	v_mov_b64_e32 v[0:1], v[188:189]
	v_mov_b64_e32 v[2:3], v[190:191]
	v_pk_fma_f32 v[22:23], v[0:1], v[34:35], v[22:23] op_sel_hi:[1,0,1]
	v_pk_fma_f32 v[4:5], v[0:1], v[6:7], v[4:5] op_sel_hi:[1,0,1]
	v_pk_fma_f32 v[10:11], v[0:1], v[12:13], v[10:11] op_sel_hi:[1,0,1]
	v_pk_fma_f32 v[14:15], v[0:1], v[16:17], v[14:15] op_sel_hi:[1,0,1]
	v_add_co_u32_e32 v0, vcc, s47, v44
	v_pk_fma_f32 v[20:21], v[2:3], v[34:35], v[20:21] op_sel_hi:[1,0,1]
	s_nop 0
	v_addc_co_u32_e32 v1, vcc, 0, v45, vcc
	v_pk_fma_f32 v[24:25], v[2:3], v[6:7], v[24:25] op_sel_hi:[1,0,1]
	v_pk_fma_f32 v[26:27], v[2:3], v[12:13], v[26:27] op_sel_hi:[1,0,1]
	v_pk_fma_f32 v[28:29], v[2:3], v[16:17], v[28:29] op_sel_hi:[1,0,1]
	s_waitcnt vmcnt(4)
	v_mov_b64_e32 v[0:1], v[192:193]
	v_mov_b64_e32 v[2:3], v[194:195]
	v_mov_b32_e32 v6, v35
	v_pk_fma_f32 v[20:21], v[2:3], v[6:7], v[20:21] op_sel_hi:[1,0,1]
	v_pk_fma_f32 v[22:23], v[0:1], v[6:7], v[22:23] op_sel_hi:[1,0,1]
	v_mov_b32_e32 v6, v7
	v_pk_fma_f32 v[30:31], v[0:1], v[6:7], v[4:5] op_sel_hi:[1,0,1]
	v_mov_b32_e32 v4, v13
	v_pk_fma_f32 v[12:13], v[2:3], v[4:5], v[26:27] op_sel_hi:[1,0,1]
	v_pk_fma_f32 v[10:11], v[0:1], v[4:5], v[10:11] op_sel_hi:[1,0,1]
	v_mov_b32_e32 v4, v17
	v_pk_fma_f32 v[26:27], v[2:3], v[4:5], v[28:29] op_sel_hi:[1,0,1]
	v_pk_fma_f32 v[28:29], v[0:1], v[4:5], v[14:15] op_sel_hi:[1,0,1]
	v_add_co_u32_e32 v0, vcc, s27, v44
	v_pk_fma_f32 v[24:25], v[2:3], v[6:7], v[24:25] op_sel_hi:[1,0,1]
	s_nop 0
	v_addc_co_u32_e32 v1, vcc, 0, v45, vcc
	s_waitcnt vmcnt(3)
	v_mov_b64_e32 v[0:1], v[202:203]
	v_mov_b64_e32 v[2:3], v[204:205]
	ds_read_b128 v[4:7], v54 offset:176
	ds_read_b128 v[14:17], v54 offset:304
	v_pk_fma_f32 v[32:33], v[2:3], v[36:37], v[20:21] op_sel_hi:[1,0,1]
	v_pk_fma_f32 v[34:35], v[0:1], v[36:37], v[22:23] op_sel_hi:[1,0,1]
	ds_read_b128 v[20:23], v54 offset:432
	s_waitcnt lgkmcnt(2)
	v_pk_fma_f32 v[30:31], v[0:1], v[4:5], v[30:31] op_sel_hi:[1,0,1]
	s_waitcnt lgkmcnt(1)
	v_pk_fma_f32 v[10:11], v[0:1], v[14:15], v[10:11] op_sel_hi:[1,0,1]
	v_pk_fma_f32 v[24:25], v[2:3], v[4:5], v[24:25] op_sel_hi:[1,0,1]
	v_pk_fma_f32 v[12:13], v[2:3], v[14:15], v[12:13] op_sel_hi:[1,0,1]
	s_waitcnt lgkmcnt(0)
	v_pk_fma_f32 v[28:29], v[0:1], v[20:21], v[28:29] op_sel_hi:[1,0,1]
	v_add_co_u32_e32 v0, vcc, s48, v44
	v_pk_fma_f32 v[26:27], v[2:3], v[20:21], v[26:27] op_sel_hi:[1,0,1]
	s_nop 0
	v_addc_co_u32_e32 v1, vcc, 0, v45, vcc
	s_waitcnt vmcnt(2)
	v_mov_b64_e32 v[0:1], v[206:207]
	v_mov_b64_e32 v[2:3], v[208:209]
	v_pk_fma_f32 v[34:35], v[0:1], v[36:37], v[34:35] op_sel:[0,1,0]
	v_pk_fma_f32 v[24:25], v[2:3], v[4:5], v[24:25] op_sel:[0,1,0]
	v_pk_fma_f32 v[4:5], v[0:1], v[4:5], v[30:31] op_sel:[0,1,0]
	v_pk_fma_f32 v[12:13], v[2:3], v[14:15], v[12:13] op_sel:[0,1,0]
	v_pk_fma_f32 v[10:11], v[0:1], v[14:15], v[10:11] op_sel:[0,1,0]
	v_pk_fma_f32 v[14:15], v[2:3], v[20:21], v[26:27] op_sel:[0,1,0]
	v_pk_fma_f32 v[20:21], v[0:1], v[20:21], v[28:29] op_sel:[0,1,0]
	v_add_co_u32_e32 v0, vcc, s49, v44
	v_pk_fma_f32 v[32:33], v[2:3], v[36:37], v[32:33] op_sel:[0,1,0]
	s_nop 0
	v_addc_co_u32_e32 v1, vcc, 0, v45, vcc
	s_waitcnt vmcnt(1)
	v_mov_b64_e32 v[0:1], v[210:211]
	v_mov_b64_e32 v[2:3], v[212:213]
	v_pk_fma_f32 v[30:31], v[0:1], v[38:39], v[34:35] op_sel_hi:[1,0,1]
	v_pk_fma_f32 v[34:35], v[0:1], v[6:7], v[4:5] op_sel_hi:[1,0,1]
	v_pk_fma_f32 v[10:11], v[0:1], v[16:17], v[10:11] op_sel_hi:[1,0,1]
	v_pk_fma_f32 v[20:21], v[0:1], v[22:23], v[20:21] op_sel_hi:[1,0,1]
	v_add_co_u32_e32 v0, vcc, s50, v44
	v_pk_fma_f32 v[28:29], v[2:3], v[38:39], v[32:33] op_sel_hi:[1,0,1]
	s_nop 0
	v_addc_co_u32_e32 v1, vcc, 0, v45, vcc
	v_pk_fma_f32 v[32:33], v[2:3], v[6:7], v[24:25] op_sel_hi:[1,0,1]
	s_waitcnt vmcnt(0)
	v_mov_b64_e32 v[24:25], v[214:215]
	v_mov_b64_e32 v[26:27], v[216:217]
	v_mov_b32_e32 v0, v39
	v_pk_fma_f32 v[40:41], v[2:3], v[22:23], v[14:15] op_sel_hi:[1,0,1]
	v_pk_fma_f32 v[36:37], v[2:3], v[16:17], v[12:13] op_sel_hi:[1,0,1]
	v_pk_fma_f32 v[4:5], v[26:27], v[0:1], v[28:29] op_sel_hi:[1,0,1]
	v_pk_fma_f32 v[14:15], v[24:25], v[0:1], v[30:31] op_sel_hi:[1,0,1]
	v_mov_b32_e32 v0, v7
	v_pk_fma_f32 v[2:3], v[26:27], v[0:1], v[32:33] op_sel_hi:[1,0,1]
	v_pk_fma_f32 v[12:13], v[24:25], v[0:1], v[34:35] op_sel_hi:[1,0,1]
	v_mov_b32_e32 v0, v17
	v_pk_fma_f32 v[16:17], v[24:25], v[0:1], v[10:11] op_sel_hi:[1,0,1]
	v_mov_b32_e32 v10, v23
	v_pk_fma_f32 v[6:7], v[26:27], v[0:1], v[36:37] op_sel_hi:[1,0,1]
	v_pk_fma_f32 v[0:1], v[26:27], v[10:11], v[40:41] op_sel_hi:[1,0,1]
	v_pk_fma_f32 v[10:11], v[24:25], v[10:11], v[20:21] op_sel_hi:[1,0,1]
	s_cbranch_scc0 .LBB0_61
	s_cmp_eq_u32 s53, 0
	s_cbranch_scc0 .LBB0_29
	s_mul_i32 s0, s2, 0x1800
	s_ashr_i32 s1, s0, 31
	s_lshl_b64 s[0:1], s[0:1], 2
	s_add_u32 s0, s86, s0
	s_addc_u32 s1, s87, s1
	v_lshl_add_u64 v[18:19], v[8:9], 2, s[0:1]
	global_load_dwordx4 v[18:21], v[18:19], off
	s_waitcnt vmcnt(0)
	v_pk_add_f32 v[4:5], v[4:5], v[20:21]
	v_pk_add_f32 v[14:15], v[14:15], v[18:19]
	v_pk_add_f32 v[2:3], v[2:3], v[20:21]
	v_pk_add_f32 v[12:13], v[12:13], v[18:19]
	v_pk_add_f32 v[6:7], v[6:7], v[20:21]
	v_pk_add_f32 v[16:17], v[16:17], v[18:19]
	v_pk_add_f32 v[0:1], v[0:1], v[20:21]
	v_pk_add_f32 v[10:11], v[10:11], v[18:19]
	s_branch .LBB0_29

; template <bool FINAL>
; __device__ __forceinline__ void norm_phase(const float* X, const float* mod, bf16_t* H, const float* fg, float* OUT, const unsigned long long* acc64 = nullptr, float* modf = nullptr) {
;     ...
;     for (int r = gw; r < MTOK; r += NGW) {
;         const f32x4* xr = (const f32x4*)(X + (size_t)r * DM) + lane;
;         f32x4 v[8]; float ss = 0.f;
; #pragma unroll
;         for (int j = 0; j < 8; ++j) { v[j] = xr[64 * j]; ss += (v[j][0] * v[j][0] + v[j][1] * v[j][1]) + (v[j][2] * v[j][2] + v[j][3] * v[j][3]); }
;         const float rstd = rsqrtf(wave_sum(ss) * (1.0f / DM) + EPS);
;         if (FINAL) {
; #pragma unroll
;             for (int j = 0; j < 8; ++j) { const f32x4 g = *((const f32x4*)fg + lane + 64 * j); *((f32x4*)(OUT + (size_t)r * DM) + lane + 64 * j) = v[j] * rstd * g; }
;         } else {
;             const float* mb = mod + (r >> 12) * 6144; const unsigned long long* mb64 = acc64 + (r >> 12) * 6144;
; #pragma unroll
;             for (int j = 0; j < 8; ++j) { const f32x4 sh = acc64 ? ld_fx4(mb64 + 4 * (lane + 64 * j)) : *((const f32x4*)mb + lane + 64 * j), sc = acc64 ? ld_fx4(mb64 + DM + 4 * (lane + 64 * j)) : *((const f32x4*)(mb + DM) + lane + 64 * j);
.LBB0_121:
	v_ashrrev_i32_e32 v40, 12, v32
	v_mul_i32_i24_e32 v40, 0x1800, v40
	v_ashrrev_i32_e32 v41, 31, v40
	v_add_u32_e32 v32, s4, v32
	v_lshl_add_u64 v[40:41], v[40:41], 3, s[6:7]
	global_load_dwordx4 v[4:7], v[36:37], off offset:-4096
	global_load_dwordx4 v[0:3], v[36:37], off offset:-3072
	global_load_dwordx4 v[8:11], v[36:37], off offset:-2048
	global_load_dwordx4 v[12:15], v[36:37], off
	global_load_dwordx4 v[16:19], v[36:37], off offset:1024
	global_load_dwordx4 v[20:23], v[36:37], off offset:-1024
	global_load_dwordx4 v[24:27], v[36:37], off offset:3072
	global_load_dwordx4 v[28:31], v[36:37], off offset:2048
	v_cmp_lt_i32_e32 vcc, s46, v32
	v_lshl_add_u64 v[98:99], v[40:41], 0, v[34:35]
	s_or_b64 s[12:13], vcc, s[12:13]
	global_load_dwordx4 v[82:85], v[98:99], off offset:16
	global_load_dwordx4 v[86:89], v[98:99], off
	v_add_co_u32_e32 v64, vcc, s33, v98
	v_lshl_add_u64 v[100:101], v[98:99], 0, s[14:15]
	s_nop 0
	v_addc_co_u32_e32 v65, vcc, 0, v99, vcc
	global_load_dwordx4 v[90:93], v[64:65], off offset:-4096
	global_load_dwordx4 v[94:97], v[100:101], off offset:16
	v_add_co_u32_e32 v66, vcc, s17, v98
	v_lshl_add_u64 v[72:73], v[98:99], 0, s[2:3]
	s_nop 0
	v_addc_co_u32_e32 v67, vcc, 0, v99, vcc
	v_add_co_u32_e32 v52, vcc, s42, v98
	v_lshl_add_u64 v[74:75], v[98:99], 0, s[18:19]
	s_nop 0
	v_addc_co_u32_e32 v53, vcc, 0, v99, vcc
	v_add_co_u32_e32 v54, vcc, s43, v98
	v_lshl_add_u64 v[70:71], v[98:99], 0, s[20:21]
	s_nop 0
	v_addc_co_u32_e32 v55, vcc, 0, v99, vcc
	v_add_co_u32_e32 v40, vcc, s45, v98
	v_lshl_add_u64 v[68:69], v[98:99], 0, s[22:23]
	s_nop 0
	v_addc_co_u32_e32 v41, vcc, 0, v99, vcc
	v_add_co_u32_e32 v42, vcc, s44, v98
	v_lshl_add_u64 v[62:63], v[98:99], 0, s[24:25]
	s_nop 0
	v_addc_co_u32_e32 v43, vcc, 0, v99, vcc
	v_lshl_add_u64 v[60:61], v[98:99], 0, s[26:27]
	v_lshl_add_u64 v[58:59], v[98:99], 0, s[28:29]
	v_lshl_add_u64 v[56:57], v[98:99], 0, s[30:31]
	v_lshl_add_u64 v[48:49], v[98:99], 0, s[34:35]
	v_lshl_add_u64 v[50:51], v[98:99], 0, s[36:37]
	v_lshl_add_u64 v[46:47], v[98:99], 0, s[38:39]
	v_lshl_add_u64 v[44:45], v[98:99], 0, s[40:41]
	v_lshl_add_u64 v[36:37], v[36:37], 0, s[8:9]
	global_load_dwordx4 v[136:139], v[98:99], off offset:2048
	global_load_dwordx4 v[140:143], v[98:99], off offset:2064
	global_load_dwordx4 v[144:147], v[100:101], off offset:2048
	global_load_dwordx4 v[148:151], v[100:101], off offset:2064
	global_load_dwordx4 v[152:155], v[52:53], off offset:-4096
	global_load_dwordx4 v[156:159], v[72:73], off offset:16
	global_load_dwordx4 v[160:163], v[64:65], off
	global_load_dwordx4 v[164:167], v[74:75], off offset:16
	global_load_dwordx4 v[168:171], v[66:67], off offset:2048
	global_load_dwordx4 v[172:175], v[70:71], off offset:16
	global_load_dwordx4 v[176:179], v[64:65], off offset:2048
	global_load_dwordx4 v[180:183], v[68:69], off offset:16
	global_load_dwordx4 v[184:187], v[52:53], off
	global_load_dwordx4 v[188:191], v[62:63], off offset:16
	global_load_dwordx4 v[196:199], v[40:41], off offset:-4096
	global_load_dwordx4 v[202:205], v[60:61], off offset:16
	global_load_dwordx4 v[206:209], v[52:53], off offset:2048
	global_load_dwordx4 v[210:213], v[58:59], off offset:16
	global_load_dwordx4 v[214:217], v[54:55], off offset:2048
	global_load_dwordx4 v[218:221], v[56:57], off offset:16
	global_load_dwordx4 v[222:225], v[42:43], off
	global_load_dwordx4 v[226:229], v[48:49], off offset:16
	global_load_dwordx4 v[230:233], v[40:41], off
	global_load_dwordx4 v[234:237], v[50:51], off offset:16
	global_load_dwordx4 v[238:241], v[42:43], off offset:2048
	global_load_dwordx4 v[242:245], v[46:47], off offset:16
	global_load_dwordx4 v[246:249], v[40:41], off offset:2048
	global_load_dwordx4 v[250:253], v[44:45], off offset:16
	s_waitcnt vmcnt(39)
	v_mov_b32_e32 v104, v5
	s_waitcnt vmcnt(38)
	v_mov_b32_e32 v105, v1
	v_mov_b32_e32 v108, v7
	v_mov_b32_e32 v109, v3
	v_mov_b32_e32 v102, v4
	v_mov_b32_e32 v103, v0
	v_mov_b32_e32 v106, v6
	v_mov_b32_e32 v107, v2
	s_waitcnt vmcnt(37)
	v_pk_mul_f32 v[110:111], v[10:11], v[10:11]
	v_pk_mul_f32 v[112:113], v[8:9], v[8:9]
	v_pk_mul_f32 v[104:105], v[104:105], v[104:105]
	v_pk_mul_f32 v[108:109], v[108:109], v[108:109]
	v_pk_mov_b32 v[126:127], v[112:113], v[110:111] op_sel:[1,0]
	v_mov_b32_e32 v113, v111
	v_pk_fma_f32 v[102:103], v[102:103], v[102:103], v[104:105]
	v_pk_fma_f32 v[104:105], v[106:107], v[106:107], v[108:109]
	s_waitcnt vmcnt(35)
	v_pk_mul_f32 v[114:115], v[18:19], v[18:19]
	v_pk_mul_f32 v[116:117], v[16:17], v[16:17]
	s_waitcnt vmcnt(34)
	v_mul_f32_e32 v118, v21, v21
	v_mul_f32_e32 v120, v23, v23
	v_pk_add_f32 v[106:107], v[126:127], v[112:113]
	v_pk_add_f32 v[102:103], v[102:103], v[104:105]
	v_mul_f32_e32 v125, v12, v12
	v_mul_f32_e32 v128, v13, v13
	v_mul_f32_e32 v129, v14, v14
	v_mul_f32_e32 v130, v15, v15
	v_pk_mov_b32 v[110:111], v[116:117], v[114:115] op_sel:[1,0]
	v_mov_b32_e32 v117, v115
	v_pk_fma_f32 v[114:115], v[20:21], v[20:21], v[118:119] op_sel_hi:[1,1,0]
	v_pk_fma_f32 v[118:119], v[22:23], v[22:23], v[120:121] op_sel_hi:[1,1,0]
	v_pk_add_f32 v[104:105], v[106:107], v[106:107] op_sel:[0,1] op_sel_hi:[1,0]
	v_pk_add_f32 v[102:103], v[102:103], v[102:103] op_sel:[0,1] op_sel_hi:[1,0]
	s_waitcnt vmcnt(32)
	v_mul_f32_e32 v122, v29, v29
	v_mul_f32_e32 v124, v31, v31
	v_mov_b32_e32 v115, v129
	v_mov_b32_e32 v119, v130
	v_mov_b32_e32 v105, v128
	v_mov_b32_e32 v103, v125
	v_mul_f32_e32 v133, v26, v26
	v_mul_f32_e32 v134, v27, v27
	v_pk_fma_f32 v[120:121], v[28:29], v[28:29], v[122:123] op_sel_hi:[1,1,0]
	v_pk_fma_f32 v[122:123], v[30:31], v[30:31], v[124:125] op_sel_hi:[1,1,0]
	v_pk_add_f32 v[108:109], v[110:111], v[116:117]
	v_pk_add_f32 v[106:107], v[114:115], v[118:119]
	s_waitcnt vmcnt(30)
; __device__ __forceinline__ unsigned cvt_pk_bf16(float lo, float hi) { const bf16x2_t r = __builtin_convertvector((f32x2){lo, hi}, bf16x2_t); return __builtin_bit_cast(unsigned, r); }
; template <bool FINAL>
; __device__ __forceinline__ void norm_phase(const float* X, const float* mod, bf16_t* H, const float* fg, float* OUT, const unsigned long long* acc64 = nullptr, float* modf = nullptr) {
;     ...
;         for (int j = 0; j < 8; ++j) { v[j] = xr[64 * j]; ss += (v[j][0] * v[j][0] + v[j][1] * v[j][1]) + (v[j][2] * v[j][2] + v[j][3] * v[j][3]); }
;         const float rstd = rsqrtf(wave_sum(ss) * (1.0f / DM) + EPS);
;         if (FINAL) {
; #pragma unroll
;             for (int j = 0; j < 8; ++j) { const f32x4 g = *((const f32x4*)fg + lane + 64 * j); *((f32x4*)(OUT + (size_t)r * DM) + lane + 64 * j) = v[j] * rstd * g; }
;         } else {
;             const float* mb = mod + (r >> 12) * 6144; const unsigned long long* mb64 = acc64 + (r >> 12) * 6144;
; #pragma unroll
;             for (int j = 0; j < 8; ++j) { const f32x4 sh = acc64 ? ld_fx4(mb64 + 4 * (lane + 64 * j)) : *((const f32x4*)mb + lane + 64 * j), sc = acc64 ? ld_fx4(mb64 + DM + 4 * (lane + 64 * j)) : *((const f32x4*)(mb + DM) + lane + 64 * j);
;                 const f32x4 o = v[j] * rstd * (sc + 1.0f) + sh; u32x2 w; w.x = cvt_pk_bf16(o[0], o[1]); w.y = cvt_pk_bf16(o[2], o[3]);
;                 *((u32x2*)(H + (size_t)r * DM) + lane + 64 * j) = w; }
	v_xor_b32_e32 v112, v86, v87
	v_xor_b32_e32 v114, v88, v89
	v_xor_b32_e32 v116, v82, v83
	v_xor_b32_e32 v118, v84, v85
	v_pk_add_f32 v[102:103], v[102:103], v[104:105]
	v_mov_b32_e32 v121, v133
	v_mov_b32_e32 v123, v134
	v_ffbh_i32_e32 v113, v87
	v_ffbh_i32_e32 v115, v89
	v_ffbh_i32_e32 v117, v83
	v_ffbh_i32_e32 v119, v85
	v_ashrrev_i32_e32 v104, 31, v112
	v_ashrrev_i32_e32 v112, 31, v114
	v_ashrrev_i32_e32 v114, 31, v116
	v_ashrrev_i32_e32 v116, 31, v118
	s_waitcnt vmcnt(29)
	v_xor_b32_e32 v118, v90, v91
	v_pk_add_f32 v[102:103], v[102:103], v[106:107]
	v_mul_f32_e32 v131, v24, v24
	v_mul_f32_e32 v132, v25, v25
	v_pk_add_f32 v[108:109], v[108:109], v[108:109] op_sel:[0,1] op_sel_hi:[1,0]
	v_pk_add_f32 v[110:111], v[120:121], v[122:123]
	v_add_u32_e32 v105, -1, v113
	v_add_u32_e32 v113, -1, v115
	v_add_u32_e32 v115, -1, v117
	v_add_u32_e32 v117, -1, v119
	v_ffbh_i32_e32 v119, v91
	v_xor_b32_e32 v120, v92, v93
	v_add_u32_e32 v104, 32, v104
	v_add_u32_e32 v106, 32, v112
	v_add_u32_e32 v107, 32, v114
	v_add_u32_e32 v112, 32, v116
	v_ashrrev_i32_e32 v114, 31, v118
	v_pk_add_f32 v[102:103], v[102:103], v[102:103] op_sel:[0,1] op_sel_hi:[1,0]
	v_mov_b32_e32 v109, v132
	v_ffbh_i32_e32 v121, v93
	v_add_u32_e32 v116, -1, v119
	v_ashrrev_i32_e32 v118, 31, v120
	v_min_u32_e32 v104, v105, v104
	v_min_u32_e32 v105, v113, v106
	v_min_u32_e32 v106, v115, v107
	v_min_u32_e32 v107, v117, v112
	v_add_u32_e32 v112, 32, v114
	v_mov_b32_e32 v103, v131
	v_add_u32_e32 v119, -1, v121
	v_add_u32_e32 v113, 32, v118
	v_lshlrev_b64 v[82:83], v106, v[82:83]
	v_lshlrev_b64 v[84:85], v107, v[84:85]
	v_min_u32_e32 v112, v116, v112
	v_pk_add_f32 v[102:103], v[102:103], v[108:109]
	v_min_u32_e32 v113, v119, v113
	v_min_u32_e32 v82, 1, v82
	v_min_u32_e32 v84, 1, v84
	v_lshlrev_b64 v[90:91], v112, v[90:91]
	v_pk_add_f32 v[102:103], v[102:103], v[110:111]
	v_lshlrev_b64 v[92:93], v113, v[92:93]
	v_or_b32_e32 v82, v83, v82
	v_or_b32_e32 v83, v85, v84
	v_min_u32_e32 v84, 1, v90
	v_add_f32_e32 v90, v102, v103
	v_min_u32_e32 v85, 1, v92
	v_cvt_f32_i32_e32 v92, v82
	v_or_b32_e32 v82, v91, v84
	ds_bpermute_b32 v91, v76, v90
	s_waitcnt vmcnt(28)
	v_xor_b32_e32 v122, v94, v95
	v_xor_b32_e32 v124, v96, v97
	v_ffbh_i32_e32 v123, v95
	v_ffbh_i32_e32 v125, v97
	s_waitcnt lgkmcnt(0)
	v_add_f32_e32 v90, v90, v91
	ds_bpermute_b32 v91, v77, v90
	v_ashrrev_i32_e32 v120, 31, v122
	v_ashrrev_i32_e32 v122, 31, v124
	v_add_u32_e32 v121, -1, v123
	v_add_u32_e32 v123, -1, v125
	s_waitcnt lgkmcnt(0)
	v_add_f32_e32 v90, v90, v91
	ds_bpermute_b32 v91, v78, v90
	v_add_u32_e32 v114, 32, v120
	v_add_u32_e32 v115, 32, v122
	v_lshlrev_b64 v[86:87], v104, v[86:87]
	v_lshlrev_b64 v[88:89], v105, v[88:89]
	s_waitcnt lgkmcnt(0)
	v_add_f32_e32 v90, v90, v91
	ds_bpermute_b32 v91, v79, v90
	v_min_u32_e32 v114, v121, v114
	v_min_u32_e32 v115, v123, v115
	v_min_u32_e32 v86, 1, v86
	v_min_u32_e32 v88, 1, v88
	s_waitcnt lgkmcnt(0)
	v_add_f32_e32 v90, v90, v91
	ds_bpermute_b32 v91, v80, v90
	v_lshlrev_b64 v[94:95], v114, v[94:95]
	v_lshlrev_b64 v[96:97], v115, v[96:97]
	v_or_b32_e32 v86, v87, v86
	v_or_b32_e32 v87, v89, v88
	s_waitcnt lgkmcnt(0)
	v_add_f32_e32 v90, v90, v91
	ds_bpermute_b32 v91, v81, v90
	v_min_u32_e32 v88, 1, v94
	v_min_u32_e32 v89, 1, v96
	v_cvt_f32_i32_e32 v94, v83
	v_or_b32_e32 v83, v93, v85
	s_waitcnt lgkmcnt(0)
	v_add_f32_e32 v90, v90, v91
	v_fmamk_f32 v90, v90, 0x3a000000, v33
	v_mul_f32_e32 v91, 0x4b800000, v90
	v_cmp_gt_f32_e32 vcc, s5, v90
	v_or_b32_e32 v84, v95, v88
	v_or_b32_e32 v85, v97, v89
	v_cndmask_b32_e32 v90, v90, v91, vcc
	v_rsq_f32_e32 v90, v90
	v_cvt_f32_i32_e32 v86, v86
	v_cvt_f32_i32_e32 v87, v87
	v_cvt_f32_i32_e32 v88, v82
	v_cvt_f32_i32_e32 v89, v83
	v_cvt_f32_i32_e32 v93, v84
	v_cvt_f32_i32_e32 v95, v85
	v_sub_u32_e32 v104, 32, v104
	v_sub_u32_e32 v105, 32, v105
	v_sub_u32_e32 v108, 32, v112
	v_sub_u32_e32 v109, 32, v113
	v_sub_u32_e32 v112, 32, v114
	v_sub_u32_e32 v113, 32, v115
	v_mul_f32_e32 v91, 0x45800000, v90
	v_sub_u32_e32 v106, 32, v106
	v_sub_u32_e32 v107, 32, v107
	v_ldexp_f32 v82, v86, v104
	v_ldexp_f32 v83, v87, v105
	v_ldexp_f32 v86, v88, v108
	v_ldexp_f32 v87, v89, v109
	v_ldexp_f32 v88, v93, v112
	v_ldexp_f32 v89, v95, v113
	v_cndmask_b32_e32 v90, v90, v91, vcc
	v_ldexp_f32 v84, v92, v106
	v_ldexp_f32 v85, v94, v107
	v_pk_fma_f32 v[86:87], v[86:87], s[16:17], 1.0 op_sel_hi:[1,0,0]
	v_pk_fma_f32 v[88:89], v[88:89], s[16:17], 1.0 op_sel_hi:[1,0,0]
	v_pk_mul_f32 v[92:93], v[6:7], v[90:91] op_sel_hi:[1,0]
	v_pk_mul_f32 v[94:95], v[4:5], v[90:91] op_sel_hi:[1,0]
	v_pk_mul_f32 v[104:105], v[10:11], v[90:91] op_sel_hi:[1,0]
	v_pk_mul_f32 v[106:107], v[8:9], v[90:91] op_sel_hi:[1,0]
	v_pk_mul_f32 v[8:9], v[18:19], v[90:91] op_sel_hi:[1,0]
	v_pk_mul_f32 v[10:11], v[16:17], v[90:91] op_sel_hi:[1,0]
	v_pk_mul_f32 v[16:17], v[86:87], v[94:95]
	v_pk_mul_f32 v[18:19], v[88:89], v[92:93]
	v_pk_fma_f32 v[16:17], v[82:83], s[16:17], v[16:17] op_sel_hi:[1,0,1]
	v_pk_fma_f32 v[18:19], v[84:85], s[16:17], v[18:19] op_sel_hi:[1,0,1]
	v_cvt_pk_bf16_f32 v16, v16, v17
	v_cvt_pk_bf16_f32 v17, v18, v19
	global_store_dwordx2 v[38:39], v[16:17], off
	v_pk_mul_f32 v[96:97], v[2:3], v[90:91] op_sel_hi:[1,0]
	v_pk_mul_f32 v[102:103], v[0:1], v[90:91] op_sel_hi:[1,0]
	v_pk_mul_f32 v[4:5], v[30:31], v[90:91] op_sel_hi:[1,0]
	v_pk_mul_f32 v[6:7], v[28:29], v[90:91] op_sel_hi:[1,0]
	v_pk_mul_f32 v[0:1], v[26:27], v[90:91] op_sel_hi:[1,0]
	v_pk_mul_f32 v[2:3], v[24:25], v[90:91] op_sel_hi:[1,0]
	s_waitcnt vmcnt(25)
; __device__ __forceinline__ unsigned cvt_pk_bf16(float lo, float hi) { const bf16x2_t r = __builtin_convertvector((f32x2){lo, hi}, bf16x2_t); return __builtin_bit_cast(unsigned, r); }
; __device__ __forceinline__ f32x4 ld_fx4(const unsigned long long* p) {
;     const long long a = (long long)p[0], b = (long long)p[1], c = (long long)p[2], d = (long long)p[3];
;     return (f32x4){(float)a, (float)b, (float)c, (float)d} * 9.094947017729282e-13f;
; }
; template <bool FINAL>
; __device__ __forceinline__ void norm_phase(const float* X, const float* mod, bf16_t* H, const float* fg, float* OUT, const unsigned long long* acc64 = nullptr, float* modf = nullptr) {
;     ...
;             const float* mb = mod + (r >> 12) * 6144; const unsigned long long* mb64 = acc64 + (r >> 12) * 6144;
; #pragma unroll
;             for (int j = 0; j < 8; ++j) { const f32x4 sh = acc64 ? ld_fx4(mb64 + 4 * (lane + 64 * j)) : *((const f32x4*)mb + lane + 64 * j), sc = acc64 ? ld_fx4(mb64 + DM + 4 * (lane + 64 * j)) : *((const f32x4*)(mb + DM) + lane + 64 * j);
;                 const f32x4 o = v[j] * rstd * (sc + 1.0f) + sh; u32x2 w; w.x = cvt_pk_bf16(o[0], o[1]); w.y = cvt_pk_bf16(o[2], o[3]);
;                 *((u32x2*)(H + (size_t)r * DM) + lane + 64 * j) = w; }
	v_mov_b64_e32 v[16:17], v[136:137]
	v_mov_b64_e32 v[18:19], v[138:139]
	v_mov_b64_e32 v[24:25], v[140:141]
	v_mov_b64_e32 v[26:27], v[142:143]
	v_mov_b64_e32 v[28:29], v[144:145]
	v_mov_b64_e32 v[30:31], v[146:147]
	v_mov_b64_e32 v[82:83], v[148:149]
	v_mov_b64_e32 v[84:85], v[150:151]
	v_pk_mul_f32 v[22:23], v[22:23], v[90:91] op_sel_hi:[1,0]
	v_pk_mul_f32 v[20:21], v[20:21], v[90:91] op_sel_hi:[1,0]
	v_pk_mul_f32 v[14:15], v[14:15], v[90:91] op_sel_hi:[1,0]
	v_pk_mul_f32 v[12:13], v[12:13], v[90:91] op_sel_hi:[1,0]
	v_xor_b32_e32 v86, v16, v17
	v_xor_b32_e32 v88, v18, v19
	v_xor_b32_e32 v90, v24, v25
	v_xor_b32_e32 v92, v26, v27
	v_xor_b32_e32 v94, v28, v29
	v_xor_b32_e32 v98, v30, v31
	v_xor_b32_e32 v100, v82, v83
	v_xor_b32_e32 v108, v84, v85
	v_ffbh_i32_e32 v87, v17
	v_ffbh_i32_e32 v89, v19
	v_ffbh_i32_e32 v91, v25
	v_ffbh_i32_e32 v93, v27
	v_ffbh_i32_e32 v95, v29
	v_ffbh_i32_e32 v99, v31
	v_ffbh_i32_e32 v101, v83
	v_ffbh_i32_e32 v109, v85
	v_ashrrev_i32_e32 v86, 31, v86
	v_ashrrev_i32_e32 v88, 31, v88
	v_ashrrev_i32_e32 v90, 31, v90
	v_ashrrev_i32_e32 v92, 31, v92
	v_ashrrev_i32_e32 v94, 31, v94
	v_ashrrev_i32_e32 v98, 31, v98
	v_ashrrev_i32_e32 v100, 31, v100
	v_ashrrev_i32_e32 v108, 31, v108
	v_add_u32_e32 v87, -1, v87
	v_add_u32_e32 v89, -1, v89
	v_add_u32_e32 v91, -1, v91
	v_add_u32_e32 v93, -1, v93
	v_add_u32_e32 v95, -1, v95
	v_add_u32_e32 v99, -1, v99
	v_add_u32_e32 v101, -1, v101
	v_add_u32_e32 v109, -1, v109
	v_add_u32_e32 v86, 32, v86
	v_add_u32_e32 v88, 32, v88
	v_add_u32_e32 v90, 32, v90
	v_add_u32_e32 v92, 32, v92
	v_add_u32_e32 v94, 32, v94
	v_add_u32_e32 v98, 32, v98
	v_add_u32_e32 v100, 32, v100
	v_add_u32_e32 v108, 32, v108
	v_min_u32_e32 v86, v87, v86
	v_min_u32_e32 v87, v89, v88
	v_min_u32_e32 v88, v91, v90
	v_min_u32_e32 v89, v93, v92
	v_min_u32_e32 v90, v95, v94
	v_min_u32_e32 v91, v99, v98
	v_min_u32_e32 v92, v101, v100
	v_min_u32_e32 v93, v109, v108
	v_lshlrev_b64 v[16:17], v86, v[16:17]
	v_lshlrev_b64 v[18:19], v87, v[18:19]
	v_lshlrev_b64 v[24:25], v88, v[24:25]
	v_lshlrev_b64 v[26:27], v89, v[26:27]
	v_lshlrev_b64 v[28:29], v90, v[28:29]
	v_lshlrev_b64 v[30:31], v91, v[30:31]
	v_lshlrev_b64 v[82:83], v92, v[82:83]
	v_lshlrev_b64 v[84:85], v93, v[84:85]
	v_min_u32_e32 v16, 1, v16
	v_min_u32_e32 v18, 1, v18
	v_min_u32_e32 v24, 1, v24
	v_min_u32_e32 v26, 1, v26
	v_min_u32_e32 v28, 1, v28
	v_min_u32_e32 v30, 1, v30
	v_min_u32_e32 v82, 1, v82
	v_min_u32_e32 v84, 1, v84
	v_or_b32_e32 v16, v17, v16
	v_or_b32_e32 v17, v19, v18
	v_or_b32_e32 v18, v25, v24
	v_or_b32_e32 v19, v27, v26
	v_or_b32_e32 v24, v29, v28
	v_or_b32_e32 v25, v31, v30
	v_or_b32_e32 v26, v83, v82
	v_or_b32_e32 v27, v85, v84
	v_cvt_f32_i32_e32 v24, v24
	v_cvt_f32_i32_e32 v25, v25
	v_cvt_f32_i32_e32 v26, v26
	v_cvt_f32_i32_e32 v27, v27
	v_cvt_f32_i32_e32 v16, v16
	v_cvt_f32_i32_e32 v17, v17
	v_cvt_f32_i32_e32 v18, v18
	v_cvt_f32_i32_e32 v19, v19
	v_sub_u32_e32 v90, 32, v90
	v_sub_u32_e32 v91, 32, v91
	v_sub_u32_e32 v92, 32, v92
	v_sub_u32_e32 v93, 32, v93
	v_ldexp_f32 v24, v24, v90
	v_ldexp_f32 v25, v25, v91
	v_ldexp_f32 v26, v26, v92
	v_ldexp_f32 v27, v27, v93
	v_sub_u32_e32 v86, 32, v86
	v_sub_u32_e32 v87, 32, v87
	v_sub_u32_e32 v88, 32, v88
	v_sub_u32_e32 v89, 32, v89
	v_pk_fma_f32 v[26:27], v[26:27], s[16:17], 1.0 op_sel_hi:[1,0,0]
	v_pk_fma_f32 v[24:25], v[24:25], s[16:17], 1.0 op_sel_hi:[1,0,0]
	v_ldexp_f32 v16, v16, v86
	v_ldexp_f32 v17, v17, v87
	v_ldexp_f32 v18, v18, v88
	v_ldexp_f32 v19, v19, v89
	v_pk_mul_f32 v[24:25], v[102:103], v[24:25]
	v_pk_mul_f32 v[26:27], v[96:97], v[26:27]
	v_pk_fma_f32 v[16:17], v[16:17], s[16:17], v[24:25] op_sel_hi:[1,0,1]
	v_pk_fma_f32 v[18:19], v[18:19], s[16:17], v[26:27] op_sel_hi:[1,0,1]
	v_cvt_pk_bf16_f32 v16, v16, v17
	v_cvt_pk_bf16_f32 v17, v18, v19
	global_store_dwordx2 v[38:39], v[16:17], off offset:512
	s_waitcnt vmcnt(22)
	v_mov_b64_e32 v[16:17], v[152:153]
	v_mov_b64_e32 v[18:19], v[154:155]
	v_mov_b64_e32 v[24:25], v[156:157]
	v_mov_b64_e32 v[26:27], v[158:159]
	v_mov_b64_e32 v[28:29], v[160:161]
	v_mov_b64_e32 v[30:31], v[162:163]
	v_mov_b64_e32 v[72:73], v[164:165]
	v_mov_b64_e32 v[74:75], v[166:167]
	v_xor_b32_e32 v82, v16, v17
	v_xor_b32_e32 v84, v18, v19
	v_xor_b32_e32 v86, v24, v25
	v_xor_b32_e32 v88, v26, v27
	v_xor_b32_e32 v90, v28, v29
	v_xor_b32_e32 v92, v30, v31
	v_xor_b32_e32 v94, v72, v73
	v_xor_b32_e32 v96, v74, v75
	v_ffbh_i32_e32 v83, v17
	v_ffbh_i32_e32 v85, v19
	v_ffbh_i32_e32 v87, v25
	v_ffbh_i32_e32 v89, v27
	v_ffbh_i32_e32 v91, v29
	v_ffbh_i32_e32 v93, v31
	v_ffbh_i32_e32 v95, v73
	v_ffbh_i32_e32 v97, v75
	v_ashrrev_i32_e32 v82, 31, v82
	v_ashrrev_i32_e32 v84, 31, v84
	v_ashrrev_i32_e32 v86, 31, v86
	v_ashrrev_i32_e32 v88, 31, v88
	v_ashrrev_i32_e32 v90, 31, v90
	v_ashrrev_i32_e32 v92, 31, v92
	v_ashrrev_i32_e32 v94, 31, v94
	v_ashrrev_i32_e32 v96, 31, v96
	v_add_u32_e32 v83, -1, v83
	v_add_u32_e32 v85, -1, v85
	v_add_u32_e32 v87, -1, v87
	v_add_u32_e32 v89, -1, v89
	v_add_u32_e32 v91, -1, v91
	v_add_u32_e32 v93, -1, v93
	v_add_u32_e32 v95, -1, v95
	v_add_u32_e32 v97, -1, v97
	v_add_u32_e32 v82, 32, v82
	v_add_u32_e32 v84, 32, v84
	v_add_u32_e32 v86, 32, v86
	v_add_u32_e32 v88, 32, v88
	v_add_u32_e32 v90, 32, v90
	v_add_u32_e32 v92, 32, v92
	v_add_u32_e32 v94, 32, v94
	v_add_u32_e32 v96, 32, v96
	v_min_u32_e32 v82, v83, v82
	v_min_u32_e32 v83, v85, v84
	v_min_u32_e32 v84, v87, v86
	v_min_u32_e32 v85, v89, v88
	v_min_u32_e32 v86, v91, v90
	v_min_u32_e32 v87, v93, v92
	v_min_u32_e32 v88, v95, v94
	v_min_u32_e32 v89, v97, v96
	v_lshlrev_b64 v[16:17], v82, v[16:17]
	v_lshlrev_b64 v[18:19], v83, v[18:19]
	v_lshlrev_b64 v[24:25], v84, v[24:25]
	v_lshlrev_b64 v[26:27], v85, v[26:27]
; __device__ __forceinline__ unsigned cvt_pk_bf16(float lo, float hi) { const bf16x2_t r = __builtin_convertvector((f32x2){lo, hi}, bf16x2_t); return __builtin_bit_cast(unsigned, r); }
; __device__ __forceinline__ f32x4 ld_fx4(const unsigned long long* p) {
;     const long long a = (long long)p[0], b = (long long)p[1], c = (long long)p[2], d = (long long)p[3];
;     return (f32x4){(float)a, (float)b, (float)c, (float)d} * 9.094947017729282e-13f;
; }
; template <bool FINAL>
; __device__ __forceinline__ void norm_phase(const float* X, const float* mod, bf16_t* H, const float* fg, float* OUT, const unsigned long long* acc64 = nullptr, float* modf = nullptr) {
;     ...
;             const float* mb = mod + (r >> 12) * 6144; const unsigned long long* mb64 = acc64 + (r >> 12) * 6144;
; #pragma unroll
;             for (int j = 0; j < 8; ++j) { const f32x4 sh = acc64 ? ld_fx4(mb64 + 4 * (lane + 64 * j)) : *((const f32x4*)mb + lane + 64 * j), sc = acc64 ? ld_fx4(mb64 + DM + 4 * (lane + 64 * j)) : *((const f32x4*)(mb + DM) + lane + 64 * j);
;                 const f32x4 o = v[j] * rstd * (sc + 1.0f) + sh; u32x2 w; w.x = cvt_pk_bf16(o[0], o[1]); w.y = cvt_pk_bf16(o[2], o[3]);
;                 *((u32x2*)(H + (size_t)r * DM) + lane + 64 * j) = w; }
	v_lshlrev_b64 v[28:29], v86, v[28:29]
	v_lshlrev_b64 v[30:31], v87, v[30:31]
	v_lshlrev_b64 v[72:73], v88, v[72:73]
	v_lshlrev_b64 v[74:75], v89, v[74:75]
	v_min_u32_e32 v16, 1, v16
	v_min_u32_e32 v18, 1, v18
	v_min_u32_e32 v24, 1, v24
	v_min_u32_e32 v26, 1, v26
	v_min_u32_e32 v28, 1, v28
	v_min_u32_e32 v30, 1, v30
	v_min_u32_e32 v72, 1, v72
	v_min_u32_e32 v74, 1, v74
	v_or_b32_e32 v16, v17, v16
	v_or_b32_e32 v17, v19, v18
	v_or_b32_e32 v18, v25, v24
	v_or_b32_e32 v19, v27, v26
	v_or_b32_e32 v24, v29, v28
	v_or_b32_e32 v25, v31, v30
	v_or_b32_e32 v26, v73, v72
	v_or_b32_e32 v27, v75, v74
	v_cvt_f32_i32_e32 v24, v24
	v_cvt_f32_i32_e32 v25, v25
	v_cvt_f32_i32_e32 v26, v26
	v_cvt_f32_i32_e32 v27, v27
	v_cvt_f32_i32_e32 v16, v16
	v_cvt_f32_i32_e32 v17, v17
	v_cvt_f32_i32_e32 v18, v18
	v_cvt_f32_i32_e32 v19, v19
	v_sub_u32_e32 v86, 32, v86
	v_sub_u32_e32 v87, 32, v87
	v_sub_u32_e32 v88, 32, v88
	v_sub_u32_e32 v89, 32, v89
	v_ldexp_f32 v24, v24, v86
	v_ldexp_f32 v25, v25, v87
	v_ldexp_f32 v26, v26, v88
	v_ldexp_f32 v27, v27, v89
	v_sub_u32_e32 v82, 32, v82
	v_sub_u32_e32 v83, 32, v83
	v_sub_u32_e32 v84, 32, v84
	v_sub_u32_e32 v85, 32, v85
	v_pk_fma_f32 v[24:25], v[24:25], s[16:17], 1.0 op_sel_hi:[1,0,0]
	v_pk_fma_f32 v[26:27], v[26:27], s[16:17], 1.0 op_sel_hi:[1,0,0]
	v_ldexp_f32 v16, v16, v82
	v_ldexp_f32 v17, v17, v83
	v_ldexp_f32 v18, v18, v84
	v_ldexp_f32 v19, v19, v85
	v_pk_mul_f32 v[24:25], v[106:107], v[24:25]
	v_pk_mul_f32 v[26:27], v[104:105], v[26:27]
	v_pk_fma_f32 v[16:17], v[16:17], s[16:17], v[24:25] op_sel_hi:[1,0,1]
	v_pk_fma_f32 v[18:19], v[18:19], s[16:17], v[26:27] op_sel_hi:[1,0,1]
	v_cvt_pk_bf16_f32 v16, v16, v17
	v_cvt_pk_bf16_f32 v17, v18, v19
	global_store_dwordx2 v[38:39], v[16:17], off offset:1024
	s_waitcnt vmcnt(19)
	v_mov_b64_e32 v[16:17], v[168:169]
	v_mov_b64_e32 v[18:19], v[170:171]
	v_mov_b64_e32 v[24:25], v[172:173]
	v_mov_b64_e32 v[26:27], v[174:175]
	v_mov_b64_e32 v[28:29], v[176:177]
	v_mov_b64_e32 v[30:31], v[178:179]
	v_mov_b64_e32 v[64:65], v[180:181]
	v_mov_b64_e32 v[66:67], v[182:183]
	v_xor_b32_e32 v68, v16, v17
	v_xor_b32_e32 v70, v18, v19
	v_xor_b32_e32 v72, v24, v25
	v_xor_b32_e32 v74, v26, v27
	v_xor_b32_e32 v82, v28, v29
	v_xor_b32_e32 v84, v30, v31
	v_xor_b32_e32 v86, v64, v65
	v_xor_b32_e32 v88, v66, v67
	v_ffbh_i32_e32 v69, v17
	v_ffbh_i32_e32 v71, v19
	v_ffbh_i32_e32 v73, v25
	v_ffbh_i32_e32 v75, v27
	v_ffbh_i32_e32 v83, v29
	v_ffbh_i32_e32 v85, v31
	v_ffbh_i32_e32 v87, v65
	v_ffbh_i32_e32 v89, v67
	v_ashrrev_i32_e32 v68, 31, v68
	v_ashrrev_i32_e32 v70, 31, v70
	v_ashrrev_i32_e32 v72, 31, v72
	v_ashrrev_i32_e32 v74, 31, v74
	v_ashrrev_i32_e32 v82, 31, v82
	v_ashrrev_i32_e32 v84, 31, v84
	v_ashrrev_i32_e32 v86, 31, v86
	v_ashrrev_i32_e32 v88, 31, v88
	v_add_u32_e32 v69, -1, v69
	v_add_u32_e32 v71, -1, v71
	v_add_u32_e32 v73, -1, v73
	v_add_u32_e32 v75, -1, v75
	v_add_u32_e32 v83, -1, v83
	v_add_u32_e32 v85, -1, v85
	v_add_u32_e32 v87, -1, v87
	v_add_u32_e32 v89, -1, v89
	v_add_u32_e32 v68, 32, v68
	v_add_u32_e32 v70, 32, v70
	v_add_u32_e32 v72, 32, v72
	v_add_u32_e32 v74, 32, v74
	v_add_u32_e32 v82, 32, v82
	v_add_u32_e32 v84, 32, v84
	v_add_u32_e32 v86, 32, v86
	v_add_u32_e32 v88, 32, v88
	v_min_u32_e32 v68, v69, v68
	v_min_u32_e32 v69, v71, v70
	v_min_u32_e32 v70, v73, v72
	v_min_u32_e32 v71, v75, v74
	v_min_u32_e32 v72, v83, v82
	v_min_u32_e32 v73, v85, v84
	v_min_u32_e32 v74, v87, v86
	v_min_u32_e32 v75, v89, v88
	v_lshlrev_b64 v[16:17], v68, v[16:17]
	v_lshlrev_b64 v[18:19], v69, v[18:19]
	v_lshlrev_b64 v[24:25], v70, v[24:25]
	v_lshlrev_b64 v[26:27], v71, v[26:27]
	v_lshlrev_b64 v[28:29], v72, v[28:29]
	v_lshlrev_b64 v[30:31], v73, v[30:31]
	v_lshlrev_b64 v[64:65], v74, v[64:65]
	v_lshlrev_b64 v[66:67], v75, v[66:67]
	v_min_u32_e32 v16, 1, v16
	v_min_u32_e32 v18, 1, v18
	v_min_u32_e32 v24, 1, v24
	v_min_u32_e32 v26, 1, v26
	v_min_u32_e32 v28, 1, v28
	v_min_u32_e32 v30, 1, v30
	v_min_u32_e32 v64, 1, v64
	v_min_u32_e32 v66, 1, v66
	v_or_b32_e32 v16, v17, v16
	v_or_b32_e32 v17, v19, v18
	v_or_b32_e32 v18, v25, v24
	v_or_b32_e32 v19, v27, v26
	v_or_b32_e32 v24, v29, v28
	v_or_b32_e32 v25, v31, v30
	v_or_b32_e32 v26, v65, v64
	v_or_b32_e32 v27, v67, v66
	v_cvt_f32_i32_e32 v24, v24
	v_cvt_f32_i32_e32 v25, v25
	v_cvt_f32_i32_e32 v26, v26
	v_cvt_f32_i32_e32 v27, v27
	v_cvt_f32_i32_e32 v16, v16
	v_cvt_f32_i32_e32 v17, v17
	v_cvt_f32_i32_e32 v18, v18
	v_cvt_f32_i32_e32 v19, v19
	v_sub_u32_e32 v72, 32, v72
	v_sub_u32_e32 v73, 32, v73
	v_sub_u32_e32 v74, 32, v74
	v_sub_u32_e32 v75, 32, v75
	v_ldexp_f32 v24, v24, v72
	v_ldexp_f32 v25, v25, v73
	v_ldexp_f32 v26, v26, v74
	v_ldexp_f32 v27, v27, v75
	v_sub_u32_e32 v68, 32, v68
	v_sub_u32_e32 v69, 32, v69
	v_sub_u32_e32 v70, 32, v70
	v_sub_u32_e32 v71, 32, v71
	v_pk_fma_f32 v[24:25], v[24:25], s[16:17], 1.0 op_sel_hi:[1,0,0]
	v_pk_fma_f32 v[26:27], v[26:27], s[16:17], 1.0 op_sel_hi:[1,0,0]
	v_ldexp_f32 v16, v16, v68
	v_ldexp_f32 v17, v17, v69
	v_ldexp_f32 v18, v18, v70
	v_ldexp_f32 v19, v19, v71
	v_pk_mul_f32 v[20:21], v[20:21], v[24:25]
	v_pk_mul_f32 v[22:23], v[22:23], v[26:27]
	v_pk_fma_f32 v[16:17], v[16:17], s[16:17], v[20:21] op_sel_hi:[1,0,1]
	v_pk_fma_f32 v[18:19], v[18:19], s[16:17], v[22:23] op_sel_hi:[1,0,1]
	v_cvt_pk_bf16_f32 v16, v16, v17
	v_cvt_pk_bf16_f32 v17, v18, v19
	global_store_dwordx2 v[38:39], v[16:17], off offset:1536
	s_waitcnt vmcnt(16)
; __device__ __forceinline__ unsigned cvt_pk_bf16(float lo, float hi) { const bf16x2_t r = __builtin_convertvector((f32x2){lo, hi}, bf16x2_t); return __builtin_bit_cast(unsigned, r); }
; __device__ __forceinline__ f32x4 ld_fx4(const unsigned long long* p) {
;     const long long a = (long long)p[0], b = (long long)p[1], c = (long long)p[2], d = (long long)p[3];
;     return (f32x4){(float)a, (float)b, (float)c, (float)d} * 9.094947017729282e-13f;
; }
; template <bool FINAL>
; __device__ __forceinline__ void norm_phase(const float* X, const float* mod, bf16_t* H, const float* fg, float* OUT, const unsigned long long* acc64 = nullptr, float* modf = nullptr) {
;     ...
;             const float* mb = mod + (r >> 12) * 6144; const unsigned long long* mb64 = acc64 + (r >> 12) * 6144;
; #pragma unroll
;             for (int j = 0; j < 8; ++j) { const f32x4 sh = acc64 ? ld_fx4(mb64 + 4 * (lane + 64 * j)) : *((const f32x4*)mb + lane + 64 * j), sc = acc64 ? ld_fx4(mb64 + DM + 4 * (lane + 64 * j)) : *((const f32x4*)(mb + DM) + lane + 64 * j);
;                 const f32x4 o = v[j] * rstd * (sc + 1.0f) + sh; u32x2 w; w.x = cvt_pk_bf16(o[0], o[1]); w.y = cvt_pk_bf16(o[2], o[3]);
;                 *((u32x2*)(H + (size_t)r * DM) + lane + 64 * j) = w; }
	v_mov_b64_e32 v[16:17], v[184:185]
	v_mov_b64_e32 v[18:19], v[186:187]
	v_mov_b64_e32 v[20:21], v[188:189]
	v_mov_b64_e32 v[22:23], v[190:191]
	v_mov_b64_e32 v[24:25], v[196:197]
	v_mov_b64_e32 v[26:27], v[198:199]
	v_mov_b64_e32 v[28:29], v[202:203]
	v_mov_b64_e32 v[30:31], v[204:205]
	v_xor_b32_e32 v60, v16, v17
	v_xor_b32_e32 v62, v18, v19
	v_xor_b32_e32 v64, v20, v21
	v_xor_b32_e32 v66, v22, v23
	v_xor_b32_e32 v68, v24, v25
	v_xor_b32_e32 v70, v26, v27
	v_xor_b32_e32 v72, v28, v29
	v_xor_b32_e32 v74, v30, v31
	v_ffbh_i32_e32 v61, v17
	v_ffbh_i32_e32 v63, v19
	v_ffbh_i32_e32 v65, v21
	v_ffbh_i32_e32 v67, v23
	v_ffbh_i32_e32 v69, v25
	v_ffbh_i32_e32 v71, v27
	v_ffbh_i32_e32 v73, v29
	v_ffbh_i32_e32 v75, v31
	v_ashrrev_i32_e32 v60, 31, v60
	v_ashrrev_i32_e32 v62, 31, v62
	v_ashrrev_i32_e32 v64, 31, v64
	v_ashrrev_i32_e32 v66, 31, v66
	v_ashrrev_i32_e32 v68, 31, v68
	v_ashrrev_i32_e32 v70, 31, v70
	v_ashrrev_i32_e32 v72, 31, v72
	v_ashrrev_i32_e32 v74, 31, v74
	v_add_u32_e32 v61, -1, v61
	v_add_u32_e32 v63, -1, v63
	v_add_u32_e32 v65, -1, v65
	v_add_u32_e32 v67, -1, v67
	v_add_u32_e32 v69, -1, v69
	v_add_u32_e32 v71, -1, v71
	v_add_u32_e32 v73, -1, v73
	v_add_u32_e32 v75, -1, v75
	v_add_u32_e32 v60, 32, v60
	v_add_u32_e32 v62, 32, v62
	v_add_u32_e32 v64, 32, v64
	v_add_u32_e32 v66, 32, v66
	v_add_u32_e32 v68, 32, v68
	v_add_u32_e32 v70, 32, v70
	v_add_u32_e32 v72, 32, v72
	v_add_u32_e32 v74, 32, v74
	v_min_u32_e32 v60, v61, v60
	v_min_u32_e32 v61, v63, v62
	v_min_u32_e32 v62, v65, v64
	v_min_u32_e32 v63, v67, v66
	v_min_u32_e32 v64, v69, v68
	v_min_u32_e32 v65, v71, v70
	v_min_u32_e32 v66, v73, v72
	v_min_u32_e32 v67, v75, v74
	v_lshlrev_b64 v[16:17], v60, v[16:17]
	v_lshlrev_b64 v[18:19], v61, v[18:19]
	v_lshlrev_b64 v[20:21], v62, v[20:21]
	v_lshlrev_b64 v[22:23], v63, v[22:23]
	v_lshlrev_b64 v[24:25], v64, v[24:25]
	v_lshlrev_b64 v[26:27], v65, v[26:27]
	v_lshlrev_b64 v[28:29], v66, v[28:29]
	v_lshlrev_b64 v[30:31], v67, v[30:31]
	v_min_u32_e32 v16, 1, v16
	v_min_u32_e32 v18, 1, v18
	v_min_u32_e32 v20, 1, v20
	v_min_u32_e32 v22, 1, v22
	v_min_u32_e32 v24, 1, v24
	v_min_u32_e32 v26, 1, v26
	v_min_u32_e32 v28, 1, v28
	v_min_u32_e32 v30, 1, v30
	v_or_b32_e32 v16, v17, v16
	v_or_b32_e32 v17, v19, v18
	v_or_b32_e32 v18, v21, v20
	v_or_b32_e32 v19, v23, v22
	v_or_b32_e32 v20, v25, v24
	v_or_b32_e32 v21, v27, v26
	v_or_b32_e32 v22, v29, v28
	v_or_b32_e32 v23, v31, v30
	v_cvt_f32_i32_e32 v20, v20
	v_cvt_f32_i32_e32 v21, v21
	v_cvt_f32_i32_e32 v22, v22
	v_cvt_f32_i32_e32 v23, v23
	v_cvt_f32_i32_e32 v16, v16
	v_cvt_f32_i32_e32 v17, v17
	v_cvt_f32_i32_e32 v18, v18
	v_cvt_f32_i32_e32 v19, v19
	v_sub_u32_e32 v64, 32, v64
	v_sub_u32_e32 v65, 32, v65
	v_sub_u32_e32 v66, 32, v66
	v_sub_u32_e32 v67, 32, v67
	v_ldexp_f32 v20, v20, v64
	v_ldexp_f32 v21, v21, v65
	v_ldexp_f32 v22, v22, v66
	v_ldexp_f32 v23, v23, v67
	v_sub_u32_e32 v60, 32, v60
	v_sub_u32_e32 v61, 32, v61
	v_sub_u32_e32 v62, 32, v62
	v_sub_u32_e32 v63, 32, v63
	v_pk_fma_f32 v[20:21], v[20:21], s[16:17], 1.0 op_sel_hi:[1,0,0]
	v_pk_fma_f32 v[22:23], v[22:23], s[16:17], 1.0 op_sel_hi:[1,0,0]
	v_ldexp_f32 v16, v16, v60
	v_ldexp_f32 v17, v17, v61
	v_ldexp_f32 v18, v18, v62
	v_ldexp_f32 v19, v19, v63
	v_pk_mul_f32 v[12:13], v[12:13], v[20:21]
	v_pk_mul_f32 v[14:15], v[14:15], v[22:23]
	v_pk_fma_f32 v[12:13], v[16:17], s[16:17], v[12:13] op_sel_hi:[1,0,1]
	v_pk_fma_f32 v[14:15], v[18:19], s[16:17], v[14:15] op_sel_hi:[1,0,1]
	v_cvt_pk_bf16_f32 v12, v12, v13
	v_cvt_pk_bf16_f32 v13, v14, v15
	global_store_dwordx2 v[38:39], v[12:13], off offset:2048
	s_waitcnt vmcnt(13)
	v_mov_b64_e32 v[12:13], v[206:207]
	v_mov_b64_e32 v[14:15], v[208:209]
	v_mov_b64_e32 v[16:17], v[210:211]
	v_mov_b64_e32 v[18:19], v[212:213]
	v_mov_b64_e32 v[20:21], v[214:215]
	v_mov_b64_e32 v[22:23], v[216:217]
	v_mov_b64_e32 v[24:25], v[218:219]
	v_mov_b64_e32 v[26:27], v[220:221]
	v_xor_b32_e32 v28, v12, v13
	v_xor_b32_e32 v30, v14, v15
	v_xor_b32_e32 v52, v16, v17
	v_xor_b32_e32 v54, v18, v19
	v_xor_b32_e32 v56, v20, v21
	v_xor_b32_e32 v58, v22, v23
	v_xor_b32_e32 v60, v24, v25
	v_xor_b32_e32 v62, v26, v27
	v_ffbh_i32_e32 v29, v13
	v_ffbh_i32_e32 v31, v15
	v_ffbh_i32_e32 v53, v17
	v_ffbh_i32_e32 v55, v19
	v_ffbh_i32_e32 v57, v21
	v_ffbh_i32_e32 v59, v23
	v_ffbh_i32_e32 v61, v25
	v_ffbh_i32_e32 v63, v27
	v_ashrrev_i32_e32 v28, 31, v28
	v_ashrrev_i32_e32 v30, 31, v30
	v_ashrrev_i32_e32 v52, 31, v52
	v_ashrrev_i32_e32 v54, 31, v54
	v_ashrrev_i32_e32 v56, 31, v56
	v_ashrrev_i32_e32 v58, 31, v58
	v_ashrrev_i32_e32 v60, 31, v60
	v_ashrrev_i32_e32 v62, 31, v62
	v_add_u32_e32 v29, -1, v29
	v_add_u32_e32 v31, -1, v31
	v_add_u32_e32 v53, -1, v53
	v_add_u32_e32 v55, -1, v55
	v_add_u32_e32 v57, -1, v57
	v_add_u32_e32 v59, -1, v59
	v_add_u32_e32 v61, -1, v61
	v_add_u32_e32 v63, -1, v63
	v_add_u32_e32 v28, 32, v28
	v_add_u32_e32 v30, 32, v30
	v_add_u32_e32 v52, 32, v52
	v_add_u32_e32 v54, 32, v54
	v_add_u32_e32 v56, 32, v56
	v_add_u32_e32 v58, 32, v58
	v_add_u32_e32 v60, 32, v60
	v_add_u32_e32 v62, 32, v62
	v_min_u32_e32 v28, v29, v28
	v_min_u32_e32 v29, v31, v30
	v_min_u32_e32 v30, v53, v52
	v_min_u32_e32 v31, v55, v54
	v_min_u32_e32 v52, v57, v56
	v_min_u32_e32 v53, v59, v58
	v_min_u32_e32 v54, v61, v60
	v_min_u32_e32 v55, v63, v62
	v_lshlrev_b64 v[12:13], v28, v[12:13]
	v_lshlrev_b64 v[14:15], v29, v[14:15]
	v_lshlrev_b64 v[16:17], v30, v[16:17]
	v_lshlrev_b64 v[18:19], v31, v[18:19]
	v_lshlrev_b64 v[20:21], v52, v[20:21]
	v_lshlrev_b64 v[22:23], v53, v[22:23]
	v_lshlrev_b64 v[24:25], v54, v[24:25]
	v_lshlrev_b64 v[26:27], v55, v[26:27]
	v_min_u32_e32 v12, 1, v12
	v_min_u32_e32 v14, 1, v14
	v_min_u32_e32 v16, 1, v16
	v_min_u32_e32 v18, 1, v18
; __device__ __forceinline__ unsigned cvt_pk_bf16(float lo, float hi) { const bf16x2_t r = __builtin_convertvector((f32x2){lo, hi}, bf16x2_t); return __builtin_bit_cast(unsigned, r); }
; __device__ __forceinline__ f32x4 ld_fx4(const unsigned long long* p) {
;     const long long a = (long long)p[0], b = (long long)p[1], c = (long long)p[2], d = (long long)p[3];
;     return (f32x4){(float)a, (float)b, (float)c, (float)d} * 9.094947017729282e-13f;
; }
; template <bool FINAL>
; __device__ __forceinline__ void norm_phase(const float* X, const float* mod, bf16_t* H, const float* fg, float* OUT, const unsigned long long* acc64 = nullptr, float* modf = nullptr) {
;     ...
;             const float* mb = mod + (r >> 12) * 6144; const unsigned long long* mb64 = acc64 + (r >> 12) * 6144;
; #pragma unroll
;             for (int j = 0; j < 8; ++j) { const f32x4 sh = acc64 ? ld_fx4(mb64 + 4 * (lane + 64 * j)) : *((const f32x4*)mb + lane + 64 * j), sc = acc64 ? ld_fx4(mb64 + DM + 4 * (lane + 64 * j)) : *((const f32x4*)(mb + DM) + lane + 64 * j);
;                 const f32x4 o = v[j] * rstd * (sc + 1.0f) + sh; u32x2 w; w.x = cvt_pk_bf16(o[0], o[1]); w.y = cvt_pk_bf16(o[2], o[3]);
;                 *((u32x2*)(H + (size_t)r * DM) + lane + 64 * j) = w; }
	v_min_u32_e32 v20, 1, v20
	v_min_u32_e32 v22, 1, v22
	v_min_u32_e32 v24, 1, v24
	v_min_u32_e32 v26, 1, v26
	v_or_b32_e32 v12, v13, v12
	v_or_b32_e32 v13, v15, v14
	v_or_b32_e32 v14, v17, v16
	v_or_b32_e32 v15, v19, v18
	v_or_b32_e32 v16, v21, v20
	v_or_b32_e32 v17, v23, v22
	v_or_b32_e32 v18, v25, v24
	v_or_b32_e32 v19, v27, v26
	v_cvt_f32_i32_e32 v16, v16
	v_cvt_f32_i32_e32 v17, v17
	v_cvt_f32_i32_e32 v18, v18
	v_cvt_f32_i32_e32 v19, v19
	v_cvt_f32_i32_e32 v12, v12
	v_cvt_f32_i32_e32 v13, v13
	v_cvt_f32_i32_e32 v14, v14
	v_cvt_f32_i32_e32 v15, v15
	v_sub_u32_e32 v52, 32, v52
	v_sub_u32_e32 v53, 32, v53
	v_sub_u32_e32 v54, 32, v54
	v_sub_u32_e32 v55, 32, v55
	v_ldexp_f32 v16, v16, v52
	v_ldexp_f32 v17, v17, v53
	v_ldexp_f32 v18, v18, v54
	v_ldexp_f32 v19, v19, v55
	v_sub_u32_e32 v28, 32, v28
	v_sub_u32_e32 v29, 32, v29
	v_sub_u32_e32 v30, 32, v30
	v_sub_u32_e32 v31, 32, v31
	v_pk_fma_f32 v[16:17], v[16:17], s[16:17], 1.0 op_sel_hi:[1,0,0]
	v_pk_fma_f32 v[18:19], v[18:19], s[16:17], 1.0 op_sel_hi:[1,0,0]
	v_ldexp_f32 v12, v12, v28
	v_ldexp_f32 v13, v13, v29
	v_ldexp_f32 v14, v14, v30
	v_ldexp_f32 v15, v15, v31
	v_pk_mul_f32 v[10:11], v[10:11], v[16:17]
	v_pk_mul_f32 v[8:9], v[8:9], v[18:19]
	v_pk_fma_f32 v[10:11], v[12:13], s[16:17], v[10:11] op_sel_hi:[1,0,1]
	v_pk_fma_f32 v[8:9], v[14:15], s[16:17], v[8:9] op_sel_hi:[1,0,1]
	v_cvt_pk_bf16_f32 v10, v10, v11
	v_cvt_pk_bf16_f32 v11, v8, v9
	global_store_dwordx2 v[38:39], v[10:11], off offset:2560
	s_waitcnt vmcnt(10)
	v_mov_b64_e32 v[8:9], v[222:223]
	v_mov_b64_e32 v[10:11], v[224:225]
	v_mov_b64_e32 v[12:13], v[226:227]
	v_mov_b64_e32 v[14:15], v[228:229]
	v_mov_b64_e32 v[16:17], v[230:231]
	v_mov_b64_e32 v[18:19], v[232:233]
	v_mov_b64_e32 v[20:21], v[234:235]
	v_mov_b64_e32 v[22:23], v[236:237]
	v_xor_b32_e32 v24, v8, v9
	v_xor_b32_e32 v26, v10, v11
	v_xor_b32_e32 v28, v12, v13
	v_xor_b32_e32 v30, v14, v15
	v_xor_b32_e32 v48, v16, v17
	v_xor_b32_e32 v50, v18, v19
	v_xor_b32_e32 v52, v20, v21
	v_xor_b32_e32 v54, v22, v23
	v_ffbh_i32_e32 v25, v9
	v_ffbh_i32_e32 v27, v11
	v_ffbh_i32_e32 v29, v13
	v_ffbh_i32_e32 v31, v15
	v_ffbh_i32_e32 v49, v17
	v_ffbh_i32_e32 v51, v19
	v_ffbh_i32_e32 v53, v21
	v_ffbh_i32_e32 v55, v23
	v_ashrrev_i32_e32 v24, 31, v24
	v_ashrrev_i32_e32 v26, 31, v26
	v_ashrrev_i32_e32 v28, 31, v28
	v_ashrrev_i32_e32 v30, 31, v30
	v_ashrrev_i32_e32 v48, 31, v48
	v_ashrrev_i32_e32 v50, 31, v50
	v_ashrrev_i32_e32 v52, 31, v52
	v_ashrrev_i32_e32 v54, 31, v54
	v_add_u32_e32 v25, -1, v25
	v_add_u32_e32 v27, -1, v27
	v_add_u32_e32 v29, -1, v29
	v_add_u32_e32 v31, -1, v31
	v_add_u32_e32 v49, -1, v49
	v_add_u32_e32 v51, -1, v51
	v_add_u32_e32 v53, -1, v53
	v_add_u32_e32 v55, -1, v55
	v_add_u32_e32 v24, 32, v24
	v_add_u32_e32 v26, 32, v26
	v_add_u32_e32 v28, 32, v28
	v_add_u32_e32 v30, 32, v30
	v_add_u32_e32 v48, 32, v48
	v_add_u32_e32 v50, 32, v50
	v_add_u32_e32 v52, 32, v52
	v_add_u32_e32 v54, 32, v54
	v_min_u32_e32 v24, v25, v24
	v_min_u32_e32 v25, v27, v26
	v_min_u32_e32 v26, v29, v28
	v_min_u32_e32 v27, v31, v30
	v_min_u32_e32 v28, v49, v48
	v_min_u32_e32 v29, v51, v50
	v_min_u32_e32 v30, v53, v52
	v_min_u32_e32 v31, v55, v54
	v_lshlrev_b64 v[8:9], v24, v[8:9]
	v_lshlrev_b64 v[10:11], v25, v[10:11]
	v_lshlrev_b64 v[12:13], v26, v[12:13]
	v_lshlrev_b64 v[14:15], v27, v[14:15]
	v_lshlrev_b64 v[16:17], v28, v[16:17]
	v_lshlrev_b64 v[18:19], v29, v[18:19]
	v_lshlrev_b64 v[20:21], v30, v[20:21]
	v_lshlrev_b64 v[22:23], v31, v[22:23]
	v_min_u32_e32 v8, 1, v8
	v_min_u32_e32 v10, 1, v10
	v_min_u32_e32 v12, 1, v12
	v_min_u32_e32 v14, 1, v14
	v_min_u32_e32 v16, 1, v16
	v_min_u32_e32 v18, 1, v18
	v_min_u32_e32 v20, 1, v20
	v_min_u32_e32 v22, 1, v22
	v_or_b32_e32 v8, v9, v8
	v_or_b32_e32 v9, v11, v10
	v_or_b32_e32 v10, v13, v12
	v_or_b32_e32 v11, v15, v14
	v_or_b32_e32 v12, v17, v16
	v_or_b32_e32 v13, v19, v18
	v_or_b32_e32 v14, v21, v20
	v_or_b32_e32 v15, v23, v22
	v_cvt_f32_i32_e32 v12, v12
	v_cvt_f32_i32_e32 v13, v13
	v_cvt_f32_i32_e32 v14, v14
	v_cvt_f32_i32_e32 v15, v15
	v_cvt_f32_i32_e32 v8, v8
	v_cvt_f32_i32_e32 v9, v9
	v_cvt_f32_i32_e32 v10, v10
	v_cvt_f32_i32_e32 v11, v11
	v_sub_u32_e32 v28, 32, v28
	v_sub_u32_e32 v29, 32, v29
	v_sub_u32_e32 v30, 32, v30
	v_sub_u32_e32 v31, 32, v31
	v_ldexp_f32 v12, v12, v28
	v_ldexp_f32 v13, v13, v29
	v_ldexp_f32 v14, v14, v30
	v_ldexp_f32 v15, v15, v31
	v_sub_u32_e32 v24, 32, v24
	v_sub_u32_e32 v25, 32, v25
	v_sub_u32_e32 v26, 32, v26
	v_sub_u32_e32 v27, 32, v27
	v_pk_fma_f32 v[12:13], v[12:13], s[16:17], 1.0 op_sel_hi:[1,0,0]
	v_pk_fma_f32 v[14:15], v[14:15], s[16:17], 1.0 op_sel_hi:[1,0,0]
	v_ldexp_f32 v8, v8, v24
	v_ldexp_f32 v9, v9, v25
	v_ldexp_f32 v10, v10, v26
	v_ldexp_f32 v11, v11, v27
	v_pk_mul_f32 v[6:7], v[6:7], v[12:13]
	v_pk_mul_f32 v[4:5], v[4:5], v[14:15]
	v_pk_fma_f32 v[6:7], v[8:9], s[16:17], v[6:7] op_sel_hi:[1,0,1]
	v_pk_fma_f32 v[4:5], v[10:11], s[16:17], v[4:5] op_sel_hi:[1,0,1]
	v_cvt_pk_bf16_f32 v6, v6, v7
	v_cvt_pk_bf16_f32 v7, v4, v5
	global_store_dwordx2 v[38:39], v[6:7], off offset:3072
	s_waitcnt vmcnt(7)
; __device__ __forceinline__ unsigned cvt_pk_bf16(float lo, float hi) { const bf16x2_t r = __builtin_convertvector((f32x2){lo, hi}, bf16x2_t); return __builtin_bit_cast(unsigned, r); }
; __device__ __forceinline__ f32x4 ld_fx4(const unsigned long long* p) {
;     const long long a = (long long)p[0], b = (long long)p[1], c = (long long)p[2], d = (long long)p[3];
;     return (f32x4){(float)a, (float)b, (float)c, (float)d} * 9.094947017729282e-13f;
; }
; template <bool FINAL>
; __device__ __forceinline__ void norm_phase(const float* X, const float* mod, bf16_t* H, const float* fg, float* OUT, const unsigned long long* acc64 = nullptr, float* modf = nullptr) {
;     ...
;             const float* mb = mod + (r >> 12) * 6144; const unsigned long long* mb64 = acc64 + (r >> 12) * 6144;
; #pragma unroll
;             for (int j = 0; j < 8; ++j) { const f32x4 sh = acc64 ? ld_fx4(mb64 + 4 * (lane + 64 * j)) : *((const f32x4*)mb + lane + 64 * j), sc = acc64 ? ld_fx4(mb64 + DM + 4 * (lane + 64 * j)) : *((const f32x4*)(mb + DM) + lane + 64 * j);
;                 const f32x4 o = v[j] * rstd * (sc + 1.0f) + sh; u32x2 w; w.x = cvt_pk_bf16(o[0], o[1]); w.y = cvt_pk_bf16(o[2], o[3]);
;                 *((u32x2*)(H + (size_t)r * DM) + lane + 64 * j) = w; }
;         }
;     }
; }
	v_mov_b64_e32 v[4:5], v[238:239]
	v_mov_b64_e32 v[6:7], v[240:241]
	v_mov_b64_e32 v[8:9], v[242:243]
	v_mov_b64_e32 v[10:11], v[244:245]
	v_mov_b64_e32 v[12:13], v[246:247]
	v_mov_b64_e32 v[14:15], v[248:249]
	v_mov_b64_e32 v[16:17], v[250:251]
	v_mov_b64_e32 v[18:19], v[252:253]
	v_xor_b32_e32 v20, v4, v5
	v_xor_b32_e32 v22, v6, v7
	v_xor_b32_e32 v24, v8, v9
	v_xor_b32_e32 v26, v10, v11
	v_xor_b32_e32 v28, v12, v13
	v_xor_b32_e32 v30, v14, v15
	v_xor_b32_e32 v40, v16, v17
	v_xor_b32_e32 v42, v18, v19
	v_ffbh_i32_e32 v21, v5
	v_ffbh_i32_e32 v23, v7
	v_ffbh_i32_e32 v25, v9
	v_ffbh_i32_e32 v27, v11
	v_ffbh_i32_e32 v29, v13
	v_ffbh_i32_e32 v31, v15
	v_ffbh_i32_e32 v41, v17
	v_ffbh_i32_e32 v43, v19
	v_ashrrev_i32_e32 v20, 31, v20
	v_ashrrev_i32_e32 v22, 31, v22
	v_ashrrev_i32_e32 v24, 31, v24
	v_ashrrev_i32_e32 v26, 31, v26
	v_ashrrev_i32_e32 v28, 31, v28
	v_ashrrev_i32_e32 v30, 31, v30
	v_ashrrev_i32_e32 v40, 31, v40
	v_ashrrev_i32_e32 v42, 31, v42
	v_add_u32_e32 v21, -1, v21
	v_add_u32_e32 v23, -1, v23
	v_add_u32_e32 v25, -1, v25
	v_add_u32_e32 v27, -1, v27
	v_add_u32_e32 v29, -1, v29
	v_add_u32_e32 v31, -1, v31
	v_add_u32_e32 v41, -1, v41
	v_add_u32_e32 v43, -1, v43
	v_add_u32_e32 v20, 32, v20
	v_add_u32_e32 v22, 32, v22
	v_add_u32_e32 v24, 32, v24
	v_add_u32_e32 v26, 32, v26
	v_add_u32_e32 v28, 32, v28
	v_add_u32_e32 v30, 32, v30
	v_add_u32_e32 v40, 32, v40
	v_add_u32_e32 v42, 32, v42
	v_min_u32_e32 v20, v21, v20
	v_min_u32_e32 v21, v23, v22
	v_min_u32_e32 v22, v25, v24
	v_min_u32_e32 v23, v27, v26
	v_min_u32_e32 v24, v29, v28
	v_min_u32_e32 v25, v31, v30
	v_min_u32_e32 v26, v41, v40
	v_min_u32_e32 v27, v43, v42
	v_lshlrev_b64 v[4:5], v20, v[4:5]
	v_lshlrev_b64 v[6:7], v21, v[6:7]
	v_lshlrev_b64 v[8:9], v22, v[8:9]
	v_lshlrev_b64 v[10:11], v23, v[10:11]
	v_lshlrev_b64 v[12:13], v24, v[12:13]
	v_lshlrev_b64 v[14:15], v25, v[14:15]
	v_lshlrev_b64 v[16:17], v26, v[16:17]
	v_lshlrev_b64 v[18:19], v27, v[18:19]
	v_min_u32_e32 v4, 1, v4
	v_min_u32_e32 v6, 1, v6
	v_min_u32_e32 v8, 1, v8
	v_min_u32_e32 v10, 1, v10
	v_min_u32_e32 v12, 1, v12
	v_min_u32_e32 v14, 1, v14
	v_min_u32_e32 v16, 1, v16
	v_min_u32_e32 v18, 1, v18
	v_or_b32_e32 v4, v5, v4
	v_or_b32_e32 v5, v7, v6
	v_or_b32_e32 v6, v9, v8
	v_or_b32_e32 v7, v11, v10
	v_or_b32_e32 v8, v13, v12
	v_or_b32_e32 v9, v15, v14
	v_or_b32_e32 v10, v17, v16
	v_or_b32_e32 v11, v19, v18
	v_cvt_f32_i32_e32 v8, v8
	v_cvt_f32_i32_e32 v9, v9
	v_cvt_f32_i32_e32 v10, v10
	v_cvt_f32_i32_e32 v11, v11
	v_cvt_f32_i32_e32 v4, v4
	v_cvt_f32_i32_e32 v5, v5
	v_cvt_f32_i32_e32 v6, v6
	v_cvt_f32_i32_e32 v7, v7
	v_sub_u32_e32 v24, 32, v24
	v_sub_u32_e32 v25, 32, v25
	v_sub_u32_e32 v26, 32, v26
	v_sub_u32_e32 v27, 32, v27
	v_ldexp_f32 v8, v8, v24
	v_ldexp_f32 v9, v9, v25
	v_ldexp_f32 v10, v10, v26
	v_ldexp_f32 v11, v11, v27
	v_sub_u32_e32 v20, 32, v20
	v_sub_u32_e32 v21, 32, v21
	v_sub_u32_e32 v22, 32, v22
	v_sub_u32_e32 v23, 32, v23
	v_pk_fma_f32 v[8:9], v[8:9], s[16:17], 1.0 op_sel_hi:[1,0,0]
	v_pk_fma_f32 v[10:11], v[10:11], s[16:17], 1.0 op_sel_hi:[1,0,0]
	v_ldexp_f32 v4, v4, v20
	v_ldexp_f32 v5, v5, v21
	v_ldexp_f32 v6, v6, v22
	v_ldexp_f32 v7, v7, v23
	v_pk_mul_f32 v[2:3], v[2:3], v[8:9]
	v_pk_mul_f32 v[0:1], v[0:1], v[10:11]
	v_pk_fma_f32 v[2:3], v[4:5], s[16:17], v[2:3] op_sel_hi:[1,0,1]
	v_pk_fma_f32 v[0:1], v[6:7], s[16:17], v[0:1] op_sel_hi:[1,0,1]
	v_cvt_pk_bf16_f32 v2, v2, v3
	v_cvt_pk_bf16_f32 v3, v0, v1
	global_store_dwordx2 v[38:39], v[2:3], off offset:3584
	v_lshl_add_u64 v[38:39], v[38:39], 0, s[10:11]
	s_andn2_b64 exec, exec, s[12:13]
	s_cbranch_execnz .LBB0_121

; template <class Epi>
; __device__ __forceinline__ void gemm_phase(LAS unsigned char* lds, const bf16_t* A, int lda, const bf16_t* Bt, int ldb, int M, int N, int K, int asel, const Epi& E, const int fixed_round = -1) {
;     ...
;         const bool has_next = (fixed_round < 0) && S.next(ui + 1, nxt);
;         const char* nA = has_next ? PG8_ABASE(nxt) : cA; const char* nB = has_next ? (const char*)Bt + (size_t)nxt.pn * tstepB : cB;
;     ...
; #pragma unroll
;         for (int a = 0; a < 2; ++a)
; #pragma unroll
;             for (int b = 0; b < 2; ++b)
; #pragma unroll
;                 for (int m = 0; m < 4; ++m)
; #pragma unroll
;                     for (int n = 0; n < 2; ++n) acc[a][b][m][n] = (f32x4){0.f, 0.f, 0.f, 0.f};
;         cur = nxt; cA = nA; cB = nB; ++ui;
.LBB0_198:
	s_ashr_i32 s21, s20, 31
	v_cmp_lt_i64_e32 vcc, s[22:23], v[144:145]
	s_lshl_b64 s[22:23], s[20:21], 20
	s_add_u32 s22, s72, s22
	s_addc_u32 s23, s73, s23
	s_and_b64 s[24:25], vcc, exec
	s_cselect_b32 s4, s23, s29
	s_cselect_b32 s21, s22, s28
	s_ashr_i32 s19, s18, 31
	s_lshl_b64 s[24:25], s[18:19], 20
	s_add_u32 s24, s36, s24
	s_addc_u32 s25, s37, s25
	s_and_b64 s[34:35], vcc, exec
	s_cselect_b32 s19, s25, s31
	s_cselect_b32 s55, s24, s30
	s_add_u32 s28, s28, 0x80080
	s_addc_u32 s29, s29, 0
	s_add_u32 s56, s30, 0x100
	v_mov_b32_e32 v0, 0
	s_addc_u32 s57, s31, 0
	s_mov_b32 s58, -2
	v_mov_b32_e32 v1, v0
	v_mov_b64_e32 v[2:3], 0
	v_mov_b64_e32 v[4:5], 0
	v_mov_b64_e32 v[6:7], 0
	v_mov_b64_e32 v[8:9], 0
	v_mov_b64_e32 v[10:11], 0
	v_mov_b64_e32 v[16:17], 0
	v_mov_b64_e32 v[18:19], 0
	v_mov_b64_e32 v[24:25], 0
	v_mov_b64_e32 v[26:27], 0
	v_mov_b64_e32 v[32:33], 0
	v_mov_b64_e32 v[34:35], 0
	v_mov_b64_e32 v[40:41], 0
	v_mov_b64_e32 v[42:43], 0
	v_mov_b64_e32 v[48:49], 0
	v_mov_b64_e32 v[50:51], 0
	v_mov_b64_e32 v[12:13], 0
	v_mov_b64_e32 v[14:15], 0
	v_mov_b64_e32 v[20:21], 0
	v_mov_b64_e32 v[22:23], 0
	v_mov_b64_e32 v[28:29], 0
	v_mov_b64_e32 v[30:31], 0
	v_mov_b64_e32 v[36:37], 0
	v_mov_b64_e32 v[38:39], 0
	v_mov_b64_e32 v[44:45], 0
	v_mov_b64_e32 v[46:47], 0
	v_mov_b64_e32 v[52:53], 0
	v_mov_b64_e32 v[54:55], 0
	v_mov_b64_e32 v[56:57], 0
	v_mov_b64_e32 v[58:59], 0
	v_mov_b64_e32 v[60:61], 0
	v_mov_b64_e32 v[62:63], 0
	v_mov_b64_e32 v[64:65], 0
	v_mov_b64_e32 v[66:67], 0
	v_mov_b64_e32 v[68:69], 0
	v_mov_b64_e32 v[70:71], 0
	v_mov_b64_e32 v[72:73], 0
	v_mov_b64_e32 v[74:75], 0
	v_mov_b64_e32 v[80:81], 0
	v_mov_b64_e32 v[82:83], 0
	v_mov_b64_e32 v[88:89], 0
	v_mov_b64_e32 v[90:91], 0
	v_mov_b64_e32 v[96:97], 0
	v_mov_b64_e32 v[98:99], 0
	v_mov_b64_e32 v[104:105], 0
	v_mov_b64_e32 v[106:107], 0
	v_mov_b64_e32 v[116:117], 0
	v_mov_b64_e32 v[118:119], 0
	v_mov_b64_e32 v[76:77], 0
	v_mov_b64_e32 v[78:79], 0
	v_mov_b64_e32 v[84:85], 0
	v_mov_b64_e32 v[86:87], 0
	v_mov_b64_e32 v[92:93], 0
	v_mov_b64_e32 v[94:95], 0
	v_mov_b64_e32 v[100:101], 0
	v_mov_b64_e32 v[102:103], 0
	v_mov_b64_e32 v[108:109], 0
	v_mov_b64_e32 v[110:111], 0
	v_mov_b64_e32 v[112:113], 0
	v_mov_b64_e32 v[114:115], 0
	v_mov_b64_e32 v[120:121], 0
	v_mov_b64_e32 v[122:123], 0
	v_mov_b64_e32 v[124:125], 0
	v_mov_b64_e32 v[126:127], 0
	s_branch .LBB0_199

; template <class Epi>
; __device__ __forceinline__ void gemm_phase(LAS unsigned char* lds, const bf16_t* A, int lda, const bf16_t* Bt, int ldb, int M, int N, int K, int asel, const Epi& E, const int fixed_round = -1) {
;     ...
;         const bool has_next = (fixed_round < 0) && S.next(ui + 1, nxt);
;         const char* nA = has_next ? PG8_ABASE(nxt) : cA; const char* nB = has_next ? (const char*)Bt + (size_t)nxt.pn * tstepB : cB;
;     ...
; #pragma unroll
;         for (int a = 0; a < 2; ++a)
; #pragma unroll
;             for (int b = 0; b < 2; ++b)
; #pragma unroll
;                 for (int m = 0; m < 4; ++m)
; #pragma unroll
;                     for (int n = 0; n < 2; ++n) acc[a][b][m][n] = (f32x4){0.f, 0.f, 0.f, 0.f};
;         cur = nxt; cA = nA; cB = nB; ++ui;
.LBB0_223:
	s_ashr_i32 s11, s10, 31
	v_cmp_lt_i64_e32 vcc, s[12:13], v[136:137]
	s_lshl_b64 s[12:13], s[10:11], 20
	s_add_u32 s12, s72, s12
	s_addc_u32 s13, s73, s13
	s_and_b64 s[14:15], vcc, exec
	s_cselect_b32 s11, s13, s17
	s_cselect_b32 s37, s12, s16
	s_ashr_i32 s9, s8, 31
	s_lshl_b64 s[14:15], s[8:9], 20
	s_add_u32 s14, s23, s14
	s_addc_u32 s15, s24, s15
	s_and_b64 s[20:21], vcc, exec
	s_cselect_b32 s9, s15, s19
	s_cselect_b32 s38, s14, s18
	s_add_u32 s16, s16, 0x80080
	s_addc_u32 s17, s17, 0
	s_add_u32 s39, s18, 0x100
	v_mov_b32_e32 v0, 0
	s_addc_u32 s40, s19, 0
	s_mov_b32 s41, -2
	v_mov_b32_e32 v1, v0
	v_mov_b64_e32 v[2:3], 0
	v_mov_b64_e32 v[16:17], 0
	v_mov_b64_e32 v[18:19], 0
	v_mov_b64_e32 v[4:5], 0
	v_mov_b64_e32 v[6:7], 0
	v_mov_b64_e32 v[20:21], 0
	v_mov_b64_e32 v[22:23], 0
	v_mov_b64_e32 v[8:9], 0
	v_mov_b64_e32 v[10:11], 0
	v_mov_b64_e32 v[24:25], 0
	v_mov_b64_e32 v[26:27], 0
	v_mov_b64_e32 v[12:13], 0
	v_mov_b64_e32 v[14:15], 0
	v_mov_b64_e32 v[32:33], 0
	v_mov_b64_e32 v[34:35], 0
	v_mov_b64_e32 v[44:45], 0
	v_mov_b64_e32 v[46:47], 0
	v_mov_b64_e32 v[76:77], 0
	v_mov_b64_e32 v[78:79], 0
	v_mov_b64_e32 v[56:57], 0
	v_mov_b64_e32 v[58:59], 0
	v_mov_b64_e32 v[84:85], 0
	v_mov_b64_e32 v[86:87], 0
	v_mov_b64_e32 v[64:65], 0
	v_mov_b64_e32 v[66:67], 0
	v_mov_b64_e32 v[88:89], 0
	v_mov_b64_e32 v[90:91], 0
	v_mov_b64_e32 v[72:73], 0
	v_mov_b64_e32 v[74:75], 0
	v_mov_b64_e32 v[96:97], 0
	v_mov_b64_e32 v[98:99], 0
	v_mov_b64_e32 v[28:29], 0
	v_mov_b64_e32 v[30:31], 0
	v_mov_b64_e32 v[52:53], 0
	v_mov_b64_e32 v[54:55], 0
	v_mov_b64_e32 v[36:37], 0
	v_mov_b64_e32 v[38:39], 0
	v_mov_b64_e32 v[60:61], 0
	v_mov_b64_e32 v[62:63], 0
	v_mov_b64_e32 v[40:41], 0
	v_mov_b64_e32 v[42:43], 0
	v_mov_b64_e32 v[68:69], 0
	v_mov_b64_e32 v[70:71], 0
	v_mov_b64_e32 v[48:49], 0
	v_mov_b64_e32 v[50:51], 0
	v_mov_b64_e32 v[80:81], 0
	v_mov_b64_e32 v[82:83], 0
	v_mov_b64_e32 v[92:93], 0
	v_mov_b64_e32 v[94:95], 0
	v_mov_b64_e32 v[112:113], 0
	v_mov_b64_e32 v[114:115], 0
	v_mov_b64_e32 v[100:101], 0
	v_mov_b64_e32 v[102:103], 0
	v_mov_b64_e32 v[116:117], 0
	v_mov_b64_e32 v[118:119], 0
	v_mov_b64_e32 v[104:105], 0
	v_mov_b64_e32 v[106:107], 0
	v_mov_b64_e32 v[120:121], 0
	v_mov_b64_e32 v[122:123], 0
	v_mov_b64_e32 v[108:109], 0
	v_mov_b64_e32 v[110:111], 0
	v_mov_b64_e32 v[124:125], 0
	v_mov_b64_e32 v[126:127], 0
	s_branch .LBB0_224

; template <class Epi>
; __device__ __forceinline__ void gemm_phase(LAS unsigned char* lds, const bf16_t* A, int lda, const bf16_t* Bt, int ldb, int M, int N, int K, int asel, const Epi& E, const int fixed_round = -1) {
;     ...
;         const bool has_next = (fixed_round < 0) && S.next(ui + 1, nxt);
;         const char* nA = has_next ? PG8_ABASE(nxt) : cA; const char* nB = has_next ? (const char*)Bt + (size_t)nxt.pn * tstepB : cB;
;     ...
; #pragma unroll
;         for (int a = 0; a < 2; ++a)
; #pragma unroll
;             for (int b = 0; b < 2; ++b)
; #pragma unroll
;                 for (int m = 0; m < 4; ++m)
; #pragma unroll
;                     for (int n = 0; n < 2; ++n) acc[a][b][m][n] = (f32x4){0.f, 0.f, 0.f, 0.f};
;         cur = nxt; cA = nA; cB = nB; ++ui;
.LBB0_244:
	s_ashr_i32 s19, s18, 31
	v_cmp_lt_i64_e32 vcc, s[20:21], v[144:145]
	s_lshl_b64 s[20:21], s[18:19], 20
	s_add_u32 s20, s72, s20
	s_addc_u32 s21, s73, s21
	s_and_b64 s[22:23], vcc, exec
	s_cselect_b32 s2, s21, s27
	s_cselect_b32 s19, s20, s26
	s_ashr_i32 s17, s16, 31
	s_lshl_b64 s[22:23], s[16:17], 20
	s_add_u32 s22, s34, s22
	s_addc_u32 s23, s35, s23
	s_and_b64 s[30:31], vcc, exec
	s_cselect_b32 s17, s23, s29
	s_cselect_b32 s54, s22, s28
	s_add_u32 s26, s26, 0x80080
	s_addc_u32 s27, s27, 0
	s_add_u32 s55, s28, 0x100
	v_mov_b32_e32 v0, 0
	s_addc_u32 s56, s29, 0
	s_mov_b32 s57, -2
	v_mov_b32_e32 v1, v0
	v_mov_b64_e32 v[2:3], 0
	v_mov_b64_e32 v[4:5], 0
	v_mov_b64_e32 v[6:7], 0
	v_mov_b64_e32 v[8:9], 0
	v_mov_b64_e32 v[10:11], 0
	v_mov_b64_e32 v[16:17], 0
	v_mov_b64_e32 v[18:19], 0
	v_mov_b64_e32 v[24:25], 0
	v_mov_b64_e32 v[26:27], 0
	v_mov_b64_e32 v[32:33], 0
	v_mov_b64_e32 v[34:35], 0
	v_mov_b64_e32 v[40:41], 0
	v_mov_b64_e32 v[42:43], 0
	v_mov_b64_e32 v[48:49], 0
	v_mov_b64_e32 v[50:51], 0
	v_mov_b64_e32 v[12:13], 0
	v_mov_b64_e32 v[14:15], 0
	v_mov_b64_e32 v[20:21], 0
	v_mov_b64_e32 v[22:23], 0
	v_mov_b64_e32 v[28:29], 0
	v_mov_b64_e32 v[30:31], 0
	v_mov_b64_e32 v[36:37], 0
	v_mov_b64_e32 v[38:39], 0
	v_mov_b64_e32 v[44:45], 0
	v_mov_b64_e32 v[46:47], 0
	v_mov_b64_e32 v[52:53], 0
	v_mov_b64_e32 v[54:55], 0
	v_mov_b64_e32 v[56:57], 0
	v_mov_b64_e32 v[58:59], 0
	v_mov_b64_e32 v[60:61], 0
	v_mov_b64_e32 v[62:63], 0
	v_mov_b64_e32 v[64:65], 0
	v_mov_b64_e32 v[66:67], 0
	v_mov_b64_e32 v[68:69], 0
	v_mov_b64_e32 v[70:71], 0
	v_mov_b64_e32 v[72:73], 0
	v_mov_b64_e32 v[74:75], 0
	v_mov_b64_e32 v[80:81], 0
	v_mov_b64_e32 v[82:83], 0
	v_mov_b64_e32 v[88:89], 0
	v_mov_b64_e32 v[90:91], 0
	v_mov_b64_e32 v[96:97], 0
	v_mov_b64_e32 v[98:99], 0
	v_mov_b64_e32 v[104:105], 0
	v_mov_b64_e32 v[106:107], 0
	v_mov_b64_e32 v[116:117], 0
	v_mov_b64_e32 v[118:119], 0
	v_mov_b64_e32 v[76:77], 0
	v_mov_b64_e32 v[78:79], 0
	v_mov_b64_e32 v[84:85], 0
	v_mov_b64_e32 v[86:87], 0
	v_mov_b64_e32 v[92:93], 0
	v_mov_b64_e32 v[94:95], 0
	v_mov_b64_e32 v[100:101], 0
	v_mov_b64_e32 v[102:103], 0
	v_mov_b64_e32 v[108:109], 0
	v_mov_b64_e32 v[110:111], 0
	v_mov_b64_e32 v[112:113], 0
	v_mov_b64_e32 v[114:115], 0
	v_mov_b64_e32 v[120:121], 0
	v_mov_b64_e32 v[122:123], 0
	v_mov_b64_e32 v[124:125], 0
	v_mov_b64_e32 v[126:127], 0
	s_branch .LBB0_245

; #define LAS __attribute__((address_space(3)))
; __device__ __forceinline__ int opaque_tid() { int t = threadIdx.x; asm volatile("" : "+v"(t)); return t; }
; __device__ __forceinline__ void build_head_scale_table(LAS unsigned char* lds, const float* SS, const int round) {
;     const int tid = opaque_tid();
;     if (tid < 256) {
;         const int c = blockIdx.x, pm = 32 * round + 4 * (c & 7) + (c >> 6);
;         const f32x4* sp = (const f32x4*)(SS + ((size_t)pm * 256 + tid) * 64);
;         LAS float* rt = (LAS float*)(lds + L_RT) + tid * 8;
;         float prev = 0.f;
; #pragma unroll 1
;         for (int h = 0; h < 8; ++h) { const f32x4 a = sp[2 * h], b = sp[2 * h + 1];
;             const float ms = (((a[0] + a[1]) + (a[2] + a[3])) + ((b[0] + b[1]) + (b[2] + b[3]))) * (1.0f / DV) + EPS;
;             if (h > 0) rt[h - 1] = prev * sqrtf(ms);
;             prev = rsqrtf(ms); }
;         rt[7] = prev;
.LBB0_433:
	s_waitcnt vmcnt(19)
	v_lshl_add_u64 v[12:13], v[0:1], 0, s[4:5]
	v_add_co_u32_e32 v8, vcc, 0x644000, v12
	s_cmp_eq_u32 s4, 0
	s_nop 0
	v_addc_co_u32_e32 v9, vcc, 0, v13, vcc
	v_lshl_add_u64 v[12:13], v[12:13], 0, s[6:7]
	s_waitcnt vmcnt(0)
	v_mov_b64_e32 v[8:9], v[16:17]
	v_mov_b64_e32 v[10:11], v[18:19]
	s_nop 0
	v_mov_b64_e32 v[12:13], v[20:21]
	v_mov_b64_e32 v[14:15], v[22:23]
	v_mov_b64_e32 v[16:17], v[24:25]
	v_mov_b64_e32 v[18:19], v[26:27]
	v_mov_b64_e32 v[20:21], v[28:29]
	v_mov_b64_e32 v[22:23], v[30:31]
	v_mov_b64_e32 v[24:25], v[32:33]
	v_mov_b64_e32 v[26:27], v[34:35]
	v_mov_b64_e32 v[28:29], v[36:37]
	v_mov_b64_e32 v[30:31], v[38:39]
	v_mov_b64_e32 v[32:33], v[40:41]
	v_mov_b64_e32 v[34:35], v[42:43]
	v_mov_b64_e32 v[36:37], v[44:45]
	v_mov_b64_e32 v[38:39], v[46:47]
	v_mov_b64_e32 v[40:41], v[48:49]
	v_mov_b64_e32 v[42:43], v[50:51]
	v_mov_b64_e32 v[44:45], v[52:53]
	v_mov_b64_e32 v[46:47], v[54:55]
	v_mov_b64_e32 v[48:49], v[56:57]
	v_mov_b64_e32 v[50:51], v[58:59]
	v_mov_b64_e32 v[52:53], v[60:61]
	v_mov_b64_e32 v[54:55], v[62:63]
	v_mov_b64_e32 v[56:57], v[64:65]
	v_mov_b64_e32 v[58:59], v[66:67]
	v_mov_b64_e32 v[60:61], v[68:69]
	v_mov_b64_e32 v[62:63], v[70:71]
	v_mov_b64_e32 v[64:65], v[72:73]
	v_mov_b64_e32 v[66:67], v[74:75]
	v_mov_b64_e32 v[68:69], v[76:77]
	v_mov_b64_e32 v[70:71], v[78:79]
	s_waitcnt vmcnt(1)
	v_add_f32_e32 v7, v8, v9
	v_add_f32_e32 v8, v10, v11
	s_waitcnt vmcnt(0)
	v_add_f32_e32 v9, v12, v13
	v_add_f32_e32 v10, v14, v15
	v_add_f32_e32 v7, v7, v8
	v_add_f32_e32 v8, v9, v10
	v_add_f32_e32 v7, v7, v8
	v_fmamk_f32 v7, v7, 0x3b800000, v4
	s_cbranch_scc1 .LBB0_432
	v_mul_f32_e32 v8, 0x4f800000, v7
	v_cmp_gt_f32_e32 vcc, s10, v7
	s_nop 1
	v_cndmask_b32_e32 v8, v7, v8, vcc
	v_sqrt_f32_e32 v9, v8
	s_nop 0
	v_add_u32_e32 v10, -1, v9
	v_fma_f32 v12, -v10, v9, v8
	v_add_u32_e32 v11, 1, v9
	v_cmp_ge_f32_e64 s[0:1], 0, v12
	s_nop 1
	v_cndmask_b32_e64 v10, v9, v10, s[0:1]
	v_fma_f32 v9, -v11, v9, v8
	v_cmp_lt_f32_e64 s[0:1], 0, v9
	s_nop 1
	v_cndmask_b32_e64 v9, v10, v11, s[0:1]
	v_mul_f32_e32 v10, 0x37800000, v9
	v_cndmask_b32_e32 v9, v9, v10, vcc
	v_cmp_class_f32_e32 vcc, v8, v5
	s_nop 1
	v_cndmask_b32_e32 v8, v9, v8, vcc
	v_mul_f32_e32 v6, v6, v8
	ds_write_b32 v3, v6
	s_branch .LBB0_432

; #define LAS __attribute__((address_space(3)))
; __device__ __forceinline__ int opaque_tid() { int t = threadIdx.x; asm volatile("" : "+v"(t)); return t; }
; __device__ __forceinline__ void build_head_scale_table(LAS unsigned char* lds, const float* SS, const int round) {
;     const int tid = opaque_tid();
;     if (tid < 256) {
;         const int c = blockIdx.x, pm = 32 * round + 4 * (c & 7) + (c >> 6);
;         const f32x4* sp = (const f32x4*)(SS + ((size_t)pm * 256 + tid) * 64);
;         LAS float* rt = (LAS float*)(lds + L_RT) + tid * 8;
;         float prev = 0.f;
; #pragma unroll 1
;         for (int h = 0; h < 8; ++h) { const f32x4 a = sp[2 * h], b = sp[2 * h + 1];
;             const float ms = (((a[0] + a[1]) + (a[2] + a[3])) + ((b[0] + b[1]) + (b[2] + b[3]))) * (1.0f / DV) + EPS;
;             if (h > 0) rt[h - 1] = prev * sqrtf(ms);
;             prev = rsqrtf(ms); }
;         rt[7] = prev;
.LBB0_480:
	v_lshl_add_u64 v[10:11], v[0:1], 0, s[18:19]
	v_add_co_u32_e32 v6, vcc, 0x644000, v10
	s_cmp_eq_u32 s18, 0
	s_nop 0
	v_addc_co_u32_e32 v7, vcc, 0, v11, vcc
	v_lshl_add_u64 v[10:11], v[10:11], 0, s[20:21]
	s_waitcnt vmcnt(0)
	v_mov_b64_e32 v[6:7], v[16:17]
	v_mov_b64_e32 v[8:9], v[18:19]
	s_nop 0
	v_mov_b64_e32 v[10:11], v[20:21]
	v_mov_b64_e32 v[12:13], v[22:23]
	v_mov_b64_e32 v[16:17], v[24:25]
	v_mov_b64_e32 v[18:19], v[26:27]
	v_mov_b64_e32 v[20:21], v[28:29]
	v_mov_b64_e32 v[22:23], v[30:31]
	v_mov_b64_e32 v[24:25], v[32:33]
	v_mov_b64_e32 v[26:27], v[34:35]
	v_mov_b64_e32 v[28:29], v[36:37]
	v_mov_b64_e32 v[30:31], v[38:39]
	v_mov_b64_e32 v[32:33], v[40:41]
	v_mov_b64_e32 v[34:35], v[42:43]
	v_mov_b64_e32 v[36:37], v[44:45]
	v_mov_b64_e32 v[38:39], v[46:47]
	v_mov_b64_e32 v[40:41], v[48:49]
	v_mov_b64_e32 v[42:43], v[50:51]
	v_mov_b64_e32 v[44:45], v[52:53]
	v_mov_b64_e32 v[46:47], v[54:55]
	v_mov_b64_e32 v[48:49], v[56:57]
	v_mov_b64_e32 v[50:51], v[58:59]
	v_mov_b64_e32 v[52:53], v[60:61]
	v_mov_b64_e32 v[54:55], v[62:63]
	v_mov_b64_e32 v[56:57], v[64:65]
	v_mov_b64_e32 v[58:59], v[66:67]
	v_mov_b64_e32 v[60:61], v[68:69]
	v_mov_b64_e32 v[62:63], v[70:71]
	v_mov_b64_e32 v[64:65], v[72:73]
	v_mov_b64_e32 v[66:67], v[74:75]
	v_mov_b64_e32 v[68:69], v[76:77]
	v_mov_b64_e32 v[70:71], v[78:79]
	s_waitcnt vmcnt(1)
	v_add_f32_e32 v6, v6, v7
	v_add_f32_e32 v7, v8, v9
	s_waitcnt vmcnt(0)
	v_add_f32_e32 v8, v10, v11
	v_add_f32_e32 v9, v12, v13
	v_add_f32_e32 v6, v6, v7
	v_add_f32_e32 v7, v8, v9
	v_add_f32_e32 v6, v6, v7
	v_fmamk_f32 v6, v6, 0x3b800000, v4
	s_cbranch_scc1 .LBB0_479
	v_mul_f32_e32 v7, 0x4f800000, v6
	v_cmp_gt_f32_e32 vcc, s24, v6
	s_nop 1
	v_cndmask_b32_e32 v7, v6, v7, vcc
	v_sqrt_f32_e32 v8, v7
	s_nop 0
	v_add_u32_e32 v9, -1, v8
	v_fma_f32 v11, -v9, v8, v7
	v_add_u32_e32 v10, 1, v8
	v_cmp_ge_f32_e64 s[0:1], 0, v11
	s_nop 1
	v_cndmask_b32_e64 v9, v8, v9, s[0:1]
	v_fma_f32 v8, -v10, v8, v7
	v_cmp_lt_f32_e64 s[0:1], 0, v8
	s_nop 1
	v_cndmask_b32_e64 v8, v9, v10, s[0:1]
	v_mul_f32_e32 v9, 0x37800000, v8
	v_cndmask_b32_e32 v8, v8, v9, vcc
	v_cmp_class_f32_e32 vcc, v7, v5
	s_nop 1
	v_cndmask_b32_e32 v7, v8, v7, vcc
	v_mul_f32_e32 v7, v145, v7
	ds_write_b32 v3, v7
	s_branch .LBB0_479

; template <class Epi>
; __device__ __forceinline__ void gemm_phase(LAS unsigned char* lds, const bf16_t* A, int lda, const bf16_t* Bt, int ldb, int M, int N, int K, int asel, const Epi& E, const int fixed_round = -1) {
;     ...
;         const bool has_next = (fixed_round < 0) && S.next(ui + 1, nxt);
;         const char* nA = has_next ? PG8_ABASE(nxt) : cA; const char* nB = has_next ? (const char*)Bt + (size_t)nxt.pn * tstepB : cB;
;     ...
; #pragma unroll
;         for (int a = 0; a < 2; ++a)
; #pragma unroll
;             for (int b = 0; b < 2; ++b)
; #pragma unroll
;                 for (int m = 0; m < 4; ++m)
; #pragma unroll
;                     for (int n = 0; n < 2; ++n) acc[a][b][m][n] = (f32x4){0.f, 0.f, 0.f, 0.f};
;         cur = nxt; cA = nA; cB = nB; ++ui;
.LBB0_590:
	s_ashr_i32 s7, s6, 31
	v_cmp_lt_i64_e32 vcc, s[18:19], v[140:141]
	s_lshl_b64 s[18:19], s[6:7], 20
	s_add_u32 s18, s38, s18
	s_addc_u32 s19, s39, s19
	s_and_b64 s[20:21], vcc, exec
	s_cselect_b32 s7, s19, s31
	s_cselect_b32 s52, s18, s30
	s_ashr_i32 s5, s4, 31
	s_lshl_b64 s[20:21], s[4:5], 20
	s_add_u32 s20, s40, s20
	s_addc_u32 s21, s41, s21
	s_and_b64 s[28:29], vcc, exec
	s_cselect_b32 s5, s21, s35
	s_cselect_b32 s53, s20, s34
	s_add_u32 s30, s30, 0x80080
	s_addc_u32 s31, s31, 0
	s_add_u32 s54, s34, 0x100
	v_mov_b32_e32 v0, 0
	s_addc_u32 s55, s35, 0
	s_mov_b32 s56, -2
	v_mov_b32_e32 v1, v0
	v_mov_b64_e32 v[2:3], 0
	v_mov_b64_e32 v[4:5], 0
	v_mov_b64_e32 v[6:7], 0
	v_mov_b64_e32 v[16:17], 0
	v_mov_b64_e32 v[18:19], 0
	v_mov_b64_e32 v[20:21], 0
	v_mov_b64_e32 v[22:23], 0
	v_mov_b64_e32 v[32:33], 0
	v_mov_b64_e32 v[34:35], 0
	v_mov_b64_e32 v[36:37], 0
	v_mov_b64_e32 v[38:39], 0
	v_mov_b64_e32 v[48:49], 0
	v_mov_b64_e32 v[50:51], 0
	v_mov_b64_e32 v[52:53], 0
	v_mov_b64_e32 v[54:55], 0
	v_mov_b64_e32 v[8:9], 0
	v_mov_b64_e32 v[10:11], 0
	v_mov_b64_e32 v[12:13], 0
	v_mov_b64_e32 v[14:15], 0
	v_mov_b64_e32 v[24:25], 0
	v_mov_b64_e32 v[26:27], 0
	v_mov_b64_e32 v[28:29], 0
	v_mov_b64_e32 v[30:31], 0
	v_mov_b64_e32 v[40:41], 0
	v_mov_b64_e32 v[42:43], 0
	v_mov_b64_e32 v[44:45], 0
	v_mov_b64_e32 v[46:47], 0
	v_mov_b64_e32 v[56:57], 0
	v_mov_b64_e32 v[58:59], 0
	v_mov_b64_e32 v[60:61], 0
	v_mov_b64_e32 v[62:63], 0
	v_mov_b64_e32 v[64:65], 0
	v_mov_b64_e32 v[66:67], 0
	v_mov_b64_e32 v[68:69], 0
	v_mov_b64_e32 v[70:71], 0
	v_mov_b64_e32 v[80:81], 0
	v_mov_b64_e32 v[82:83], 0
	v_mov_b64_e32 v[84:85], 0
	v_mov_b64_e32 v[86:87], 0
	v_mov_b64_e32 v[96:97], 0
	v_mov_b64_e32 v[98:99], 0
	v_mov_b64_e32 v[100:101], 0
	v_mov_b64_e32 v[102:103], 0
	v_mov_b64_e32 v[112:113], 0
	v_mov_b64_e32 v[114:115], 0
	v_mov_b64_e32 v[116:117], 0
	v_mov_b64_e32 v[118:119], 0
	v_mov_b64_e32 v[72:73], 0
	v_mov_b64_e32 v[74:75], 0
	v_mov_b64_e32 v[76:77], 0
	v_mov_b64_e32 v[78:79], 0
	v_mov_b64_e32 v[88:89], 0
	v_mov_b64_e32 v[90:91], 0
	v_mov_b64_e32 v[92:93], 0
	v_mov_b64_e32 v[94:95], 0
	v_mov_b64_e32 v[104:105], 0
	v_mov_b64_e32 v[106:107], 0
	v_mov_b64_e32 v[108:109], 0
	v_mov_b64_e32 v[110:111], 0
	v_mov_b64_e32 v[120:121], 0
	v_mov_b64_e32 v[122:123], 0
	v_mov_b64_e32 v[124:125], 0
	v_mov_b64_e32 v[126:127], 0
	s_branch .LBB0_591

; template <class Epi>
; __device__ __forceinline__ void gemm_phase(LAS unsigned char* lds, const bf16_t* A, int lda, const bf16_t* Bt, int ldb, int M, int N, int K, int asel, const Epi& E, const int fixed_round = -1) {
;     ...
;         const bool has_next = (fixed_round < 0) && S.next(ui + 1, nxt);
;         const char* nA = has_next ? PG8_ABASE(nxt) : cA; const char* nB = has_next ? (const char*)Bt + (size_t)nxt.pn * tstepB : cB;
;     ...
; #pragma unroll
;         for (int a = 0; a < 2; ++a)
; #pragma unroll
;             for (int b = 0; b < 2; ++b)
; #pragma unroll
;                 for (int m = 0; m < 4; ++m)
; #pragma unroll
;                     for (int n = 0; n < 2; ++n) acc[a][b][m][n] = (f32x4){0.f, 0.f, 0.f, 0.f};
;         cur = nxt; cA = nA; cB = nB; ++ui;
.LBB0_798:
	s_ashr_i32 s41, s40, 31
	s_lshl_b64 s[28:29], s[40:41], 20
	v_cmp_lt_i64_e32 vcc, s[44:45], v[142:143]
	s_add_u32 s44, s72, s28
	s_addc_u32 s45, s73, s29
	s_and_b64 s[28:29], vcc, exec
	s_cselect_b32 s5, s45, s51
	s_cselect_b32 s41, s44, s50
	s_ashr_i32 s7, s6, 31
	s_lshl_b64 s[28:29], s[6:7], 20
	s_add_u32 s46, s56, s28
	s_addc_u32 s47, s57, s29
	s_and_b64 s[28:29], vcc, exec
	s_cselect_b32 s7, s47, s53
	s_cselect_b32 s65, s46, s52
	s_add_u32 s50, s50, 0x80080
	s_addc_u32 s51, s51, 0
	s_add_u32 s66, s52, 0x100
	v_mov_b32_e32 v0, 0
	s_addc_u32 s67, s53, 0
	s_mov_b32 s68, -2
	v_mov_b32_e32 v1, v0
	v_mov_b64_e32 v[2:3], 0
	v_mov_b64_e32 v[4:5], 0
	v_mov_b64_e32 v[6:7], 0
	v_mov_b64_e32 v[16:17], 0
	v_mov_b64_e32 v[18:19], 0
	v_mov_b64_e32 v[20:21], 0
	v_mov_b64_e32 v[22:23], 0
	v_mov_b64_e32 v[32:33], 0
	v_mov_b64_e32 v[34:35], 0
	v_mov_b64_e32 v[36:37], 0
	v_mov_b64_e32 v[38:39], 0
	v_mov_b64_e32 v[48:49], 0
	v_mov_b64_e32 v[50:51], 0
	v_mov_b64_e32 v[52:53], 0
	v_mov_b64_e32 v[54:55], 0
	v_mov_b64_e32 v[8:9], 0
	v_mov_b64_e32 v[10:11], 0
	v_mov_b64_e32 v[12:13], 0
	v_mov_b64_e32 v[14:15], 0
	v_mov_b64_e32 v[24:25], 0
	v_mov_b64_e32 v[26:27], 0
	v_mov_b64_e32 v[28:29], 0
	v_mov_b64_e32 v[30:31], 0
	v_mov_b64_e32 v[40:41], 0
	v_mov_b64_e32 v[42:43], 0
	v_mov_b64_e32 v[44:45], 0
	v_mov_b64_e32 v[46:47], 0
	v_mov_b64_e32 v[56:57], 0
	v_mov_b64_e32 v[58:59], 0
	v_mov_b64_e32 v[60:61], 0
	v_mov_b64_e32 v[62:63], 0
	v_mov_b64_e32 v[64:65], 0
	v_mov_b64_e32 v[66:67], 0
	v_mov_b64_e32 v[68:69], 0
	v_mov_b64_e32 v[70:71], 0
	v_mov_b64_e32 v[80:81], 0
	v_mov_b64_e32 v[82:83], 0
	v_mov_b64_e32 v[84:85], 0
	v_mov_b64_e32 v[86:87], 0
	v_mov_b64_e32 v[96:97], 0
	v_mov_b64_e32 v[98:99], 0
	v_mov_b64_e32 v[100:101], 0
	v_mov_b64_e32 v[102:103], 0
	v_mov_b64_e32 v[112:113], 0
	v_mov_b64_e32 v[114:115], 0
	v_mov_b64_e32 v[116:117], 0
	v_mov_b64_e32 v[118:119], 0
	v_mov_b64_e32 v[72:73], 0
	v_mov_b64_e32 v[74:75], 0
	v_mov_b64_e32 v[76:77], 0
	v_mov_b64_e32 v[78:79], 0
	v_mov_b64_e32 v[88:89], 0
	v_mov_b64_e32 v[90:91], 0
	v_mov_b64_e32 v[92:93], 0
	v_mov_b64_e32 v[94:95], 0
	v_mov_b64_e32 v[104:105], 0
	v_mov_b64_e32 v[106:107], 0
	v_mov_b64_e32 v[108:109], 0
	v_mov_b64_e32 v[110:111], 0
	v_mov_b64_e32 v[120:121], 0
	v_mov_b64_e32 v[122:123], 0
	v_mov_b64_e32 v[124:125], 0
	v_mov_b64_e32 v[126:127], 0
	s_branch .LBB0_799

; #define PG8_STAGE(bufoff, gbase, voff) do { _Pragma("unroll") for (int _i = 0; _i < 2; ++_i) \
;         __builtin_amdgcn_global_load_lds((const unsigned*)((const char*)(gbase) + (voff)[_i]), (LAS unsigned*)(lds + (bufoff) + ldsw + _i * 8192), 16, 0, 0); } while (0)
; #define PG8_LDA(dst, b, h) do { _Pragma("unroll") for (int m = 0; m < 4; ++m) _Pragma("unroll") for (int k = 0; k < 2; ++k) dst[m][k] = *(const LAS bf16x8*)(lds + PG8_SA(b, h) + aoff + m * 2048 + k * 1024); } while (0)
; #define PG8_LDB(dst, b, h) do { _Pragma("unroll") for (int n = 0; n < 2; ++n) _Pragma("unroll") for (int k = 0; k < 2; ++k) dst[n][k] = *(const LAS bf16x8*)(lds + PG8_SB(b, h) + boff + n * 2048 + k * 1024); } while (0)
; #define PG8_WAIT_V(n) asm volatile("s_waitcnt vmcnt(" #n ")" ::: "memory")
; #define PG8_WAIT_L(n) asm volatile("s_waitcnt lgkmcnt(" #n ")" ::: "memory")
; #define PG8_BAR __builtin_amdgcn_s_barrier()
; #define PG8_SCHED __builtin_amdgcn_sched_barrier(0)
; template <class Epi>
; __device__ __forceinline__ void gemm_phase(LAS unsigned char* lds, const bf16_t* A, int lda, const bf16_t* Bt, int ldb, int M, int N, int K, int asel, const Epi& E, const int fixed_round = -1) {
;     ...
;         for (int t = 0; t < nt; t += 2) {
;             const bool last = (t == nt - 2);
;             const char* a1 = cA + (size_t)(t + 1) * kstep;
;             const char* a2 = last ? nA : cA + (size_t)(t + 2) * kstep; const char* b2 = last ? nB : cB + (size_t)(t + 2) * kstep;
;             const char* a3 = a2 + kstep; const char* b3 = b2 + kstep;
;             PG8_LDB(B0, 0, 0); PG8_SCHED; PG8_LDA(At, 0, 0); PG8_STAGE(PG8_SA(1, 1), a1 + hstepA, voffA);
;             PG8_WAIT_L(8); PG8_BAR; PG8_WAIT_L(0); PG8_MMA(0, 0, At, B0); PG8_BAR; PG8_SCHED;
;             PG8_LDB(B1, 0, 1); PG8_STAGE(PG8_SB(0, 0), b2, voffB);
;             PG8_BAR; PG8_WAIT_L(0); PG8_MMA(0, 1, At, B1); PG8_BAR;
;             PG8_LDA(At, 0, 1); PG8_STAGE(PG8_SA(0, 0), a2, voffA);
;             PG8_BAR; PG8_WAIT_L(0); PG8_MMA(1, 0, At, B0); PG8_BAR; PG8_SCHED;
;             PG8_STAGE(PG8_SB(0, 1), b2 + hstepB, voffB);
;             PG8_WAIT_V(6); PG8_BAR; PG8_MMA(1, 1, At, B1); PG8_BAR;
.LBB0_938:
	s_ashr_i32 s57, s56, 31
	s_lshl_b64 s[2:3], s[56:57], 20
	s_add_u32 s28, s6, s2
	s_addc_u32 s29, s7, s3
	s_ashr_i32 s2, s54, 1
	s_ashr_i32 s3, s2, 31
	s_lshl_b64 s[2:3], s[2:3], 9
	s_add_u32 s58, s28, s2
	s_addc_u32 s59, s29, s3
	ds_read_b128 v[0:3], v215
	ds_read_b128 v[4:7], v215 offset:1024
	ds_read_b128 v[8:11], v215 offset:2048
	ds_read_b128 v[12:15], v215 offset:3072
	s_and_b64 s[2:3], exec, s[0:1]
	s_cselect_b32 s3, s59, s65
	s_cselect_b32 s2, s58, s64
	s_ashr_i32 s55, s54, 31
	s_lshl_b64 s[28:29], s[54:55], 17
	s_add_u32 s60, s68, s28
	s_addc_u32 s61, s69, s29
	s_and_b64 s[0:1], exec, s[0:1]
	s_cselect_b32 s1, s61, s67
	s_cselect_b32 s0, s60, s66
	s_add_u32 s28, s64, 0x80080
	s_addc_u32 s29, s65, 0
	s_add_i32 vcc_hi, s63, 0xc000
	v_lshl_add_u64 v[48:49], s[28:29], 0, v[140:141]
	s_mov_b32 m0, vcc_hi
	s_add_i32 s55, s63, 0xe000
	ds_read_b128 v[16:19], v216
	ds_read_b128 v[20:23], v216 offset:1024
	ds_read_b128 v[24:27], v216 offset:2048
	ds_read_b128 v[28:31], v216 offset:3072
	ds_read_b128 v[32:35], v216 offset:4096
	ds_read_b128 v[36:39], v216 offset:5120
	ds_read_b128 v[40:43], v216 offset:6144
	ds_read_b128 v[44:47], v216 offset:7168
	global_load_lds_dwordx4 v[48:49], off
	v_lshl_add_u64 v[48:49], s[28:29], 0, v[144:145]
	s_mov_b32 m0, s55
	s_nop 0
	global_load_lds_dwordx4 v[48:49], off
	s_waitcnt lgkmcnt(8)
	s_barrier
	s_waitcnt lgkmcnt(0)
	s_setprio 1
	s_waitcnt lgkmcnt(0)
	v_mfma_f32_16x16x32_bf16 v[48:51], v[0:3], v[16:19], 0
	v_mfma_f32_16x16x32_bf16 v[52:55], v[8:11], v[16:19], 0
	v_mfma_f32_16x16x32_bf16 v[56:59], v[0:3], v[24:27], 0
	v_mfma_f32_16x16x32_bf16 v[60:63], v[8:11], v[24:27], 0
	v_mfma_f32_16x16x32_bf16 v[64:67], v[0:3], v[32:35], 0
	v_mfma_f32_16x16x32_bf16 v[68:71], v[8:11], v[32:35], 0
	v_mfma_f32_16x16x32_bf16 v[72:75], v[0:3], v[40:43], 0
	v_mfma_f32_16x16x32_bf16 v[76:79], v[8:11], v[40:43], 0
	v_mfma_f32_16x16x32_bf16 v[48:51], v[4:7], v[20:23], v[48:51]
	v_mfma_f32_16x16x32_bf16 v[52:55], v[12:15], v[20:23], v[52:55]
	v_mfma_f32_16x16x32_bf16 v[56:59], v[4:7], v[28:31], v[56:59]
	v_mfma_f32_16x16x32_bf16 v[60:63], v[12:15], v[28:31], v[60:63]
	v_mfma_f32_16x16x32_bf16 v[64:67], v[4:7], v[36:39], v[64:67]
	v_mfma_f32_16x16x32_bf16 v[68:71], v[12:15], v[36:39], v[68:71]
	v_mfma_f32_16x16x32_bf16 v[72:75], v[4:7], v[44:47], v[72:75]
	v_mfma_f32_16x16x32_bf16 v[76:79], v[12:15], v[44:47], v[76:79]
	s_setprio 0
	s_barrier
	v_lshl_add_u64 v[198:199], s[66:67], 0, v[142:143]
	s_add_i32 s96, s81, s70
	v_lshl_add_u64 v[96:97], v[198:199], 0, s[46:47]
	s_mov_b32 m0, s96
	v_lshl_add_u64 v[210:211], s[66:67], 0, v[146:147]
	s_add_i32 s57, s96, 0x2000
	ds_read_b128 v[80:83], v217
	ds_read_b128 v[84:87], v217 offset:1024
	ds_read_b128 v[88:91], v217 offset:2048
	ds_read_b128 v[92:95], v217 offset:3072
	global_load_lds_dwordx4 v[96:97], off
	v_lshl_add_u64 v[96:97], v[210:211], 0, s[46:47]
	s_mov_b32 m0, s57
	s_nop 0
	global_load_lds_dwordx4 v[96:97], off
	s_barrier
	s_waitcnt lgkmcnt(0)
	s_setprio 1
	s_waitcnt lgkmcnt(0)
	v_mfma_f32_16x16x32_bf16 v[96:99], v[80:83], v[16:19], 0
	v_mfma_f32_16x16x32_bf16 v[16:19], v[88:91], v[16:19], 0
	v_mfma_f32_16x16x32_bf16 v[96:99], v[84:87], v[20:23], v[96:99]
	v_mfma_f32_16x16x32_bf16 v[16:19], v[92:95], v[20:23], v[16:19]
	v_mfma_f32_16x16x32_bf16 v[20:23], v[80:83], v[24:27], 0
	v_mfma_f32_16x16x32_bf16 v[24:27], v[88:91], v[24:27], 0
	v_mfma_f32_16x16x32_bf16 v[20:23], v[84:87], v[28:31], v[20:23]
	v_mfma_f32_16x16x32_bf16 v[24:27], v[92:95], v[28:31], v[24:27]
	v_mfma_f32_16x16x32_bf16 v[28:31], v[80:83], v[32:35], 0
	v_mfma_f32_16x16x32_bf16 v[32:35], v[88:91], v[32:35], 0
	v_mfma_f32_16x16x32_bf16 v[28:31], v[84:87], v[36:39], v[28:31]
	v_mfma_f32_16x16x32_bf16 v[32:35], v[92:95], v[36:39], v[32:35]
	v_mfma_f32_16x16x32_bf16 v[36:39], v[80:83], v[40:43], 0
	v_mfma_f32_16x16x32_bf16 v[40:43], v[88:91], v[40:43], 0
	v_mfma_f32_16x16x32_bf16 v[36:39], v[84:87], v[44:47], v[36:39]
	v_mfma_f32_16x16x32_bf16 v[40:43], v[92:95], v[44:47], v[40:43]
	s_setprio 0
	v_lshl_add_u64 v[224:225], s[64:65], 0, v[140:141]
	s_mov_b32 m0, s63
	v_lshl_add_u64 v[128:129], v[224:225], 0, s[46:47]
	v_lshl_add_u64 v[226:227], s[64:65], 0, v[144:145]
	s_barrier
	ds_read_b128 v[44:47], v216 offset:16384
	ds_read_b128 v[100:103], v216 offset:17408
	ds_read_b128 v[104:107], v216 offset:18432
	ds_read_b128 v[108:111], v216 offset:19456
	ds_read_b128 v[112:115], v216 offset:20480
	ds_read_b128 v[116:119], v216 offset:21504
	ds_read_b128 v[120:123], v216 offset:22528
	ds_read_b128 v[124:127], v216 offset:23552
	global_load_lds_dwordx4 v[128:129], off
	v_lshl_add_u64 v[128:129], v[226:227], 0, s[46:47]
	s_mov_b32 m0, s71
	s_nop 0
	global_load_lds_dwordx4 v[128:129], off
	s_barrier
	s_waitcnt lgkmcnt(0)
	s_setprio 1
	s_waitcnt lgkmcnt(0)
	v_mfma_f32_16x16x32_bf16 v[128:131], v[0:3], v[44:47], 0
	v_mfma_f32_16x16x32_bf16 v[136:139], v[0:3], v[104:107], 0
	v_mfma_f32_16x16x32_bf16 v[158:161], v[0:3], v[112:115], 0
	v_mfma_f32_16x16x32_bf16 v[0:3], v[0:3], v[120:123], 0
	v_mfma_f32_16x16x32_bf16 v[128:131], v[4:7], v[100:103], v[128:131]
	v_mfma_f32_16x16x32_bf16 v[132:135], v[8:11], v[44:47], 0
	v_mfma_f32_16x16x32_bf16 v[136:139], v[4:7], v[108:111], v[136:139]
	v_mfma_f32_16x16x32_bf16 v[154:157], v[8:11], v[104:107], 0
	v_mfma_f32_16x16x32_bf16 v[158:161], v[4:7], v[116:119], v[158:161]
	v_mfma_f32_16x16x32_bf16 v[162:165], v[8:11], v[112:115], 0
	v_mfma_f32_16x16x32_bf16 v[0:3], v[4:7], v[124:127], v[0:3]
	v_mfma_f32_16x16x32_bf16 v[4:7], v[8:11], v[120:123], 0
	v_mfma_f32_16x16x32_bf16 v[132:135], v[12:15], v[100:103], v[132:135]
	v_mfma_f32_16x16x32_bf16 v[154:157], v[12:15], v[108:111], v[154:157]
	v_mfma_f32_16x16x32_bf16 v[162:165], v[12:15], v[116:119], v[162:165]
	v_mfma_f32_16x16x32_bf16 v[4:7], v[12:15], v[124:127], v[4:7]
	s_setprio 0
	s_barrier
; #define PG8_STAGE(bufoff, gbase, voff) do { _Pragma("unroll") for (int _i = 0; _i < 2; ++_i) \
;         __builtin_amdgcn_global_load_lds((const unsigned*)((const char*)(gbase) + (voff)[_i]), (LAS unsigned*)(lds + (bufoff) + ldsw + _i * 8192), 16, 0, 0); } while (0)
; #define PG8_LDA(dst, b, h) do { _Pragma("unroll") for (int m = 0; m < 4; ++m) _Pragma("unroll") for (int k = 0; k < 2; ++k) dst[m][k] = *(const LAS bf16x8*)(lds + PG8_SA(b, h) + aoff + m * 2048 + k * 1024); } while (0)
; #define PG8_LDB(dst, b, h) do { _Pragma("unroll") for (int n = 0; n < 2; ++n) _Pragma("unroll") for (int k = 0; k < 2; ++k) dst[n][k] = *(const LAS bf16x8*)(lds + PG8_SB(b, h) + boff + n * 2048 + k * 1024); } while (0)
; #define PG8_WAIT_V(n) asm volatile("s_waitcnt vmcnt(" #n ")" ::: "memory")
; #define PG8_WAIT_L(n) asm volatile("s_waitcnt lgkmcnt(" #n ")" ::: "memory")
; #define PG8_BAR __builtin_amdgcn_s_barrier()
; #define PG8_SCHED __builtin_amdgcn_sched_barrier(0)
; template <class Epi>
; __device__ __forceinline__ void gemm_phase(LAS unsigned char* lds, const bf16_t* A, int lda, const bf16_t* Bt, int ldb, int M, int N, int K, int asel, const Epi& E, const int fixed_round = -1) {
;     ...
;             PG8_WAIT_L(8); PG8_BAR; PG8_WAIT_L(0); PG8_MMA(0, 0, At, B0); PG8_BAR; PG8_SCHED;
;             PG8_LDB(B1, 0, 1); PG8_STAGE(PG8_SB(0, 0), b2, voffB);
;             PG8_BAR; PG8_WAIT_L(0); PG8_MMA(0, 1, At, B1); PG8_BAR;
;             PG8_LDA(At, 0, 1); PG8_STAGE(PG8_SA(0, 0), a2, voffA);
;             PG8_BAR; PG8_WAIT_L(0); PG8_MMA(1, 0, At, B0); PG8_BAR; PG8_SCHED;
;             PG8_STAGE(PG8_SB(0, 1), b2 + hstepB, voffB);
;             PG8_WAIT_V(6); PG8_BAR; PG8_MMA(1, 1, At, B1); PG8_BAR;
;             PG8_LDB(B0, 1, 0); PG8_SCHED; PG8_LDA(At, 1, 0); PG8_STAGE(PG8_SA(0, 1), a2 + hstepA, voffA);
;             PG8_WAIT_L(8); PG8_BAR; PG8_WAIT_L(0); PG8_MMA(0, 0, At, B0); PG8_BAR; PG8_SCHED;
;             PG8_LDB(B1, 1, 1); PG8_STAGE(PG8_SB(1, 0), b3, voffB);
;             PG8_BAR; PG8_WAIT_L(0); PG8_MMA(0, 1, At, B1); PG8_BAR;
	s_add_u32 s28, s66, 0x10100
	s_addc_u32 s29, s67, 0
	s_add_i32 vcc_lo, s82, s70
	v_lshl_add_u64 v[8:9], s[28:29], 0, v[142:143]
	s_mov_b32 m0, vcc_lo
	s_add_i32 s95, vcc_lo, 0x2000
	global_load_lds_dwordx4 v[8:9], off
	v_lshl_add_u64 v[8:9], s[28:29], 0, v[146:147]
	s_mov_b32 m0, s95
	s_nop 0
	global_load_lds_dwordx4 v[8:9], off
	s_waitcnt vmcnt(6)
	s_barrier
	s_setprio 1
	v_mfma_f32_16x16x32_bf16 v[8:11], v[80:83], v[44:47], 0
	v_mfma_f32_16x16x32_bf16 v[12:15], v[88:91], v[44:47], 0
	v_mfma_f32_16x16x32_bf16 v[8:11], v[84:87], v[100:103], v[8:11]
	v_mfma_f32_16x16x32_bf16 v[12:15], v[92:95], v[100:103], v[12:15]
	v_mfma_f32_16x16x32_bf16 v[44:47], v[80:83], v[104:107], 0
	v_mfma_f32_16x16x32_bf16 v[100:103], v[88:91], v[104:107], 0
	v_mfma_f32_16x16x32_bf16 v[104:107], v[80:83], v[112:115], 0
	v_mfma_f32_16x16x32_bf16 v[80:83], v[80:83], v[120:123], 0
	v_mfma_f32_16x16x32_bf16 v[44:47], v[84:87], v[108:111], v[44:47]
	v_mfma_f32_16x16x32_bf16 v[100:103], v[92:95], v[108:111], v[100:103]
	v_mfma_f32_16x16x32_bf16 v[104:107], v[84:87], v[116:119], v[104:107]
	v_mfma_f32_16x16x32_bf16 v[108:111], v[88:91], v[112:115], 0
	v_mfma_f32_16x16x32_bf16 v[80:83], v[84:87], v[124:127], v[80:83]
	v_mfma_f32_16x16x32_bf16 v[84:87], v[88:91], v[120:123], 0
	v_mfma_f32_16x16x32_bf16 v[108:111], v[92:95], v[116:119], v[108:111]
	v_mfma_f32_16x16x32_bf16 v[84:87], v[92:95], v[124:127], v[84:87]
	s_setprio 0
	v_add_u32_e32 v153, s83, v213
	s_barrier
	ds_read_b128 v[88:91], v153
	ds_read_b128 v[92:95], v153 offset:1024
	ds_read_b128 v[112:115], v153 offset:2048
	ds_read_b128 v[116:119], v153 offset:3072
	s_add_u32 s28, s64, 0x80100
	s_addc_u32 s29, s65, 0
	s_mov_b32 m0, s72
	v_lshl_add_u64 v[190:191], s[28:29], 0, v[140:141]
	ds_read_b128 v[120:123], v216 offset:32768
	ds_read_b128 v[124:127], v216 offset:33792
	ds_read_b128 v[166:169], v216 offset:34816
	ds_read_b128 v[170:173], v216 offset:35840
	ds_read_b128 v[174:177], v216 offset:36864
	ds_read_b128 v[178:181], v216 offset:37888
	ds_read_b128 v[182:185], v216 offset:38912
	ds_read_b128 v[186:189], v216 offset:39936
	global_load_lds_dwordx4 v[190:191], off
	v_lshl_add_u64 v[190:191], s[28:29], 0, v[144:145]
	s_mov_b32 m0, s73
	s_nop 0
	global_load_lds_dwordx4 v[190:191], off
	s_waitcnt lgkmcnt(8)
	s_barrier
	s_waitcnt lgkmcnt(0)
	s_setprio 1
	s_waitcnt lgkmcnt(0)
	v_mfma_f32_16x16x32_bf16 v[48:51], v[88:91], v[120:123], v[48:51]
	v_mfma_f32_16x16x32_bf16 v[52:55], v[112:115], v[120:123], v[52:55]
	v_mfma_f32_16x16x32_bf16 v[56:59], v[88:91], v[166:169], v[56:59]
	v_mfma_f32_16x16x32_bf16 v[60:63], v[112:115], v[166:169], v[60:63]
	v_mfma_f32_16x16x32_bf16 v[64:67], v[88:91], v[174:177], v[64:67]
	v_mfma_f32_16x16x32_bf16 v[68:71], v[112:115], v[174:177], v[68:71]
	v_mfma_f32_16x16x32_bf16 v[72:75], v[88:91], v[182:185], v[72:75]
	v_mfma_f32_16x16x32_bf16 v[76:79], v[112:115], v[182:185], v[76:79]
	v_mfma_f32_16x16x32_bf16 v[48:51], v[92:95], v[124:127], v[48:51]
	v_mfma_f32_16x16x32_bf16 v[52:55], v[116:119], v[124:127], v[52:55]
	v_mfma_f32_16x16x32_bf16 v[56:59], v[92:95], v[170:173], v[56:59]
	v_mfma_f32_16x16x32_bf16 v[60:63], v[116:119], v[170:173], v[60:63]
	v_mfma_f32_16x16x32_bf16 v[64:67], v[92:95], v[178:181], v[64:67]
	v_mfma_f32_16x16x32_bf16 v[68:71], v[116:119], v[178:181], v[68:71]
	v_mfma_f32_16x16x32_bf16 v[72:75], v[92:95], v[186:189], v[72:75]
	v_mfma_f32_16x16x32_bf16 v[76:79], v[116:119], v[186:189], v[76:79]
	s_setprio 0
	s_barrier
	s_add_i32 s97, s83, s70
	v_add_u32_e32 v223, s84, v213
	v_lshl_add_u64 v[198:199], v[198:199], 0, s[48:49]
	s_mov_b32 m0, s97
	s_add_i32 s28, s97, 0x2000
	ds_read_b128 v[190:193], v223
	ds_read_b128 v[194:197], v223 offset:1024
	ds_read_b128 v[202:205], v223 offset:2048
	ds_read_b128 v[206:209], v223 offset:3072
	global_load_lds_dwordx4 v[198:199], off
	v_lshl_add_u64 v[198:199], v[210:211], 0, s[48:49]
	s_mov_b32 m0, s28
	s_nop 0
	global_load_lds_dwordx4 v[198:199], off
	s_barrier
	s_waitcnt lgkmcnt(0)
	s_setprio 1
	s_waitcnt lgkmcnt(0)
	v_mfma_f32_16x16x32_bf16 v[96:99], v[190:193], v[120:123], v[96:99]
	v_mfma_f32_16x16x32_bf16 v[16:19], v[202:205], v[120:123], v[16:19]
	v_mfma_f32_16x16x32_bf16 v[20:23], v[190:193], v[166:169], v[20:23]
	v_mfma_f32_16x16x32_bf16 v[24:27], v[202:205], v[166:169], v[24:27]
	v_mfma_f32_16x16x32_bf16 v[28:31], v[190:193], v[174:177], v[28:31]
	v_mfma_f32_16x16x32_bf16 v[32:35], v[202:205], v[174:177], v[32:35]
	v_mfma_f32_16x16x32_bf16 v[36:39], v[190:193], v[182:185], v[36:39]
	v_mfma_f32_16x16x32_bf16 v[40:43], v[202:205], v[182:185], v[40:43]
	v_mfma_f32_16x16x32_bf16 v[96:99], v[194:197], v[124:127], v[96:99]
	v_mfma_f32_16x16x32_bf16 v[16:19], v[206:209], v[124:127], v[16:19]
	v_mfma_f32_16x16x32_bf16 v[20:23], v[194:197], v[170:173], v[20:23]
	v_mfma_f32_16x16x32_bf16 v[24:27], v[206:209], v[170:173], v[24:27]
	v_mfma_f32_16x16x32_bf16 v[28:31], v[194:197], v[178:181], v[28:31]
	v_mfma_f32_16x16x32_bf16 v[32:35], v[206:209], v[178:181], v[32:35]
	v_mfma_f32_16x16x32_bf16 v[36:39], v[194:197], v[186:189], v[36:39]
	v_mfma_f32_16x16x32_bf16 v[40:43], v[206:209], v[186:189], v[40:43]
	s_setprio 0
	s_mov_b32 m0, s74
	v_lshl_add_u64 v[198:199], v[224:225], 0, s[48:49]
	s_barrier
	ds_read_b128 v[120:123], v216 offset:49152
	ds_read_b128 v[124:127], v216 offset:50176
	ds_read_b128 v[166:169], v216 offset:51200
	ds_read_b128 v[170:173], v216 offset:52224
	ds_read_b128 v[174:177], v216 offset:53248
	ds_read_b128 v[178:181], v216 offset:54272
	ds_read_b128 v[182:185], v216 offset:55296
	ds_read_b128 v[186:189], v216 offset:56320
	global_load_lds_dwordx4 v[198:199], off
	v_lshl_add_u64 v[198:199], v[226:227], 0, s[48:49]
	s_mov_b32 m0, s75
	s_nop 0
	global_load_lds_dwordx4 v[198:199], off
	s_barrier
; #define PG8_STAGE(bufoff, gbase, voff) do { _Pragma("unroll") for (int _i = 0; _i < 2; ++_i) \
;         __builtin_amdgcn_global_load_lds((const unsigned*)((const char*)(gbase) + (voff)[_i]), (LAS unsigned*)(lds + (bufoff) + ldsw + _i * 8192), 16, 0, 0); } while (0)
; #define PG8_LDA(dst, b, h) do { _Pragma("unroll") for (int m = 0; m < 4; ++m) _Pragma("unroll") for (int k = 0; k < 2; ++k) dst[m][k] = *(const LAS bf16x8*)(lds + PG8_SA(b, h) + aoff + m * 2048 + k * 1024); } while (0)
; #define PG8_LDB(dst, b, h) do { _Pragma("unroll") for (int n = 0; n < 2; ++n) _Pragma("unroll") for (int k = 0; k < 2; ++k) dst[n][k] = *(const LAS bf16x8*)(lds + PG8_SB(b, h) + boff + n * 2048 + k * 1024); } while (0)
; #define PG8_WAIT_V(n) asm volatile("s_waitcnt vmcnt(" #n ")" ::: "memory")
; #define PG8_WAIT_L(n) asm volatile("s_waitcnt lgkmcnt(" #n ")" ::: "memory")
; #define PG8_BAR __builtin_amdgcn_s_barrier()
; #define PG8_SCHED __builtin_amdgcn_sched_barrier(0)
; template <class Epi>
; __device__ __forceinline__ void gemm_phase(LAS unsigned char* lds, const bf16_t* A, int lda, const bf16_t* Bt, int ldb, int M, int N, int K, int asel, const Epi& E, const int fixed_round = -1) {
;     ...
;             PG8_WAIT_V(6); PG8_BAR; PG8_MMA(1, 1, At, B1); PG8_BAR;
;             PG8_LDB(B0, 1, 0); PG8_SCHED; PG8_LDA(At, 1, 0); PG8_STAGE(PG8_SA(0, 1), a2 + hstepA, voffA);
;             PG8_WAIT_L(8); PG8_BAR; PG8_WAIT_L(0); PG8_MMA(0, 0, At, B0); PG8_BAR; PG8_SCHED;
;             PG8_LDB(B1, 1, 1); PG8_STAGE(PG8_SB(1, 0), b3, voffB);
;             PG8_BAR; PG8_WAIT_L(0); PG8_MMA(0, 1, At, B1); PG8_BAR;
;             PG8_LDA(At, 1, 1); PG8_STAGE(PG8_SA(1, 0), a3, voffA);
;             PG8_BAR; PG8_WAIT_L(0); PG8_MMA(1, 0, At, B0); PG8_BAR; PG8_SCHED;
;             PG8_STAGE(PG8_SB(1, 1), b3 + hstepB, voffB);
;             PG8_WAIT_V(6); PG8_BAR; PG8_MMA(1, 1, At, B1); PG8_BAR;
	s_waitcnt lgkmcnt(0)
	s_setprio 1
	s_waitcnt lgkmcnt(0)
	v_mfma_f32_16x16x32_bf16 v[128:131], v[88:91], v[120:123], v[128:131]
	v_mfma_f32_16x16x32_bf16 v[132:135], v[112:115], v[120:123], v[132:135]
	v_mfma_f32_16x16x32_bf16 v[136:139], v[88:91], v[166:169], v[136:139]
	v_mfma_f32_16x16x32_bf16 v[154:157], v[112:115], v[166:169], v[154:157]
	v_mfma_f32_16x16x32_bf16 v[158:161], v[88:91], v[174:177], v[158:161]
	v_mfma_f32_16x16x32_bf16 v[162:165], v[112:115], v[174:177], v[162:165]
	v_mfma_f32_16x16x32_bf16 v[0:3], v[88:91], v[182:185], v[0:3]
	v_mfma_f32_16x16x32_bf16 v[4:7], v[112:115], v[182:185], v[4:7]
	v_mfma_f32_16x16x32_bf16 v[128:131], v[92:95], v[124:127], v[128:131]
	v_mfma_f32_16x16x32_bf16 v[132:135], v[116:119], v[124:127], v[132:135]
	v_mfma_f32_16x16x32_bf16 v[136:139], v[92:95], v[170:173], v[136:139]
	v_mfma_f32_16x16x32_bf16 v[154:157], v[116:119], v[170:173], v[154:157]
	v_mfma_f32_16x16x32_bf16 v[158:161], v[92:95], v[178:181], v[158:161]
	v_mfma_f32_16x16x32_bf16 v[162:165], v[116:119], v[178:181], v[162:165]
	v_mfma_f32_16x16x32_bf16 v[0:3], v[92:95], v[186:189], v[0:3]
	v_mfma_f32_16x16x32_bf16 v[4:7], v[116:119], v[186:189], v[4:7]
	s_setprio 0
	s_barrier
	s_add_u32 s66, s66, 0x10180
	s_addc_u32 s67, s67, 0
	s_add_i32 s29, s84, s70
	v_lshl_add_u64 v[88:89], s[66:67], 0, v[142:143]
	s_mov_b32 m0, s29
	s_nop 0
	global_load_lds_dwordx4 v[88:89], off
	v_lshl_add_u64 v[88:89], s[66:67], 0, v[146:147]
	s_add_i32 s66, s29, 0x2000
	s_mov_b32 m0, s66
	s_nop 0
	global_load_lds_dwordx4 v[88:89], off
	s_waitcnt vmcnt(6)
	s_barrier
	s_setprio 1
	v_mfma_f32_16x16x32_bf16 v[8:11], v[190:193], v[120:123], v[8:11]
	v_mfma_f32_16x16x32_bf16 v[12:15], v[202:205], v[120:123], v[12:15]
	v_mfma_f32_16x16x32_bf16 v[44:47], v[190:193], v[166:169], v[44:47]
	v_mfma_f32_16x16x32_bf16 v[88:91], v[202:205], v[166:169], v[100:103]
	v_mfma_f32_16x16x32_bf16 v[92:95], v[190:193], v[174:177], v[104:107]
	v_mfma_f32_16x16x32_bf16 v[100:103], v[202:205], v[174:177], v[108:111]
	v_mfma_f32_16x16x32_bf16 v[80:83], v[190:193], v[182:185], v[80:83]
	v_mfma_f32_16x16x32_bf16 v[84:87], v[202:205], v[182:185], v[84:87]
	v_mfma_f32_16x16x32_bf16 v[8:11], v[194:197], v[124:127], v[8:11]
	v_mfma_f32_16x16x32_bf16 v[12:15], v[206:209], v[124:127], v[12:15]
	v_mfma_f32_16x16x32_bf16 v[44:47], v[194:197], v[170:173], v[44:47]
	v_mfma_f32_16x16x32_bf16 v[88:91], v[206:209], v[170:173], v[88:91]
	v_mfma_f32_16x16x32_bf16 v[92:95], v[194:197], v[178:181], v[92:95]
	v_mfma_f32_16x16x32_bf16 v[100:103], v[206:209], v[178:181], v[100:103]
	v_mfma_f32_16x16x32_bf16 v[80:83], v[194:197], v[186:189], v[80:83]
	v_mfma_f32_16x16x32_bf16 v[84:87], v[206:209], v[186:189], v[84:87]
	s_setprio 0
	s_barrier
	ds_read_b128 v[104:107], v215
	ds_read_b128 v[108:111], v215 offset:1024
	ds_read_b128 v[112:115], v215 offset:2048
	ds_read_b128 v[116:119], v215 offset:3072
	s_add_u32 s64, s64, 0x80180
	s_addc_u32 s65, s65, 0
	s_mov_b32 m0, vcc_hi
	v_lshl_add_u64 v[190:191], s[64:65], 0, v[140:141]
	ds_read_b128 v[120:123], v216
	ds_read_b128 v[124:127], v216 offset:1024
	ds_read_b128 v[166:169], v216 offset:2048
	ds_read_b128 v[170:173], v216 offset:3072
	ds_read_b128 v[174:177], v216 offset:4096
	ds_read_b128 v[178:181], v216 offset:5120
	ds_read_b128 v[182:185], v216 offset:6144
	ds_read_b128 v[186:189], v216 offset:7168
	global_load_lds_dwordx4 v[190:191], off
	v_lshl_add_u64 v[190:191], s[64:65], 0, v[144:145]
	s_mov_b32 m0, s55
	s_nop 0
	global_load_lds_dwordx4 v[190:191], off
	s_waitcnt lgkmcnt(8)
	s_barrier
	s_waitcnt lgkmcnt(0)
	s_setprio 1
	s_waitcnt lgkmcnt(0)
	v_mfma_f32_16x16x32_bf16 v[56:59], v[104:107], v[166:169], v[56:59]
	v_mfma_f32_16x16x32_bf16 v[190:193], v[108:111], v[170:173], v[56:59]
	v_mfma_f32_16x16x32_bf16 v[56:59], v[112:115], v[166:169], v[60:63]
	v_mfma_f32_16x16x32_bf16 v[60:63], v[116:119], v[170:173], v[56:59]
	v_mfma_f32_16x16x32_bf16 v[56:59], v[104:107], v[174:177], v[64:67]
	v_mfma_f32_16x16x32_bf16 v[64:67], v[108:111], v[178:181], v[56:59]
	v_mfma_f32_16x16x32_bf16 v[56:59], v[112:115], v[174:177], v[68:71]
	v_mfma_f32_16x16x32_bf16 v[68:71], v[116:119], v[178:181], v[56:59]
	v_mfma_f32_16x16x32_bf16 v[56:59], v[104:107], v[182:185], v[72:75]
	v_mfma_f32_16x16x32_bf16 v[48:51], v[104:107], v[120:123], v[48:51]
	v_mfma_f32_16x16x32_bf16 v[52:55], v[112:115], v[120:123], v[52:55]
	v_mfma_f32_16x16x32_bf16 v[72:75], v[108:111], v[186:189], v[56:59]
	v_mfma_f32_16x16x32_bf16 v[56:59], v[112:115], v[182:185], v[76:79]
	v_mfma_f32_16x16x32_bf16 v[48:51], v[108:111], v[124:127], v[48:51]
	v_mfma_f32_16x16x32_bf16 v[52:55], v[116:119], v[124:127], v[52:55]
	v_mfma_f32_16x16x32_bf16 v[76:79], v[116:119], v[186:189], v[56:59]
	s_setprio 0
	s_barrier
	s_mov_b32 m0, s96
	v_lshl_add_u64 v[198:199], s[0:1], 0, v[142:143]
	s_nop 0
	ds_read_b128 v[56:59], v217
	ds_read_b128 v[194:197], v217 offset:1024
	ds_read_b128 v[202:205], v217 offset:2048
	ds_read_b128 v[206:209], v217 offset:3072
	global_load_lds_dwordx4 v[198:199], off
	v_lshl_add_u64 v[210:211], s[0:1], 0, v[146:147]
	s_mov_b32 m0, s57
	s_nop 0
	global_load_lds_dwordx4 v[210:211], off
	s_barrier
; #define PG8_STAGE(bufoff, gbase, voff) do { _Pragma("unroll") for (int _i = 0; _i < 2; ++_i) \
;         __builtin_amdgcn_global_load_lds((const unsigned*)((const char*)(gbase) + (voff)[_i]), (LAS unsigned*)(lds + (bufoff) + ldsw + _i * 8192), 16, 0, 0); } while (0)
; #define PG8_LDA(dst, b, h) do { _Pragma("unroll") for (int m = 0; m < 4; ++m) _Pragma("unroll") for (int k = 0; k < 2; ++k) dst[m][k] = *(const LAS bf16x8*)(lds + PG8_SA(b, h) + aoff + m * 2048 + k * 1024); } while (0)
; #define PG8_LDB(dst, b, h) do { _Pragma("unroll") for (int n = 0; n < 2; ++n) _Pragma("unroll") for (int k = 0; k < 2; ++k) dst[n][k] = *(const LAS bf16x8*)(lds + PG8_SB(b, h) + boff + n * 2048 + k * 1024); } while (0)
; #define PG8_WAIT_V(n) asm volatile("s_waitcnt vmcnt(" #n ")" ::: "memory")
; #define PG8_WAIT_L(n) asm volatile("s_waitcnt lgkmcnt(" #n ")" ::: "memory")
; #define PG8_BAR __builtin_amdgcn_s_barrier()
; #define PG8_SCHED __builtin_amdgcn_sched_barrier(0)
; template <class Epi>
; __device__ __forceinline__ void gemm_phase(LAS unsigned char* lds, const bf16_t* A, int lda, const bf16_t* Bt, int ldb, int M, int N, int K, int asel, const Epi& E, const int fixed_round = -1) {
;     ...
;             PG8_LDB(B0, 0, 0); PG8_SCHED; PG8_LDA(At, 0, 0); PG8_STAGE(PG8_SA(1, 1), a1 + hstepA, voffA);
;             PG8_WAIT_L(8); PG8_BAR; PG8_WAIT_L(0); PG8_MMA(0, 0, At, B0); PG8_BAR; PG8_SCHED;
;             PG8_LDB(B1, 0, 1); PG8_STAGE(PG8_SB(0, 0), b2, voffB);
;             PG8_BAR; PG8_WAIT_L(0); PG8_MMA(0, 1, At, B1); PG8_BAR;
;             PG8_LDA(At, 0, 1); PG8_STAGE(PG8_SA(0, 0), a2, voffA);
;             PG8_BAR; PG8_WAIT_L(0); PG8_MMA(1, 0, At, B0); PG8_BAR; PG8_SCHED;
;             PG8_STAGE(PG8_SB(0, 1), b2 + hstepB, voffB);
;             PG8_WAIT_V(6); PG8_BAR; PG8_MMA(1, 1, At, B1); PG8_BAR;
;             PG8_LDB(B0, 1, 0); PG8_SCHED; PG8_LDA(At, 1, 0); PG8_STAGE(PG8_SA(0, 1), a2 + hstepA, voffA);
;             PG8_WAIT_L(8); PG8_BAR; PG8_WAIT_L(0); PG8_MMA(0, 0, At, B0); PG8_BAR; PG8_SCHED;
;             PG8_LDB(B1, 1, 1); PG8_STAGE(PG8_SB(1, 0), b3, voffB);
;             PG8_BAR; PG8_WAIT_L(0); PG8_MMA(0, 1, At, B1); PG8_BAR;
	s_waitcnt lgkmcnt(0)
	s_setprio 1
	s_waitcnt lgkmcnt(0)
	v_mfma_f32_16x16x32_bf16 v[32:35], v[202:205], v[174:177], v[32:35]
	v_mfma_f32_16x16x32_bf16 v[20:23], v[56:59], v[166:169], v[20:23]
	v_mfma_f32_16x16x32_bf16 v[24:27], v[202:205], v[166:169], v[24:27]
	v_mfma_f32_16x16x32_bf16 v[166:169], v[206:209], v[178:181], v[32:35]
	v_mfma_f32_16x16x32_bf16 v[32:35], v[56:59], v[182:185], v[36:39]
	v_mfma_f32_16x16x32_bf16 v[96:99], v[56:59], v[120:123], v[96:99]
	v_mfma_f32_16x16x32_bf16 v[16:19], v[202:205], v[120:123], v[16:19]
	v_mfma_f32_16x16x32_bf16 v[28:31], v[56:59], v[174:177], v[28:31]
	v_mfma_f32_16x16x32_bf16 v[36:39], v[194:197], v[186:189], v[32:35]
	v_mfma_f32_16x16x32_bf16 v[32:35], v[202:205], v[182:185], v[40:43]
	v_mfma_f32_16x16x32_bf16 v[96:99], v[194:197], v[124:127], v[96:99]
	v_mfma_f32_16x16x32_bf16 v[16:19], v[206:209], v[124:127], v[16:19]
	v_mfma_f32_16x16x32_bf16 v[20:23], v[194:197], v[170:173], v[20:23]
	v_mfma_f32_16x16x32_bf16 v[24:27], v[206:209], v[170:173], v[24:27]
	v_mfma_f32_16x16x32_bf16 v[28:31], v[194:197], v[178:181], v[28:31]
	v_mfma_f32_16x16x32_bf16 v[170:173], v[206:209], v[186:189], v[32:35]
	s_setprio 0
	s_mov_b32 m0, s63
	v_lshl_add_u64 v[252:253], s[2:3], 0, v[140:141]
	s_barrier
	ds_read_b128 v[32:35], v216 offset:16384
	ds_read_b128 v[40:43], v216 offset:17408
	ds_read_b128 v[120:123], v216 offset:18432
	ds_read_b128 v[124:127], v216 offset:19456
	ds_read_b128 v[174:177], v216 offset:20480
	ds_read_b128 v[178:181], v216 offset:21504
	ds_read_b128 v[182:185], v216 offset:22528
	ds_read_b128 v[186:189], v216 offset:23552
	global_load_lds_dwordx4 v[252:253], off
	v_lshl_add_u64 v[148:149], s[2:3], 0, v[144:145]
	s_mov_b32 m0, s71
	s_nop 0
	global_load_lds_dwordx4 v[148:149], off
	s_barrier
	s_waitcnt lgkmcnt(0)
	s_setprio 1
	s_waitcnt lgkmcnt(0)
	v_mfma_f32_16x16x32_bf16 v[128:131], v[104:107], v[32:35], v[128:131]
	v_mfma_f32_16x16x32_bf16 v[224:227], v[108:111], v[40:43], v[128:131]
	v_mfma_f32_16x16x32_bf16 v[128:131], v[112:115], v[32:35], v[132:135]
	v_mfma_f32_16x16x32_bf16 v[228:231], v[116:119], v[40:43], v[128:131]
	v_mfma_f32_16x16x32_bf16 v[128:131], v[104:107], v[120:123], v[136:139]
	v_mfma_f32_16x16x32_bf16 v[136:139], v[108:111], v[124:127], v[128:131]
	v_mfma_f32_16x16x32_bf16 v[128:131], v[112:115], v[120:123], v[154:157]
	v_mfma_f32_16x16x32_bf16 v[154:157], v[116:119], v[124:127], v[128:131]
	v_mfma_f32_16x16x32_bf16 v[128:131], v[104:107], v[174:177], v[158:161]
	v_mfma_f32_16x16x32_bf16 v[158:161], v[108:111], v[178:181], v[128:131]
	v_mfma_f32_16x16x32_bf16 v[128:131], v[112:115], v[174:177], v[162:165]
	v_mfma_f32_16x16x32_bf16 v[0:3], v[104:107], v[182:185], v[0:3]
	v_mfma_f32_16x16x32_bf16 v[4:7], v[112:115], v[182:185], v[4:7]
	v_mfma_f32_16x16x32_bf16 v[162:165], v[116:119], v[178:181], v[128:131]
	v_mfma_f32_16x16x32_bf16 v[0:3], v[108:111], v[186:189], v[0:3]
	v_mfma_f32_16x16x32_bf16 v[4:7], v[116:119], v[186:189], v[4:7]
	s_setprio 0
	s_barrier
	s_add_u32 s64, s0, 0x10000
	s_addc_u32 s65, s1, 0
	s_mov_b32 m0, vcc_lo
	v_lshl_add_u64 v[104:105], s[64:65], 0, v[142:143]
	global_load_lds_dwordx4 v[104:105], off
	v_lshl_add_u64 v[104:105], s[64:65], 0, v[146:147]
	s_mov_b32 m0, s95
	s_nop 0
	global_load_lds_dwordx4 v[104:105], off
	s_waitcnt vmcnt(6)
	s_barrier
	s_setprio 1
	v_mfma_f32_16x16x32_bf16 v[8:11], v[56:59], v[32:35], v[8:11]
	v_mfma_f32_16x16x32_bf16 v[232:235], v[194:197], v[40:43], v[8:11]
	v_mfma_f32_16x16x32_bf16 v[8:11], v[202:205], v[32:35], v[12:15]
	v_mfma_f32_16x16x32_bf16 v[12:15], v[206:209], v[40:43], v[8:11]
	v_mfma_f32_16x16x32_bf16 v[8:11], v[56:59], v[120:123], v[44:47]
	v_mfma_f32_16x16x32_bf16 v[236:239], v[194:197], v[124:127], v[8:11]
	v_mfma_f32_16x16x32_bf16 v[8:11], v[202:205], v[120:123], v[88:91]
	v_mfma_f32_16x16x32_bf16 v[240:243], v[206:209], v[124:127], v[8:11]
	v_mfma_f32_16x16x32_bf16 v[8:11], v[56:59], v[174:177], v[92:95]
	v_mfma_f32_16x16x32_bf16 v[244:247], v[194:197], v[178:181], v[8:11]
	v_mfma_f32_16x16x32_bf16 v[8:11], v[202:205], v[174:177], v[100:103]
	v_mfma_f32_16x16x32_bf16 v[174:177], v[206:209], v[178:181], v[8:11]
	v_mfma_f32_16x16x32_bf16 v[8:11], v[56:59], v[182:185], v[80:83]
	v_mfma_f32_16x16x32_bf16 v[178:181], v[194:197], v[186:189], v[8:11]
	v_mfma_f32_16x16x32_bf16 v[8:11], v[202:205], v[182:185], v[84:87]
	v_mfma_f32_16x16x32_bf16 v[182:185], v[206:209], v[186:189], v[8:11]
	s_setprio 0
	s_barrier
	ds_read_b128 v[84:87], v153
	ds_read_b128 v[92:95], v153 offset:1024
	ds_read_b128 v[100:103], v153 offset:2048
	ds_read_b128 v[186:189], v153 offset:3072
	s_add_u32 s2, s2, 0x80000
	s_addc_u32 s3, s3, 0
	s_mov_b32 m0, s72
	v_lshl_add_u64 v[32:33], s[2:3], 0, v[140:141]
	ds_read_b128 v[8:11], v216 offset:32768
	ds_read_b128 v[44:47], v216 offset:33792
	ds_read_b128 v[80:83], v216 offset:34816
	ds_read_b128 v[88:91], v216 offset:35840
	ds_read_b128 v[108:111], v216 offset:36864
	ds_read_b128 v[194:197], v216 offset:37888
	ds_read_b128 v[202:205], v216 offset:38912
	ds_read_b128 v[206:209], v216 offset:39936
	global_load_lds_dwordx4 v[32:33], off
	v_lshl_add_u64 v[32:33], s[2:3], 0, v[144:145]
	s_mov_b32 m0, s73
	s_nop 0
	global_load_lds_dwordx4 v[32:33], off
	s_waitcnt lgkmcnt(8)
	s_barrier
; #define PG8_STAGE(bufoff, gbase, voff) do { _Pragma("unroll") for (int _i = 0; _i < 2; ++_i) \
;         __builtin_amdgcn_global_load_lds((const unsigned*)((const char*)(gbase) + (voff)[_i]), (LAS unsigned*)(lds + (bufoff) + ldsw + _i * 8192), 16, 0, 0); } while (0)
; #define PG8_LDA(dst, b, h) do { _Pragma("unroll") for (int m = 0; m < 4; ++m) _Pragma("unroll") for (int k = 0; k < 2; ++k) dst[m][k] = *(const LAS bf16x8*)(lds + PG8_SA(b, h) + aoff + m * 2048 + k * 1024); } while (0)
; #define PG8_LDB(dst, b, h) do { _Pragma("unroll") for (int n = 0; n < 2; ++n) _Pragma("unroll") for (int k = 0; k < 2; ++k) dst[n][k] = *(const LAS bf16x8*)(lds + PG8_SB(b, h) + boff + n * 2048 + k * 1024); } while (0)
; #define PG8_WAIT_V(n) asm volatile("s_waitcnt vmcnt(" #n ")" ::: "memory")
; #define PG8_WAIT_L(n) asm volatile("s_waitcnt lgkmcnt(" #n ")" ::: "memory")
; #define PG8_BAR __builtin_amdgcn_s_barrier()
; #define PG8_SCHED __builtin_amdgcn_sched_barrier(0)
; template <class Epi>
; __device__ __forceinline__ void gemm_phase(LAS unsigned char* lds, const bf16_t* A, int lda, const bf16_t* Bt, int ldb, int M, int N, int K, int asel, const Epi& E, const int fixed_round = -1) {
;     ...
;             PG8_WAIT_V(6); PG8_BAR; PG8_MMA(1, 1, At, B1); PG8_BAR;
;             PG8_LDB(B0, 1, 0); PG8_SCHED; PG8_LDA(At, 1, 0); PG8_STAGE(PG8_SA(0, 1), a2 + hstepA, voffA);
;             PG8_WAIT_L(8); PG8_BAR; PG8_WAIT_L(0); PG8_MMA(0, 0, At, B0); PG8_BAR; PG8_SCHED;
;             PG8_LDB(B1, 1, 1); PG8_STAGE(PG8_SB(1, 0), b3, voffB);
;             PG8_BAR; PG8_WAIT_L(0); PG8_MMA(0, 1, At, B1); PG8_BAR;
;             PG8_LDA(At, 1, 1); PG8_STAGE(PG8_SA(1, 0), a3, voffA);
;             PG8_BAR; PG8_WAIT_L(0); PG8_MMA(1, 0, At, B0); PG8_BAR; PG8_SCHED;
;             PG8_STAGE(PG8_SB(1, 1), b3 + hstepB, voffB);
;             PG8_WAIT_V(6); PG8_BAR; PG8_MMA(1, 1, At, B1); PG8_BAR;
	s_waitcnt lgkmcnt(0)
	s_setprio 1
	s_waitcnt lgkmcnt(0)
	v_mfma_f32_16x16x32_bf16 v[32:35], v[84:87], v[8:11], v[48:51]
	v_mfma_f32_16x16x32_bf16 v[128:131], v[92:95], v[44:47], v[32:35]
	v_mfma_f32_16x16x32_bf16 v[32:35], v[100:103], v[8:11], v[52:55]
	v_mfma_f32_16x16x32_bf16 v[56:59], v[186:189], v[44:47], v[32:35]
	v_mfma_f32_16x16x32_bf16 v[32:35], v[84:87], v[80:83], v[190:193]
	v_mfma_f32_16x16x32_bf16 v[120:123], v[92:95], v[88:91], v[32:35]
	v_mfma_f32_16x16x32_bf16 v[32:35], v[100:103], v[80:83], v[60:63]
	v_mfma_f32_16x16x32_bf16 v[48:51], v[186:189], v[88:91], v[32:35]
	v_mfma_f32_16x16x32_bf16 v[32:35], v[84:87], v[108:111], v[64:67]
	v_mfma_f32_16x16x32_bf16 v[112:115], v[92:95], v[194:197], v[32:35]
	v_mfma_f32_16x16x32_bf16 v[32:35], v[100:103], v[108:111], v[68:71]
	v_mfma_f32_16x16x32_bf16 v[40:43], v[186:189], v[194:197], v[32:35]
	v_mfma_f32_16x16x32_bf16 v[32:35], v[84:87], v[202:205], v[72:75]
	v_mfma_f32_16x16x32_bf16 v[104:107], v[92:95], v[206:209], v[32:35]
	v_mfma_f32_16x16x32_bf16 v[32:35], v[100:103], v[202:205], v[76:79]
	v_mfma_f32_16x16x32_bf16 v[32:35], v[186:189], v[206:209], v[32:35]
	s_setprio 0
	s_barrier
	s_mov_b32 m0, s97
	v_lshl_add_u64 v[52:53], v[198:199], 0, s[44:45]
	ds_read_b128 v[68:71], v223
	ds_read_b128 v[72:75], v223 offset:1024
	ds_read_b128 v[76:79], v223 offset:2048
	ds_read_b128 v[190:193], v223 offset:3072
	global_load_lds_dwordx4 v[52:53], off
	v_lshl_add_u64 v[52:53], v[210:211], 0, s[44:45]
	s_mov_b32 m0, s28
	s_nop 0
	global_load_lds_dwordx4 v[52:53], off
	s_barrier
	s_waitcnt lgkmcnt(0)
	s_setprio 1
	s_waitcnt lgkmcnt(0)
	v_mfma_f32_16x16x32_bf16 v[52:55], v[68:71], v[8:11], v[96:99]
	v_mfma_f32_16x16x32_bf16 v[8:11], v[76:79], v[8:11], v[16:19]
	v_mfma_f32_16x16x32_bf16 v[60:63], v[190:193], v[44:47], v[8:11]
	v_mfma_f32_16x16x32_bf16 v[8:11], v[68:71], v[80:83], v[20:23]
	v_mfma_f32_16x16x32_bf16 v[124:127], v[72:75], v[88:91], v[8:11]
	v_mfma_f32_16x16x32_bf16 v[8:11], v[76:79], v[80:83], v[24:27]
	v_mfma_f32_16x16x32_bf16 v[132:135], v[72:75], v[44:47], v[52:55]
	v_mfma_f32_16x16x32_bf16 v[52:55], v[190:193], v[88:91], v[8:11]
	v_mfma_f32_16x16x32_bf16 v[8:11], v[68:71], v[108:111], v[28:31]
	v_mfma_f32_16x16x32_bf16 v[116:119], v[72:75], v[194:197], v[8:11]
	v_mfma_f32_16x16x32_bf16 v[8:11], v[76:79], v[108:111], v[166:169]
	v_mfma_f32_16x16x32_bf16 v[44:47], v[190:193], v[194:197], v[8:11]
	v_mfma_f32_16x16x32_bf16 v[8:11], v[68:71], v[202:205], v[36:39]
	v_mfma_f32_16x16x32_bf16 v[108:111], v[72:75], v[206:209], v[8:11]
	v_mfma_f32_16x16x32_bf16 v[8:11], v[76:79], v[202:205], v[170:173]
	v_mfma_f32_16x16x32_bf16 v[36:39], v[190:193], v[206:209], v[8:11]
	s_setprio 0
	s_mov_b32 m0, s74
	s_nop 4
	v_lshl_add_u64 v[8:9], v[252:253], 0, s[44:45]
	s_barrier
	ds_read_b128 v[20:23], v216 offset:49152
	ds_read_b128 v[28:31], v216 offset:50176
	ds_read_b128 v[166:169], v216 offset:51200
	ds_read_b128 v[170:173], v216 offset:52224
	ds_read_b128 v[194:197], v216 offset:53248
	ds_read_b128 v[202:205], v216 offset:54272
	ds_read_b128 v[206:209], v216 offset:55296
	ds_read_b128 v[248:251], v216 offset:56320
	global_load_lds_dwordx4 v[8:9], off
	v_lshl_add_u64 v[8:9], v[148:149], 0, s[44:45]
	s_mov_b32 m0, s75
	s_nop 0
	global_load_lds_dwordx4 v[8:9], off
	s_barrier
	s_waitcnt lgkmcnt(0)
	s_setprio 1
	s_waitcnt lgkmcnt(0)
	v_mfma_f32_16x16x32_bf16 v[8:11], v[84:87], v[20:23], v[224:227]
	v_mfma_f32_16x16x32_bf16 v[96:99], v[92:95], v[28:31], v[8:11]
	v_mfma_f32_16x16x32_bf16 v[8:11], v[100:103], v[20:23], v[228:231]
	v_mfma_f32_16x16x32_bf16 v[24:27], v[186:189], v[28:31], v[8:11]
	v_mfma_f32_16x16x32_bf16 v[8:11], v[84:87], v[166:169], v[136:139]
	v_mfma_f32_16x16x32_bf16 v[88:91], v[92:95], v[170:173], v[8:11]
	v_mfma_f32_16x16x32_bf16 v[8:11], v[100:103], v[166:169], v[154:157]
	v_mfma_f32_16x16x32_bf16 v[16:19], v[186:189], v[170:173], v[8:11]
	v_mfma_f32_16x16x32_bf16 v[8:11], v[84:87], v[194:197], v[158:161]
	v_mfma_f32_16x16x32_bf16 v[0:3], v[84:87], v[206:209], v[0:3]
	v_mfma_f32_16x16x32_bf16 v[80:83], v[92:95], v[202:205], v[8:11]
	v_mfma_f32_16x16x32_bf16 v[8:11], v[100:103], v[194:197], v[162:165]
	v_mfma_f32_16x16x32_bf16 v[64:67], v[92:95], v[248:251], v[0:3]
	v_mfma_f32_16x16x32_bf16 v[0:3], v[100:103], v[206:209], v[4:7]
	v_mfma_f32_16x16x32_bf16 v[8:11], v[186:189], v[202:205], v[8:11]
	v_mfma_f32_16x16x32_bf16 v[0:3], v[186:189], v[248:251], v[0:3]
	s_setprio 0
	s_barrier
	s_add_u32 s0, s0, 0x10080
	s_addc_u32 s1, s1, 0
	s_mov_b32 m0, s29
	v_lshl_add_u64 v[4:5], s[0:1], 0, v[142:143]
	global_load_lds_dwordx4 v[4:5], off
	v_lshl_add_u64 v[4:5], s[0:1], 0, v[146:147]
	s_mov_b32 m0, s66
	s_nop 0
	global_load_lds_dwordx4 v[4:5], off
	s_waitcnt vmcnt(6)
	s_barrier
; #define PG8_STAGE(bufoff, gbase, voff) do { _Pragma("unroll") for (int _i = 0; _i < 2; ++_i) \
;         __builtin_amdgcn_global_load_lds((const unsigned*)((const char*)(gbase) + (voff)[_i]), (LAS unsigned*)(lds + (bufoff) + ldsw + _i * 8192), 16, 0, 0); } while (0)
; #define PG8_LDA(dst, b, h) do { _Pragma("unroll") for (int m = 0; m < 4; ++m) _Pragma("unroll") for (int k = 0; k < 2; ++k) dst[m][k] = *(const LAS bf16x8*)(lds + PG8_SA(b, h) + aoff + m * 2048 + k * 1024); } while (0)
; #define PG8_WAIT_V(n) asm volatile("s_waitcnt vmcnt(" #n ")" ::: "memory")
; #define PG8_WAIT_L(n) asm volatile("s_waitcnt lgkmcnt(" #n ")" ::: "memory")
; #define PG8_BAR __builtin_amdgcn_s_barrier()
; template <class Epi>
; __device__ __forceinline__ void gemm_phase(LAS unsigned char* lds, const bf16_t* A, int lda, const bf16_t* Bt, int ldb, int M, int N, int K, int asel, const Epi& E, const int fixed_round = -1) {
;     ...
;             PG8_WAIT_V(6); PG8_BAR; PG8_MMA(1, 1, At, B1); PG8_BAR;
;             PG8_LDB(B0, 1, 0); PG8_SCHED; PG8_LDA(At, 1, 0); PG8_STAGE(PG8_SA(0, 1), a2 + hstepA, voffA);
;             PG8_WAIT_L(8); PG8_BAR; PG8_WAIT_L(0); PG8_MMA(0, 0, At, B0); PG8_BAR; PG8_SCHED;
;             PG8_LDB(B1, 1, 1); PG8_STAGE(PG8_SB(1, 0), b3, voffB);
;             PG8_BAR; PG8_WAIT_L(0); PG8_MMA(0, 1, At, B1); PG8_BAR;
;             PG8_LDA(At, 1, 1); PG8_STAGE(PG8_SA(1, 0), a3, voffA);
;             PG8_BAR; PG8_WAIT_L(0); PG8_MMA(1, 0, At, B0); PG8_BAR; PG8_SCHED;
;             PG8_STAGE(PG8_SB(1, 1), b3 + hstepB, voffB);
;             PG8_WAIT_V(6); PG8_BAR; PG8_MMA(1, 1, At, B1); PG8_BAR;
;     __device__ __forceinline__ void operator()(const AccT& acc, const Unit& u, int wr, int wc, int fr, int fq) const {
;         const int row0 = u.pm * BM + wr * 64 + fr, ch0 = u.pn * HALF + wc * 32 + 4 * fq;
; #pragma unroll
;         for (int n = 0; n < 2; ++n) {
;             u32x2 xw[2][4];
; #pragma unroll
;             for (int ai = 0; ai < 2; ++ai)
; #pragma unroll
;                 for (int m = 0; m < 4; ++m) xw[ai][m] = *(const u32x2*)(XC + (size_t)(row0 + ai * HALF + m * 16) * DM + ch0 + 16 * n);
;             const f32x4 bra = *(const f32x4*)(b_ra + ch0 + 16 * n), bri = *(const f32x4*)(b_ri + ch0 + 16 * n), l = *(const f32x4*)(lam + ch0 + 16 * n);
;             f32x4 sp;
; #pragma unroll
;             for (int j = 0; j < 4; ++j) sp[j] = -8.0f * log1pf(__expf(-l[j]));
	s_setprio 1
	v_mfma_f32_16x16x32_bf16 v[4:7], v[68:71], v[20:23], v[232:235]
	v_mfma_f32_16x16x32_bf16 v[100:103], v[72:75], v[28:31], v[4:7]
	v_mfma_f32_16x16x32_bf16 v[4:7], v[76:79], v[20:23], v[12:15]
	v_mfma_f32_16x16x32_bf16 v[28:31], v[190:193], v[28:31], v[4:7]
	v_mfma_f32_16x16x32_bf16 v[4:7], v[68:71], v[166:169], v[236:239]
	v_mfma_f32_16x16x32_bf16 v[92:95], v[72:75], v[170:173], v[4:7]
	v_mfma_f32_16x16x32_bf16 v[4:7], v[76:79], v[166:169], v[240:243]
	v_mfma_f32_16x16x32_bf16 v[20:23], v[190:193], v[170:173], v[4:7]
	v_mfma_f32_16x16x32_bf16 v[4:7], v[68:71], v[194:197], v[244:247]
	v_mfma_f32_16x16x32_bf16 v[84:87], v[72:75], v[202:205], v[4:7]
	v_mfma_f32_16x16x32_bf16 v[4:7], v[76:79], v[194:197], v[174:177]
	v_mfma_f32_16x16x32_bf16 v[12:15], v[190:193], v[202:205], v[4:7]
	v_mfma_f32_16x16x32_bf16 v[4:7], v[68:71], v[206:209], v[178:181]
	v_mfma_f32_16x16x32_bf16 v[68:71], v[72:75], v[248:251], v[4:7]
	v_mfma_f32_16x16x32_bf16 v[4:7], v[76:79], v[206:209], v[182:185]
	v_mfma_f32_16x16x32_bf16 v[4:7], v[190:193], v[248:251], v[4:7]
	s_setprio 0
	v_readlane_b32 s8, v254, 8
	v_lshl_or_b32 v72, s94, 7, v214
	v_readlane_b32 s12, v254, 12
	v_readlane_b32 s13, v254, 13
	v_readlane_b32 s14, v254, 14
	v_readlane_b32 s15, v254, 15
	v_readlane_b32 s20, v254, 20
	v_readlane_b32 s21, v254, 21
	v_ashrrev_i32_e32 v73, 31, v72
	v_readlane_b32 s22, v254, 22
	v_readlane_b32 s23, v254, 23
	s_mov_b64 s[12:13], s[20:21]
	v_lshlrev_b64 v[174:175], 2, v[72:73]
	s_mov_b64 s[14:15], s[22:23]
	v_lshl_add_u64 v[172:173], s[14:15], 0, v[174:175]
	global_load_dwordx4 v[136:139], v[172:173], off
	v_lshl_add_u32 v206, s62, 8, v212
	v_ashrrev_i32_e32 v207, 31, v206
	v_or_b32_e32 v202, 16, v206
	v_lshl_add_u64 v[74:75], v[72:73], 1, s[6:7]
	v_lshlrev_b64 v[76:77], 12, v[206:207]
	v_ashrrev_i32_e32 v203, 31, v202
	v_or_b32_e32 v196, 32, v206
	v_lshl_add_u64 v[154:155], v[74:75], 0, v[76:77]
	v_lshlrev_b64 v[76:77], 12, v[202:203]
	v_ashrrev_i32_e32 v197, 31, v196
	v_or_b32_e32 v192, 48, v206
	v_lshl_add_u64 v[156:157], v[74:75], 0, v[76:77]
	v_lshlrev_b64 v[76:77], 12, v[196:197]
	v_ashrrev_i32_e32 v193, 31, v192
	v_add_u32_e32 v188, 0x80, v206
	v_lshl_add_u64 v[158:159], v[74:75], 0, v[76:77]
	v_lshlrev_b64 v[76:77], 12, v[192:193]
	v_ashrrev_i32_e32 v189, 31, v188
	v_add_u32_e32 v184, 0x90, v206
	v_lshl_add_u64 v[160:161], v[74:75], 0, v[76:77]
	v_lshlrev_b64 v[76:77], 12, v[188:189]
	v_ashrrev_i32_e32 v185, 31, v184
	v_add_u32_e32 v180, 0xa0, v206
	v_lshl_add_u64 v[162:163], v[74:75], 0, v[76:77]
	v_lshlrev_b64 v[76:77], 12, v[184:185]
	v_ashrrev_i32_e32 v181, 31, v180
	v_add_u32_e32 v170, 0xb0, v206
	v_readlane_b32 s9, v254, 9
	v_readlane_b32 s16, v254, 16
	v_readlane_b32 s17, v254, 17
	v_lshl_add_u64 v[164:165], v[74:75], 0, v[76:77]
	v_lshlrev_b64 v[76:77], 12, v[180:181]
	v_ashrrev_i32_e32 v171, 31, v170
	s_mov_b64 s[8:9], s[16:17]
	v_lshl_add_u64 v[166:167], v[74:75], 0, v[76:77]
	v_lshlrev_b64 v[76:77], 12, v[170:171]
	v_lshl_add_u64 v[176:177], s[8:9], 0, v[174:175]
	v_lshl_add_u64 v[168:169], v[74:75], 0, v[76:77]
	global_load_dwordx4 v[76:79], v[176:177], off
	v_lshl_add_u64 v[178:179], s[12:13], 0, v[174:175]
	global_load_dwordx4 v[72:75], v[178:179], off
	global_load_dwordx2 v[210:211], v[154:155], off
	global_load_dwordx2 v[208:209], v[156:157], off
	global_load_dwordx2 v[204:205], v[158:159], off
	global_load_dwordx2 v[198:199], v[160:161], off
	global_load_dwordx2 v[194:195], v[162:163], off
	global_load_dwordx2 v[190:191], v[164:165], off
	global_load_dwordx2 v[186:187], v[166:167], off
	global_load_dwordx2 v[182:183], v[168:169], off
	v_readlane_b32 s96, v254, 58
	s_mov_b64 s[2:3], s[52:53]
	s_mov_b32 s94, s54
	s_mov_b32 s62, s56
	s_mov_b64 s[66:67], s[60:61]
	s_mov_b64 s[64:65], s[58:59]
	v_readlane_b32 s97, v254, 59
	v_readlane_b32 s10, v254, 10
	v_readlane_b32 s11, v254, 11
	v_readlane_b32 s18, v254, 18
	v_readlane_b32 s19, v254, 19
	s_barrier
	s_waitcnt vmcnt(0)
	v_mul_f32_e32 v136, 0xbfb8aa3b, v136
	v_exp_f32_e32 v136, v136
	v_mul_f32_e32 v137, 0xbfb8aa3b, v137
	v_exp_f32_e32 v137, v137
	v_mul_f32_e32 v138, 0xbfb8aa3b, v138
	v_add_f32_e32 v153, 1.0, v136
	v_add_f32_e32 v148, -1.0, v153
	v_sub_f32_e32 v149, v148, v153
	v_add_f32_e32 v149, 1.0, v149
	v_sub_f32_e32 v148, v136, v148
	v_add_f32_e32 v223, v148, v149
	v_frexp_mant_f32_e32 v148, v153
	v_cmp_gt_f32_e32 vcc, s76, v148
	v_cvt_f64_f32_e32 v[148:149], v153
	v_frexp_exp_i32_f64_e32 v148, v[148:149]
	v_subbrev_co_u32_e32 v230, vcc, 0, v148, vcc
	v_sub_u32_e32 v148, 0, v230
	v_ldexp_f32 v149, v153, v148
	v_add_f32_e32 v153, -1.0, v149
	v_add_f32_e32 v224, 1.0, v149
	v_ldexp_f32 v148, v223, v148
	v_add_f32_e32 v223, 1.0, v153
	v_add_f32_e32 v225, -1.0, v224
	v_sub_f32_e32 v223, v149, v223
	v_sub_f32_e32 v149, v149, v225
	v_add_f32_e32 v223, v148, v223
	v_add_f32_e32 v148, v148, v149
	v_add_f32_e32 v231, v224, v148
	v_rcp_f32_e32 v233, v231
	v_sub_f32_e32 v149, v231, v224
	v_sub_f32_e32 v232, v148, v149
	v_add_f32_e32 v149, v153, v223
	v_sub_f32_e32 v148, v149, v153
	v_sub_f32_e32 v153, v223, v148
	v_mul_f32_e32 v223, v149, v233
	v_mul_f32_e32 v224, v231, v223
	v_fma_f32 v226, v223, v231, -v224
	v_fmac_f32_e32 v226, v223, v232
	v_add_f32_e32 v148, v224, v226
	v_sub_f32_e32 v225, v149, v148
	v_pk_add_f32 v[228:229], v[148:149], v[224:225] neg_lo:[0,1] neg_hi:[0,1]
	v_mov_b32_e32 v227, v148
	v_pk_add_f32 v[148:149], v[228:229], v[226:227] neg_lo:[0,1] neg_hi:[0,1]
	v_cmp_neq_f32_e32 vcc, s78, v136
	v_add_f32_e32 v149, v153, v149
	v_add_f32_e32 v148, v148, v149
	v_add_f32_e32 v149, v225, v148
	v_mul_f32_e32 v153, v233, v149
	v_mul_f32_e32 v224, v231, v153
	v_fma_f32 v226, v153, v231, -v224
;     __device__ __forceinline__ void operator()(const AccT& acc, const Unit& u, int wr, int wc, int fr, int fq) const {
;     ...
;             for (int j = 0; j < 4; ++j) sp[j] = -8.0f * log1pf(__expf(-l[j]));
;     ...
;                     for (int j = 0; j < 4; ++j) { const float r = __builtin_amdgcn_rcpf(1.0f + __expf(-rp[j])), ig = __builtin_amdgcn_rcpf(1.0f + __expf(-ip[j])); const float la = sp[j] * r; const float d = 1.0f - __expf(la);
	v_fmac_f32_e32 v226, v153, v232
	v_sub_f32_e32 v225, v225, v149
	v_add_f32_e32 v231, v148, v225
	v_add_f32_e32 v148, v224, v226
	v_sub_f32_e32 v225, v149, v148
	v_pk_add_f32 v[228:229], v[148:149], v[224:225] neg_lo:[0,1] neg_hi:[0,1]
	v_mov_b32_e32 v227, v148
	v_pk_add_f32 v[148:149], v[228:229], v[226:227] neg_lo:[0,1] neg_hi:[0,1]
	v_exp_f32_e32 v138, v138
	v_add_f32_e32 v149, v231, v149
	v_add_f32_e32 v148, v148, v149
	v_add_f32_e32 v149, v223, v153
	v_add_f32_e32 v148, v225, v148
	v_sub_f32_e32 v223, v149, v223
	v_mul_f32_e32 v148, v233, v148
	v_sub_f32_e32 v153, v153, v223
	v_add_f32_e32 v223, v153, v148
	v_add_f32_e32 v224, v149, v223
	v_mul_f32_e32 v226, v224, v224
	v_fmamk_f32 v148, v226, 0x3e9b6dac, v218
	v_fmaak_f32 v153, v226, v148, 0x3f2aaada
	v_cvt_f32_i32_e32 v148, v230
	v_sub_f32_e32 v149, v224, v149
	v_sub_f32_e32 v149, v223, v149
	v_ldexp_f32 v223, v149, 1
	v_mul_f32_e32 v149, v224, v226
	v_pk_mul_f32 v[226:227], v[148:149], v[152:153]
	v_ldexp_f32 v225, v224, 1
	v_fma_f32 v224, v148, s77, -v226
	v_fmac_f32_e32 v224, 0xb102e308, v148
	v_pk_add_f32 v[148:149], v[226:227], v[224:225]
	v_mov_b32_e32 v228, v226
	v_sub_f32_e32 v153, v149, v225
	v_sub_f32_e32 v153, v227, v153
	v_add_f32_e32 v229, v223, v153
	v_pk_add_f32 v[226:227], v[148:149], v[226:227] neg_lo:[0,1] neg_hi:[0,1]
	v_pk_add_f32 v[230:231], v[148:149], v[228:229]
	v_mov_b32_e32 v225, v148
	v_mov_b32_e32 v227, v231
	v_pk_add_f32 v[232:233], v[224:225], v[226:227] neg_lo:[0,1] neg_hi:[0,1]
	v_pk_add_f32 v[224:225], v[224:225], v[226:227]
	v_mov_b32_e32 v228, v229
	v_pk_add_f32 v[226:227], v[224:225], v[148:149] op_sel:[1,0] op_sel_hi:[0,1] neg_lo:[0,1] neg_hi:[0,1]
	v_pk_add_f32 v[234:235], v[230:231], v[226:227] op_sel_hi:[1,0] neg_lo:[0,1] neg_hi:[0,1]
	v_mov_b32_e32 v230, v231
	v_mov_b32_e32 v231, v225
	v_pk_mov_b32 v[226:227], v[148:149], v[226:227] op_sel:[1,0]
	v_mov_b32_e32 v229, v148
	v_pk_add_f32 v[226:227], v[230:231], v[226:227] neg_lo:[0,1] neg_hi:[0,1]
	v_mov_b32_e32 v234, v232
	v_pk_add_f32 v[148:149], v[228:229], v[226:227] neg_lo:[0,1] neg_hi:[0,1]
	v_mov_b32_e32 v233, v225
	v_pk_add_f32 v[226:227], v[234:235], v[148:149]
	v_mul_f32_e32 v139, 0xbfb8aa3b, v139
	v_pk_add_f32 v[228:229], v[226:227], v[226:227] op_sel:[0,1] op_sel_hi:[1,0]
	v_exp_f32_e32 v139, v139
	v_pk_add_f32 v[224:225], v[224:225], v[228:229] op_sel:[1,0] op_sel_hi:[0,1]
	v_mov_b32_e32 v227, v224
	v_pk_add_f32 v[230:231], v[226:227], v[232:233] neg_lo:[0,1] neg_hi:[0,1]
	v_mov_b32_e32 v149, v228
	v_sub_f32_e32 v153, v226, v230
	v_pk_add_f32 v[148:149], v[148:149], v[230:231] neg_lo:[0,1] neg_hi:[0,1]
	v_sub_f32_e32 v153, v232, v153
	v_add_f32_e32 v148, v148, v153
	v_add_f32_e32 v148, v148, v149
	v_add_f32_e32 v148, v224, v148
	v_cndmask_b32_e32 v148, v219, v148, vcc
	v_cmp_ngt_f32_e32 vcc, -1.0, v136
	v_add_f32_e32 v153, 1.0, v137
	v_add_f32_e32 v128, v128, v76
	v_cndmask_b32_e32 v148, v220, v148, vcc
	v_cmp_neq_f32_e32 vcc, -1.0, v136
	v_mul_f32_e32 v128, 0xbfb8aa3b, v128
	v_exp_f32_e32 v128, v128
	v_cndmask_b32_e32 v148, v221, v148, vcc
	v_cmp_lt_f32_e64 vcc, |v136|, s79
	v_add_f32_e32 v132, v132, v72
	v_add_f32_e32 v128, 1.0, v128
	v_cndmask_b32_e32 v136, v148, v136, vcc
	v_add_f32_e32 v148, -1.0, v153
	v_sub_f32_e32 v149, v148, v153
	v_add_f32_e32 v149, 1.0, v149
	v_sub_f32_e32 v148, v137, v148
	v_add_f32_e32 v223, v148, v149
	v_frexp_mant_f32_e32 v148, v153
	v_cmp_gt_f32_e32 vcc, s76, v148
	v_cvt_f64_f32_e32 v[148:149], v153
	v_frexp_exp_i32_f64_e32 v148, v[148:149]
	v_subbrev_co_u32_e32 v230, vcc, 0, v148, vcc
	v_sub_u32_e32 v148, 0, v230
	v_ldexp_f32 v149, v153, v148
	v_add_f32_e32 v153, -1.0, v149
	v_add_f32_e32 v224, 1.0, v149
	v_ldexp_f32 v148, v223, v148
	v_add_f32_e32 v223, 1.0, v153
	v_add_f32_e32 v225, -1.0, v224
	v_sub_f32_e32 v223, v149, v223
	v_sub_f32_e32 v149, v149, v225
	v_add_f32_e32 v223, v148, v223
	v_add_f32_e32 v148, v148, v149
	v_add_f32_e32 v231, v224, v148
	v_rcp_f32_e32 v233, v231
	v_sub_f32_e32 v149, v231, v224
	v_sub_f32_e32 v232, v148, v149
	v_add_f32_e32 v149, v153, v223
	v_sub_f32_e32 v148, v149, v153
	v_sub_f32_e32 v153, v223, v148
	v_mul_f32_e32 v223, v149, v233
	v_mul_f32_e32 v224, v231, v223
	v_fma_f32 v226, v223, v231, -v224
	v_fmac_f32_e32 v226, v223, v232
	v_add_f32_e32 v148, v224, v226
	v_sub_f32_e32 v225, v149, v148
	v_pk_add_f32 v[228:229], v[148:149], v[224:225] neg_lo:[0,1] neg_hi:[0,1]
	v_mov_b32_e32 v227, v148
	v_pk_add_f32 v[148:149], v[228:229], v[226:227] neg_lo:[0,1] neg_hi:[0,1]
	v_cmp_neq_f32_e32 vcc, s78, v137
	v_add_f32_e32 v149, v153, v149
	v_add_f32_e32 v148, v148, v149
	v_add_f32_e32 v149, v225, v148
	v_mul_f32_e32 v153, v233, v149
	v_mul_f32_e32 v224, v231, v153
	v_fma_f32 v226, v153, v231, -v224
	v_fmac_f32_e32 v226, v153, v232
	v_sub_f32_e32 v225, v225, v149
	v_add_f32_e32 v231, v148, v225
	v_add_f32_e32 v148, v224, v226
	v_sub_f32_e32 v225, v149, v148
	v_pk_add_f32 v[228:229], v[148:149], v[224:225] neg_lo:[0,1] neg_hi:[0,1]
	v_mov_b32_e32 v227, v148
	v_pk_add_f32 v[148:149], v[228:229], v[226:227] neg_lo:[0,1] neg_hi:[0,1]
	v_rcp_f32_e32 v128, v128
	v_add_f32_e32 v149, v231, v149
	v_add_f32_e32 v148, v148, v149
	v_add_f32_e32 v149, v223, v153
	v_add_f32_e32 v148, v225, v148
	v_sub_f32_e32 v223, v149, v223
	v_mul_f32_e32 v148, v233, v148
	v_sub_f32_e32 v153, v153, v223
	v_add_f32_e32 v223, v153, v148
	v_add_f32_e32 v224, v149, v223
	v_mul_f32_e32 v226, v224, v224
	v_fmamk_f32 v148, v226, 0x3e9b6dac, v218
	v_fmaak_f32 v153, v226, v148, 0x3f2aaada
	v_cvt_f32_i32_e32 v148, v230
	v_sub_f32_e32 v149, v224, v149
	v_sub_f32_e32 v149, v223, v149
	v_ldexp_f32 v223, v149, 1
	v_mul_f32_e32 v149, v224, v226
;     __device__ __forceinline__ void operator()(const AccT& acc, const Unit& u, int wr, int wc, int fr, int fq) const {
;     ...
;             for (int j = 0; j < 4; ++j) sp[j] = -8.0f * log1pf(__expf(-l[j]));
;     ...
;                     for (int j = 0; j < 4; ++j) { const float r = __builtin_amdgcn_rcpf(1.0f + __expf(-rp[j])), ig = __builtin_amdgcn_rcpf(1.0f + __expf(-ip[j])); const float la = sp[j] * r; const float d = 1.0f - __expf(la);
	v_pk_mul_f32 v[226:227], v[148:149], v[152:153]
	v_ldexp_f32 v225, v224, 1
	v_fma_f32 v224, v148, s77, -v226
	v_fmac_f32_e32 v224, 0xb102e308, v148
	v_pk_add_f32 v[148:149], v[226:227], v[224:225]
	v_mov_b32_e32 v228, v226
	v_sub_f32_e32 v153, v149, v225
	v_sub_f32_e32 v153, v227, v153
	v_add_f32_e32 v229, v223, v153
	v_pk_add_f32 v[226:227], v[148:149], v[226:227] neg_lo:[0,1] neg_hi:[0,1]
	v_pk_add_f32 v[230:231], v[148:149], v[228:229]
	v_mov_b32_e32 v225, v148
	v_mov_b32_e32 v227, v231
	v_pk_add_f32 v[232:233], v[224:225], v[226:227] neg_lo:[0,1] neg_hi:[0,1]
	v_pk_add_f32 v[224:225], v[224:225], v[226:227]
	v_mov_b32_e32 v228, v229
	v_pk_add_f32 v[226:227], v[224:225], v[148:149] op_sel:[1,0] op_sel_hi:[0,1] neg_lo:[0,1] neg_hi:[0,1]
	v_pk_add_f32 v[234:235], v[230:231], v[226:227] op_sel_hi:[1,0] neg_lo:[0,1] neg_hi:[0,1]
	v_mov_b32_e32 v230, v231
	v_mov_b32_e32 v231, v225
	v_pk_mov_b32 v[226:227], v[148:149], v[226:227] op_sel:[1,0]
	v_mov_b32_e32 v229, v148
	v_pk_add_f32 v[226:227], v[230:231], v[226:227] neg_lo:[0,1] neg_hi:[0,1]
	v_mov_b32_e32 v234, v232
	v_pk_add_f32 v[148:149], v[228:229], v[226:227] neg_lo:[0,1] neg_hi:[0,1]
	v_mov_b32_e32 v233, v225
	v_pk_add_f32 v[226:227], v[234:235], v[148:149]
	v_mul_f32_e32 v136, 0xc1000000, v136
	v_pk_add_f32 v[228:229], v[226:227], v[226:227] op_sel:[0,1] op_sel_hi:[1,0]
	v_mul_f32_e32 v128, v128, v136
	v_pk_add_f32 v[224:225], v[224:225], v[228:229] op_sel:[1,0] op_sel_hi:[0,1]
	v_mov_b32_e32 v227, v224
	v_pk_add_f32 v[230:231], v[226:227], v[232:233] neg_lo:[0,1] neg_hi:[0,1]
	v_mov_b32_e32 v149, v228
	v_sub_f32_e32 v153, v226, v230
	v_pk_add_f32 v[148:149], v[148:149], v[230:231] neg_lo:[0,1] neg_hi:[0,1]
	v_sub_f32_e32 v153, v232, v153
	v_add_f32_e32 v148, v148, v153
	v_add_f32_e32 v148, v148, v149
	v_add_f32_e32 v148, v224, v148
	v_cndmask_b32_e32 v148, v219, v148, vcc
	v_cmp_ngt_f32_e32 vcc, -1.0, v137
	v_add_f32_e32 v153, 1.0, v138
	v_mul_f32_e32 v128, 0x3fb8aa3b, v128
	v_cndmask_b32_e32 v148, v220, v148, vcc
	v_cmp_neq_f32_e32 vcc, -1.0, v137
	v_exp_f32_e32 v128, v128
	v_mul_f32_e32 v132, 0xbfb8aa3b, v132
	v_cndmask_b32_e32 v148, v221, v148, vcc
	v_cmp_lt_f32_e64 vcc, |v137|, s79
	v_exp_f32_e32 v132, v132
	v_sub_f32_e32 v128, 1.0, v128
	v_cndmask_b32_e32 v137, v148, v137, vcc
	v_add_f32_e32 v148, -1.0, v153
	v_sub_f32_e32 v149, v148, v153
	v_add_f32_e32 v149, 1.0, v149
	v_sub_f32_e32 v148, v138, v148
	v_add_f32_e32 v223, v148, v149
	v_frexp_mant_f32_e32 v148, v153
	v_cmp_gt_f32_e32 vcc, s76, v148
	v_cvt_f64_f32_e32 v[148:149], v153
	v_frexp_exp_i32_f64_e32 v148, v[148:149]
	v_subbrev_co_u32_e32 v230, vcc, 0, v148, vcc
	v_sub_u32_e32 v148, 0, v230
	v_ldexp_f32 v149, v153, v148
	v_add_f32_e32 v153, -1.0, v149
	v_add_f32_e32 v224, 1.0, v149
	v_ldexp_f32 v148, v223, v148
	v_add_f32_e32 v223, 1.0, v153
	v_add_f32_e32 v225, -1.0, v224
	v_sub_f32_e32 v223, v149, v223
	v_sub_f32_e32 v149, v149, v225
	v_add_f32_e32 v223, v148, v223
	v_add_f32_e32 v148, v148, v149
	v_add_f32_e32 v231, v224, v148
	v_rcp_f32_e32 v233, v231
	v_sub_f32_e32 v149, v231, v224
	v_sub_f32_e32 v232, v148, v149
	v_add_f32_e32 v149, v153, v223
	v_sub_f32_e32 v148, v149, v153
	v_sub_f32_e32 v153, v223, v148
	v_mul_f32_e32 v223, v149, v233
	v_mul_f32_e32 v224, v231, v223
	v_fma_f32 v226, v223, v231, -v224
	v_fmac_f32_e32 v226, v223, v232
	v_add_f32_e32 v148, v224, v226
	v_sub_f32_e32 v225, v149, v148
	v_pk_add_f32 v[228:229], v[148:149], v[224:225] neg_lo:[0,1] neg_hi:[0,1]
	v_mov_b32_e32 v227, v148
	v_pk_add_f32 v[148:149], v[228:229], v[226:227] neg_lo:[0,1] neg_hi:[0,1]
	v_cmp_neq_f32_e32 vcc, s78, v138
	v_add_f32_e32 v149, v153, v149
	v_add_f32_e32 v148, v148, v149
	v_add_f32_e32 v149, v225, v148
	v_mul_f32_e32 v153, v233, v149
	v_mul_f32_e32 v224, v231, v153
	v_fma_f32 v226, v153, v231, -v224
	v_fmac_f32_e32 v226, v153, v232
	v_sub_f32_e32 v225, v225, v149
	v_add_f32_e32 v231, v148, v225
	v_add_f32_e32 v148, v224, v226
	v_sub_f32_e32 v225, v149, v148
	v_pk_add_f32 v[228:229], v[148:149], v[224:225] neg_lo:[0,1] neg_hi:[0,1]
	v_mov_b32_e32 v227, v148
	v_pk_add_f32 v[148:149], v[228:229], v[226:227] neg_lo:[0,1] neg_hi:[0,1]
	v_add_f32_e32 v132, 1.0, v132
	v_add_f32_e32 v149, v231, v149
	v_add_f32_e32 v148, v148, v149
	v_add_f32_e32 v149, v223, v153
	v_add_f32_e32 v148, v225, v148
	v_sub_f32_e32 v223, v149, v223
	v_mul_f32_e32 v148, v233, v148
	v_sub_f32_e32 v153, v153, v223
	v_add_f32_e32 v223, v153, v148
	v_add_f32_e32 v224, v149, v223
	v_mul_f32_e32 v226, v224, v224
	v_fmamk_f32 v148, v226, 0x3e9b6dac, v218
	v_fmaak_f32 v153, v226, v148, 0x3f2aaada
	v_cvt_f32_i32_e32 v148, v230
	v_sub_f32_e32 v149, v224, v149
	v_sub_f32_e32 v149, v223, v149
	v_ldexp_f32 v223, v149, 1
	v_mul_f32_e32 v149, v224, v226
	v_pk_mul_f32 v[226:227], v[148:149], v[152:153]
	v_ldexp_f32 v225, v224, 1
	v_fma_f32 v224, v148, s77, -v226
	v_fmac_f32_e32 v224, 0xb102e308, v148
	v_pk_add_f32 v[148:149], v[226:227], v[224:225]
	v_mov_b32_e32 v228, v226
	v_sub_f32_e32 v153, v149, v225
	v_sub_f32_e32 v153, v227, v153
	v_add_f32_e32 v229, v223, v153
	v_pk_add_f32 v[226:227], v[148:149], v[226:227] neg_lo:[0,1] neg_hi:[0,1]
	v_pk_add_f32 v[230:231], v[148:149], v[228:229]
	v_mov_b32_e32 v225, v148
	v_mov_b32_e32 v227, v231
	v_pk_add_f32 v[232:233], v[224:225], v[226:227] neg_lo:[0,1] neg_hi:[0,1]
	v_pk_add_f32 v[224:225], v[224:225], v[226:227]
	v_mov_b32_e32 v228, v229
	v_pk_add_f32 v[226:227], v[224:225], v[148:149] op_sel:[1,0] op_sel_hi:[0,1] neg_lo:[0,1] neg_hi:[0,1]
	v_pk_add_f32 v[234:235], v[230:231], v[226:227] op_sel_hi:[1,0] neg_lo:[0,1] neg_hi:[0,1]
	v_mov_b32_e32 v230, v231
	v_mov_b32_e32 v231, v225
	v_pk_mov_b32 v[226:227], v[148:149], v[226:227] op_sel:[1,0]
;     __device__ __forceinline__ void operator()(const AccT& acc, const Unit& u, int wr, int wc, int fr, int fq) const {
;     ...
;             for (int j = 0; j < 4; ++j) sp[j] = -8.0f * log1pf(__expf(-l[j]));
;     ...
;                     for (int j = 0; j < 4; ++j) { const float r = __builtin_amdgcn_rcpf(1.0f + __expf(-rp[j])), ig = __builtin_amdgcn_rcpf(1.0f + __expf(-ip[j])); const float la = sp[j] * r; const float d = 1.0f - __expf(la);
	v_mov_b32_e32 v229, v148
	v_pk_add_f32 v[226:227], v[230:231], v[226:227] neg_lo:[0,1] neg_hi:[0,1]
	v_mov_b32_e32 v234, v232
	v_pk_add_f32 v[148:149], v[228:229], v[226:227] neg_lo:[0,1] neg_hi:[0,1]
	v_mov_b32_e32 v233, v225
	v_pk_add_f32 v[226:227], v[234:235], v[148:149]
	v_rcp_f32_e32 v132, v132
	v_pk_add_f32 v[228:229], v[226:227], v[226:227] op_sel:[0,1] op_sel_hi:[1,0]
	v_mul_f32_e32 v137, 0xc1000000, v137
	v_pk_add_f32 v[224:225], v[224:225], v[228:229] op_sel:[1,0] op_sel_hi:[0,1]
	v_mov_b32_e32 v227, v224
	v_pk_add_f32 v[230:231], v[226:227], v[232:233] neg_lo:[0,1] neg_hi:[0,1]
	v_mov_b32_e32 v149, v228
	v_sub_f32_e32 v153, v226, v230
	v_pk_add_f32 v[148:149], v[148:149], v[230:231] neg_lo:[0,1] neg_hi:[0,1]
	v_sub_f32_e32 v153, v232, v153
	v_add_f32_e32 v148, v148, v153
	v_add_f32_e32 v148, v148, v149
	v_add_f32_e32 v148, v224, v148
	v_cndmask_b32_e32 v148, v219, v148, vcc
	v_cmp_ngt_f32_e32 vcc, -1.0, v138
	v_add_f32_e32 v153, 1.0, v139
	v_add_f32_e32 v120, v120, v76
	v_cndmask_b32_e32 v148, v220, v148, vcc
	v_cmp_neq_f32_e32 vcc, -1.0, v138
	v_mul_f32_e32 v120, 0xbfb8aa3b, v120
	v_exp_f32_e32 v120, v120
	v_cndmask_b32_e32 v148, v221, v148, vcc
	v_cmp_lt_f32_e64 vcc, |v138|, s79
	v_add_f32_e32 v124, v124, v72
	v_add_f32_e32 v120, 1.0, v120
	v_cndmask_b32_e32 v138, v148, v138, vcc
	v_add_f32_e32 v148, -1.0, v153
	v_sub_f32_e32 v149, v148, v153
	v_add_f32_e32 v149, 1.0, v149
	v_sub_f32_e32 v148, v139, v148
	v_add_f32_e32 v223, v148, v149
	v_frexp_mant_f32_e32 v148, v153
	v_cmp_gt_f32_e32 vcc, s76, v148
	v_cvt_f64_f32_e32 v[148:149], v153
	v_frexp_exp_i32_f64_e32 v148, v[148:149]
	v_subbrev_co_u32_e32 v230, vcc, 0, v148, vcc
	v_sub_u32_e32 v148, 0, v230
	v_ldexp_f32 v149, v153, v148
	v_add_f32_e32 v153, -1.0, v149
	v_add_f32_e32 v224, 1.0, v149
	v_ldexp_f32 v148, v223, v148
	v_add_f32_e32 v223, 1.0, v153
	v_add_f32_e32 v225, -1.0, v224
	v_sub_f32_e32 v223, v149, v223
	v_sub_f32_e32 v149, v149, v225
	v_add_f32_e32 v223, v148, v223
	v_add_f32_e32 v148, v148, v149
	v_add_f32_e32 v231, v224, v148
	v_rcp_f32_e32 v233, v231
	v_sub_f32_e32 v149, v231, v224
	v_sub_f32_e32 v232, v148, v149
	v_add_f32_e32 v149, v153, v223
	v_sub_f32_e32 v148, v149, v153
	v_sub_f32_e32 v153, v223, v148
	v_mul_f32_e32 v223, v149, v233
	v_mul_f32_e32 v224, v231, v223
	v_fma_f32 v226, v223, v231, -v224
	v_fmac_f32_e32 v226, v223, v232
	v_add_f32_e32 v148, v224, v226
	v_sub_f32_e32 v225, v149, v148
	v_pk_add_f32 v[228:229], v[148:149], v[224:225] neg_lo:[0,1] neg_hi:[0,1]
	v_mov_b32_e32 v227, v148
	v_pk_add_f32 v[148:149], v[228:229], v[226:227] neg_lo:[0,1] neg_hi:[0,1]
	v_cmp_neq_f32_e32 vcc, s78, v139
	v_add_f32_e32 v149, v153, v149
	v_add_f32_e32 v148, v148, v149
	v_add_f32_e32 v149, v225, v148
	v_mul_f32_e32 v153, v233, v149
	v_mul_f32_e32 v224, v231, v153
	v_fma_f32 v226, v153, v231, -v224
	v_fmac_f32_e32 v226, v153, v232
	v_sub_f32_e32 v225, v225, v149
	v_add_f32_e32 v231, v148, v225
	v_add_f32_e32 v148, v224, v226
	v_sub_f32_e32 v225, v149, v148
	v_pk_add_f32 v[228:229], v[148:149], v[224:225] neg_lo:[0,1] neg_hi:[0,1]
	v_mov_b32_e32 v227, v148
	v_pk_add_f32 v[148:149], v[228:229], v[226:227] neg_lo:[0,1] neg_hi:[0,1]
	v_mul_f32_e32 v138, 0xc1000000, v138
	v_add_f32_e32 v149, v231, v149
	v_add_f32_e32 v148, v148, v149
	v_add_f32_e32 v149, v223, v153
	v_add_f32_e32 v148, v225, v148
	v_sub_f32_e32 v223, v149, v223
	v_mul_f32_e32 v148, v233, v148
	v_sub_f32_e32 v153, v153, v223
	v_add_f32_e32 v223, v153, v148
	v_add_f32_e32 v224, v149, v223
	v_mul_f32_e32 v226, v224, v224
	v_fmamk_f32 v148, v226, 0x3e9b6dac, v218
	v_fmaak_f32 v153, v226, v148, 0x3f2aaada
	v_cvt_f32_i32_e32 v148, v230
	v_sub_f32_e32 v149, v224, v149
	v_sub_f32_e32 v149, v223, v149
	v_ldexp_f32 v223, v149, 1
	v_mul_f32_e32 v149, v224, v226
	v_pk_mul_f32 v[226:227], v[148:149], v[152:153]
	v_ldexp_f32 v225, v224, 1
	v_fma_f32 v224, v148, s77, -v226
	v_fmac_f32_e32 v224, 0xb102e308, v148
	v_pk_add_f32 v[148:149], v[226:227], v[224:225]
	v_mov_b32_e32 v228, v226
	v_sub_f32_e32 v153, v149, v225
	v_sub_f32_e32 v153, v227, v153
	v_add_f32_e32 v229, v223, v153
	v_pk_add_f32 v[226:227], v[148:149], v[226:227] neg_lo:[0,1] neg_hi:[0,1]
	v_pk_add_f32 v[230:231], v[148:149], v[228:229]
	v_mov_b32_e32 v225, v148
	v_mov_b32_e32 v227, v231
	v_pk_add_f32 v[232:233], v[224:225], v[226:227] neg_lo:[0,1] neg_hi:[0,1]
	v_pk_add_f32 v[224:225], v[224:225], v[226:227]
	v_mov_b32_e32 v228, v229
	v_pk_add_f32 v[226:227], v[224:225], v[148:149] op_sel:[1,0] op_sel_hi:[0,1] neg_lo:[0,1] neg_hi:[0,1]
	v_pk_add_f32 v[234:235], v[230:231], v[226:227] op_sel_hi:[1,0] neg_lo:[0,1] neg_hi:[0,1]
	v_mov_b32_e32 v230, v231
	v_mov_b32_e32 v231, v225
	v_pk_mov_b32 v[226:227], v[148:149], v[226:227] op_sel:[1,0]
	v_mov_b32_e32 v229, v148
	v_pk_add_f32 v[226:227], v[230:231], v[226:227] neg_lo:[0,1] neg_hi:[0,1]
	v_mov_b32_e32 v234, v232
	v_pk_add_f32 v[148:149], v[228:229], v[226:227] neg_lo:[0,1] neg_hi:[0,1]
	v_mov_b32_e32 v233, v225
	v_pk_add_f32 v[226:227], v[234:235], v[148:149]
	v_rcp_f32_e32 v120, v120
	v_pk_add_f32 v[228:229], v[226:227], v[226:227] op_sel:[0,1] op_sel_hi:[1,0]
	v_mul_f32_e32 v124, 0xbfb8aa3b, v124
	v_pk_add_f32 v[224:225], v[224:225], v[228:229] op_sel:[1,0] op_sel_hi:[0,1]
	v_mov_b32_e32 v227, v224
	v_pk_add_f32 v[230:231], v[226:227], v[232:233] neg_lo:[0,1] neg_hi:[0,1]
	v_mov_b32_e32 v149, v228
	v_sub_f32_e32 v153, v226, v230
	v_pk_add_f32 v[148:149], v[148:149], v[230:231] neg_lo:[0,1] neg_hi:[0,1]
	v_sub_f32_e32 v153, v232, v153
	v_add_f32_e32 v148, v148, v153
	v_add_f32_e32 v148, v148, v149
	v_add_f32_e32 v148, v224, v148
	v_cndmask_b32_e32 v148, v219, v148, vcc
	v_cmp_ngt_f32_e32 vcc, -1.0, v139
; __device__ __forceinline__ unsigned cvt_pk_bf16(float lo, float hi) { const bf16x2_t r = __builtin_convertvector((f32x2){lo, hi}, bf16x2_t); return __builtin_bit_cast(unsigned, r); }
; __device__ __forceinline__ float bf_lo(unsigned w) { return __uint_as_float(w << 16); }
; __device__ __forceinline__ float bf_hi(unsigned w) { return __uint_as_float(w & 0xffff0000u); }
;     __device__ __forceinline__ void operator()(const AccT& acc, const Unit& u, int wr, int wc, int fr, int fq) const {
;     ...
;                 for (int m = 0; m < 4; ++m) { const size_t off = (size_t)(row0 + ai * HALF + m * 16) * DM + ch0 + 16 * n;
;                     const f32x4 rp = acc[ai][0][m][n] + bra, ip = acc[ai][1][m][n] + bri;
;                     const u32x2 w = xw[ai][m]; const float xv[4] = {bf_lo(w.x), bf_hi(w.x), bf_lo(w.y), bf_hi(w.y)};
;                     u32x4 o;
; #pragma unroll
;                     for (int j = 0; j < 4; ++j) { const float r = __builtin_amdgcn_rcpf(1.0f + __expf(-rp[j])), ig = __builtin_amdgcn_rcpf(1.0f + __expf(-ip[j])); const float la = sp[j] * r; const float d = 1.0f - __expf(la);
;                         o[j] = cvt_pk_bf16(d, __builtin_amdgcn_sqrtf(fmaxf(d * (2.0f - d), 0.f)) * (ig * xv[j])); }
;                     *(u32x4*)(AU + off) = o; }
	v_and_b32_e32 v149, 0xffff0000, v210
	v_lshlrev_b32_e32 v153, 16, v211
	v_cndmask_b32_e32 v148, v220, v148, vcc
	v_cmp_neq_f32_e32 vcc, -1.0, v139
	v_mul_f32_e32 v120, v120, v136
	v_mul_f32_e32 v120, 0x3fb8aa3b, v120
	v_cndmask_b32_e32 v148, v221, v148, vcc
	v_cmp_lt_f32_e64 vcc, |v139|, s79
	v_exp_f32_e32 v120, v120
	v_exp_f32_e32 v124, v124
	v_cndmask_b32_e32 v139, v148, v139, vcc
	v_lshlrev_b32_e32 v148, 16, v210
	v_and_b32_e32 v210, 0xffff0000, v211
	v_sub_f32_e32 v211, 2.0, v128
	v_mul_f32_e32 v211, v128, v211
	v_max_f32_e32 v211, 0, v211
	v_sqrt_f32_e32 v211, v211
	v_mul_f32_e32 v132, v132, v148
	v_mul_f32_e32 v139, 0xc1000000, v139
	v_sub_f32_e32 v120, 1.0, v120
	v_mul_f32_e32 v132, v132, v211
	v_cvt_pk_bf16_f32 v132, v128, v132
	v_add_f32_e32 v128, v129, v77
	v_mul_f32_e32 v128, 0xbfb8aa3b, v128
	v_exp_f32_e32 v128, v128
	v_add_f32_e32 v129, v133, v73
	v_mul_f32_e32 v129, 0xbfb8aa3b, v129
	v_exp_f32_e32 v129, v129
	v_add_f32_e32 v128, 1.0, v128
	v_rcp_f32_e32 v128, v128
	v_add_f32_e32 v124, 1.0, v124
	v_add_f32_e32 v129, 1.0, v129
	v_rcp_f32_e32 v129, v129
	v_mul_f32_e32 v128, v128, v137
	v_mul_f32_e32 v128, 0x3fb8aa3b, v128
	v_exp_f32_e32 v128, v128
	v_mul_f32_e32 v129, v129, v149
	v_rcp_f32_e32 v124, v124
	v_add_f32_e32 v112, v112, v76
	v_sub_f32_e32 v128, 1.0, v128
	v_sub_f32_e32 v133, 2.0, v128
	v_mul_f32_e32 v133, v128, v133
	v_max_f32_e32 v133, 0, v133
	v_sqrt_f32_e32 v133, v133
	v_mul_f32_e32 v112, 0xbfb8aa3b, v112
	v_exp_f32_e32 v112, v112
	v_add_f32_e32 v116, v116, v72
	v_mul_f32_e32 v129, v129, v133
	v_cvt_pk_bf16_f32 v133, v128, v129
	v_add_f32_e32 v128, v130, v78
	v_mul_f32_e32 v128, 0xbfb8aa3b, v128
	v_exp_f32_e32 v128, v128
	v_add_f32_e32 v129, v134, v74
	v_mul_f32_e32 v129, 0xbfb8aa3b, v129
	v_exp_f32_e32 v129, v129
	v_add_f32_e32 v128, 1.0, v128
	v_rcp_f32_e32 v128, v128
	v_add_f32_e32 v112, 1.0, v112
	v_add_f32_e32 v129, 1.0, v129
	v_rcp_f32_e32 v129, v129
	v_mul_f32_e32 v128, v128, v138
	v_mul_f32_e32 v128, 0x3fb8aa3b, v128
	v_exp_f32_e32 v128, v128
	v_mul_f32_e32 v129, v129, v153
	v_rcp_f32_e32 v112, v112
	v_mul_f32_e32 v116, 0xbfb8aa3b, v116
	v_sub_f32_e32 v128, 1.0, v128
	v_sub_f32_e32 v130, 2.0, v128
	v_mul_f32_e32 v130, v128, v130
	v_max_f32_e32 v130, 0, v130
	v_sqrt_f32_e32 v130, v130
	v_mul_f32_e32 v112, v112, v136
	v_mul_f32_e32 v112, 0x3fb8aa3b, v112
	v_exp_f32_e32 v112, v112
	v_mul_f32_e32 v129, v129, v130
	v_cvt_pk_bf16_f32 v134, v128, v129
	v_add_f32_e32 v128, v131, v79
	v_mul_f32_e32 v128, 0xbfb8aa3b, v128
	v_exp_f32_e32 v128, v128
	v_add_f32_e32 v129, v135, v75
	v_mul_f32_e32 v129, 0xbfb8aa3b, v129
	v_exp_f32_e32 v129, v129
	v_add_f32_e32 v128, 1.0, v128
	v_rcp_f32_e32 v128, v128
	v_and_b32_e32 v131, 0xffff0000, v208
	v_add_f32_e32 v129, 1.0, v129
	v_rcp_f32_e32 v129, v129
	v_mul_f32_e32 v128, v128, v139
	v_mul_f32_e32 v128, 0x3fb8aa3b, v128
	v_exp_f32_e32 v128, v128
	v_mul_f32_e32 v129, v129, v210
	v_exp_f32_e32 v116, v116
	v_sub_f32_e32 v112, 1.0, v112
	v_sub_f32_e32 v128, 1.0, v128
	v_sub_f32_e32 v130, 2.0, v128
	v_mul_f32_e32 v130, v128, v130
	v_max_f32_e32 v130, 0, v130
	v_sqrt_f32_e32 v130, v130
	v_add_f32_e32 v116, 1.0, v116
	v_rcp_f32_e32 v116, v116
	v_add_f32_e32 v104, v104, v76
	v_mul_f32_e32 v129, v129, v130
	v_cvt_pk_bf16_f32 v135, v128, v129
	v_lshlrev_b64 v[128:129], 13, v[206:207]
	v_lshl_add_u64 v[128:129], s[42:43], 0, v[128:129]
	v_lshl_add_u64 v[128:129], v[128:129], 0, v[174:175]
	global_store_dwordx4 v[128:129], v[132:135], off
	v_lshlrev_b32_e32 v130, 16, v208
	v_mul_f32_e32 v124, v124, v130
	v_sub_f32_e32 v134, 2.0, v120
	v_mul_f32_e32 v134, v120, v134
	v_max_f32_e32 v134, 0, v134
	v_sqrt_f32_e32 v134, v134
	v_lshlrev_b32_e32 v132, 16, v209
	v_and_b32_e32 v133, 0xffff0000, v209
	v_mul_f32_e32 v104, 0xbfb8aa3b, v104
	v_mul_f32_e32 v124, v124, v134
	v_cvt_pk_bf16_f32 v124, v120, v124
	v_add_f32_e32 v120, v121, v77
	v_mul_f32_e32 v120, 0xbfb8aa3b, v120
	v_exp_f32_e32 v120, v120
	v_add_f32_e32 v121, v125, v73
	v_mul_f32_e32 v121, 0xbfb8aa3b, v121
	v_exp_f32_e32 v121, v121
	v_add_f32_e32 v120, 1.0, v120
	v_rcp_f32_e32 v120, v120
	v_exp_f32_e32 v104, v104
	v_add_f32_e32 v121, 1.0, v121
	v_rcp_f32_e32 v121, v121
	v_mul_f32_e32 v120, v120, v137
	v_mul_f32_e32 v120, 0x3fb8aa3b, v120
	v_exp_f32_e32 v120, v120
	v_mul_f32_e32 v121, v121, v131
	v_add_f32_e32 v104, 1.0, v104
	v_rcp_f32_e32 v104, v104
	v_sub_f32_e32 v120, 1.0, v120
	v_sub_f32_e32 v125, 2.0, v120
	v_mul_f32_e32 v125, v120, v125
	v_max_f32_e32 v125, 0, v125
	v_sqrt_f32_e32 v125, v125
	v_mul_f32_e32 v104, v104, v136
	v_mul_f32_e32 v104, 0x3fb8aa3b, v104
	v_add_f32_e32 v108, v108, v72
	v_mul_f32_e32 v121, v121, v125
	v_cvt_pk_bf16_f32 v125, v120, v121
	v_add_f32_e32 v120, v122, v78
	v_mul_f32_e32 v120, 0xbfb8aa3b, v120
	v_exp_f32_e32 v120, v120
	v_add_f32_e32 v121, v126, v74
	v_mul_f32_e32 v121, 0xbfb8aa3b, v121
	v_exp_f32_e32 v121, v121
	v_add_f32_e32 v120, 1.0, v120
	v_rcp_f32_e32 v120, v120
	v_exp_f32_e32 v104, v104
	v_add_f32_e32 v121, 1.0, v121
	v_rcp_f32_e32 v121, v121
	v_mul_f32_e32 v120, v120, v138
	v_mul_f32_e32 v120, 0x3fb8aa3b, v120
	v_exp_f32_e32 v120, v120
	v_mul_f32_e32 v121, v121, v132
	v_mul_f32_e32 v108, 0xbfb8aa3b, v108
	v_exp_f32_e32 v108, v108
	v_sub_f32_e32 v120, 1.0, v120
	v_sub_f32_e32 v122, 2.0, v120
	v_mul_f32_e32 v122, v120, v122
	v_max_f32_e32 v122, 0, v122
	v_sqrt_f32_e32 v122, v122
	v_sub_f32_e32 v104, 1.0, v104
	v_add_f32_e32 v108, 1.0, v108
	v_rcp_f32_e32 v108, v108
	v_mul_f32_e32 v121, v121, v122
	v_cvt_pk_bf16_f32 v126, v120, v121
	v_add_f32_e32 v120, v123, v79
	v_mul_f32_e32 v120, 0xbfb8aa3b, v120
	v_exp_f32_e32 v120, v120
	v_add_f32_e32 v121, v127, v75
	v_mul_f32_e32 v121, 0xbfb8aa3b, v121
; __device__ __forceinline__ unsigned cvt_pk_bf16(float lo, float hi) { const bf16x2_t r = __builtin_convertvector((f32x2){lo, hi}, bf16x2_t); return __builtin_bit_cast(unsigned, r); }
; __device__ __forceinline__ float bf_lo(unsigned w) { return __uint_as_float(w << 16); }
; __device__ __forceinline__ float bf_hi(unsigned w) { return __uint_as_float(w & 0xffff0000u); }
;     __device__ __forceinline__ void operator()(const AccT& acc, const Unit& u, int wr, int wc, int fr, int fq) const {
;     ...
;                 for (int m = 0; m < 4; ++m) { const size_t off = (size_t)(row0 + ai * HALF + m * 16) * DM + ch0 + 16 * n;
;                     const f32x4 rp = acc[ai][0][m][n] + bra, ip = acc[ai][1][m][n] + bri;
;                     const u32x2 w = xw[ai][m]; const float xv[4] = {bf_lo(w.x), bf_hi(w.x), bf_lo(w.y), bf_hi(w.y)};
;                     u32x4 o;
; #pragma unroll
;                     for (int j = 0; j < 4; ++j) { const float r = __builtin_amdgcn_rcpf(1.0f + __expf(-rp[j])), ig = __builtin_amdgcn_rcpf(1.0f + __expf(-ip[j])); const float la = sp[j] * r; const float d = 1.0f - __expf(la);
;                         o[j] = cvt_pk_bf16(d, __builtin_amdgcn_sqrtf(fmaxf(d * (2.0f - d), 0.f)) * (ig * xv[j])); }
;                     *(u32x4*)(AU + off) = o; }
	v_exp_f32_e32 v121, v121
	v_add_f32_e32 v120, 1.0, v120
	v_rcp_f32_e32 v120, v120
	v_and_b32_e32 v123, 0xffff0000, v204
	v_add_f32_e32 v121, 1.0, v121
	v_rcp_f32_e32 v121, v121
	v_mul_f32_e32 v120, v120, v139
	v_mul_f32_e32 v120, 0x3fb8aa3b, v120
	v_exp_f32_e32 v120, v120
	v_mul_f32_e32 v121, v121, v133
	v_add_f32_e32 v96, v96, v76
	v_mul_f32_e32 v96, 0xbfb8aa3b, v96
	v_sub_f32_e32 v120, 1.0, v120
	v_sub_f32_e32 v122, 2.0, v120
	v_mul_f32_e32 v122, v120, v122
	v_max_f32_e32 v122, 0, v122
	v_sqrt_f32_e32 v122, v122
	v_exp_f32_e32 v96, v96
	v_add_f32_e32 v100, v100, v72
	v_mul_f32_e32 v100, 0xbfb8aa3b, v100
	v_mul_f32_e32 v121, v121, v122
	v_cvt_pk_bf16_f32 v127, v120, v121
	v_lshlrev_b64 v[120:121], 13, v[202:203]
	v_lshl_add_u64 v[120:121], s[42:43], 0, v[120:121]
	v_lshl_add_u64 v[120:121], v[120:121], 0, v[174:175]
	global_store_dwordx4 v[120:121], v[124:127], off
	v_lshlrev_b32_e32 v122, 16, v204
	v_mul_f32_e32 v116, v116, v122
	v_sub_f32_e32 v126, 2.0, v112
	v_mul_f32_e32 v126, v112, v126
	v_max_f32_e32 v126, 0, v126
	v_sqrt_f32_e32 v126, v126
	v_lshlrev_b32_e32 v124, 16, v205
	v_and_b32_e32 v125, 0xffff0000, v205
	v_add_f32_e32 v96, 1.0, v96
	v_mul_f32_e32 v116, v116, v126
	v_cvt_pk_bf16_f32 v116, v112, v116
	v_add_f32_e32 v112, v113, v77
	v_mul_f32_e32 v112, 0xbfb8aa3b, v112
	v_exp_f32_e32 v112, v112
	v_add_f32_e32 v113, v117, v73
	v_mul_f32_e32 v113, 0xbfb8aa3b, v113
	v_exp_f32_e32 v113, v113
	v_add_f32_e32 v112, 1.0, v112
	v_rcp_f32_e32 v112, v112
	v_rcp_f32_e32 v96, v96
	v_add_f32_e32 v113, 1.0, v113
	v_rcp_f32_e32 v113, v113
	v_mul_f32_e32 v112, v112, v137
	v_mul_f32_e32 v112, 0x3fb8aa3b, v112
	v_exp_f32_e32 v112, v112
	v_mul_f32_e32 v113, v113, v123
	v_mul_f32_e32 v96, v96, v136
	v_mul_f32_e32 v96, 0x3fb8aa3b, v96
	v_sub_f32_e32 v112, 1.0, v112
	v_sub_f32_e32 v117, 2.0, v112
	v_mul_f32_e32 v117, v112, v117
	v_max_f32_e32 v117, 0, v117
	v_sqrt_f32_e32 v117, v117
	v_exp_f32_e32 v96, v96
	v_exp_f32_e32 v100, v100
	v_add_f32_e32 v88, v88, v76
	v_mul_f32_e32 v113, v113, v117
	v_cvt_pk_bf16_f32 v117, v112, v113
	v_add_f32_e32 v112, v114, v78
	v_mul_f32_e32 v112, 0xbfb8aa3b, v112
	v_exp_f32_e32 v112, v112
	v_add_f32_e32 v113, v118, v74
	v_mul_f32_e32 v113, 0xbfb8aa3b, v113
	v_exp_f32_e32 v113, v113
	v_add_f32_e32 v112, 1.0, v112
	v_rcp_f32_e32 v112, v112
	v_sub_f32_e32 v96, 1.0, v96
	v_add_f32_e32 v113, 1.0, v113
	v_rcp_f32_e32 v113, v113
	v_mul_f32_e32 v112, v112, v138
	v_mul_f32_e32 v112, 0x3fb8aa3b, v112
	v_exp_f32_e32 v112, v112
	v_mul_f32_e32 v113, v113, v124
	v_add_f32_e32 v100, 1.0, v100
	v_rcp_f32_e32 v100, v100
	v_sub_f32_e32 v112, 1.0, v112
	v_sub_f32_e32 v114, 2.0, v112
	v_mul_f32_e32 v114, v112, v114
	v_max_f32_e32 v114, 0, v114
	v_sqrt_f32_e32 v114, v114
	v_mul_f32_e32 v88, 0xbfb8aa3b, v88
	v_exp_f32_e32 v88, v88
	v_add_f32_e32 v92, v92, v72
	v_mul_f32_e32 v113, v113, v114
	v_cvt_pk_bf16_f32 v118, v112, v113
	v_add_f32_e32 v112, v115, v79
	v_mul_f32_e32 v112, 0xbfb8aa3b, v112
	v_exp_f32_e32 v112, v112
	v_add_f32_e32 v113, v119, v75
	v_mul_f32_e32 v113, 0xbfb8aa3b, v113
	v_exp_f32_e32 v113, v113
	v_add_f32_e32 v112, 1.0, v112
	v_rcp_f32_e32 v112, v112
	v_and_b32_e32 v115, 0xffff0000, v198
	v_add_f32_e32 v113, 1.0, v113
	v_rcp_f32_e32 v113, v113
	v_mul_f32_e32 v112, v112, v139
	v_mul_f32_e32 v112, 0x3fb8aa3b, v112
	v_exp_f32_e32 v112, v112
	v_mul_f32_e32 v113, v113, v125
	v_add_f32_e32 v88, 1.0, v88
	v_rcp_f32_e32 v88, v88
	v_sub_f32_e32 v112, 1.0, v112
	v_sub_f32_e32 v114, 2.0, v112
	v_mul_f32_e32 v114, v112, v114
	v_max_f32_e32 v114, 0, v114
	v_sqrt_f32_e32 v114, v114
	v_mul_f32_e32 v88, v88, v136
	v_mul_f32_e32 v88, 0x3fb8aa3b, v88
	v_exp_f32_e32 v88, v88
	v_mul_f32_e32 v113, v113, v114
	v_cvt_pk_bf16_f32 v119, v112, v113
	v_lshlrev_b64 v[112:113], 13, v[196:197]
	v_lshl_add_u64 v[112:113], s[42:43], 0, v[112:113]
	v_lshl_add_u64 v[112:113], v[112:113], 0, v[174:175]
	global_store_dwordx4 v[112:113], v[116:119], off
	v_lshlrev_b32_e32 v114, 16, v198
	v_mul_f32_e32 v108, v108, v114
	v_sub_f32_e32 v118, 2.0, v104
	v_mul_f32_e32 v118, v104, v118
	v_max_f32_e32 v118, 0, v118
	v_sqrt_f32_e32 v118, v118
	v_lshlrev_b32_e32 v116, 16, v199
	v_and_b32_e32 v117, 0xffff0000, v199
	v_mul_f32_e32 v92, 0xbfb8aa3b, v92
	v_mul_f32_e32 v108, v108, v118
	v_cvt_pk_bf16_f32 v108, v104, v108
	v_add_f32_e32 v104, v105, v77
	v_mul_f32_e32 v104, 0xbfb8aa3b, v104
	v_exp_f32_e32 v104, v104
	v_add_f32_e32 v105, v109, v73
	v_mul_f32_e32 v105, 0xbfb8aa3b, v105
	v_exp_f32_e32 v105, v105
	v_add_f32_e32 v104, 1.0, v104
	v_rcp_f32_e32 v104, v104
	v_exp_f32_e32 v92, v92
	v_add_f32_e32 v105, 1.0, v105
	v_rcp_f32_e32 v105, v105
	v_mul_f32_e32 v104, v104, v137
	v_mul_f32_e32 v104, 0x3fb8aa3b, v104
	v_exp_f32_e32 v104, v104
	v_mul_f32_e32 v105, v105, v115
	v_sub_f32_e32 v88, 1.0, v88
	v_add_f32_e32 v92, 1.0, v92
	v_sub_f32_e32 v104, 1.0, v104
	v_sub_f32_e32 v109, 2.0, v104
	v_mul_f32_e32 v109, v104, v109
	v_max_f32_e32 v109, 0, v109
	v_sqrt_f32_e32 v109, v109
	v_rcp_f32_e32 v92, v92
	v_add_f32_e32 v80, v80, v76
	v_mul_f32_e32 v80, 0xbfb8aa3b, v80
	v_mul_f32_e32 v105, v105, v109
	v_cvt_pk_bf16_f32 v109, v104, v105
	v_add_f32_e32 v104, v106, v78
	v_mul_f32_e32 v104, 0xbfb8aa3b, v104
	v_exp_f32_e32 v104, v104
	v_add_f32_e32 v105, v110, v74
	v_mul_f32_e32 v105, 0xbfb8aa3b, v105
	v_exp_f32_e32 v105, v105
	v_add_f32_e32 v104, 1.0, v104
	v_rcp_f32_e32 v104, v104
	v_exp_f32_e32 v80, v80
	v_add_f32_e32 v105, 1.0, v105
	v_rcp_f32_e32 v105, v105
	v_mul_f32_e32 v104, v104, v138
	v_mul_f32_e32 v104, 0x3fb8aa3b, v104
	v_exp_f32_e32 v104, v104
	v_mul_f32_e32 v105, v105, v116
	v_add_f32_e32 v80, 1.0, v80
	v_rcp_f32_e32 v80, v80
	v_sub_f32_e32 v104, 1.0, v104
; __device__ __forceinline__ unsigned cvt_pk_bf16(float lo, float hi) { const bf16x2_t r = __builtin_convertvector((f32x2){lo, hi}, bf16x2_t); return __builtin_bit_cast(unsigned, r); }
; __device__ __forceinline__ float bf_lo(unsigned w) { return __uint_as_float(w << 16); }
; __device__ __forceinline__ float bf_hi(unsigned w) { return __uint_as_float(w & 0xffff0000u); }
;     __device__ __forceinline__ void operator()(const AccT& acc, const Unit& u, int wr, int wc, int fr, int fq) const {
;     ...
;         for (int n = 0; n < 2; ++n) {
;             u32x2 xw[2][4];
; #pragma unroll
;             for (int ai = 0; ai < 2; ++ai)
; #pragma unroll
;                 for (int m = 0; m < 4; ++m) xw[ai][m] = *(const u32x2*)(XC + (size_t)(row0 + ai * HALF + m * 16) * DM + ch0 + 16 * n);
;             const f32x4 bra = *(const f32x4*)(b_ra + ch0 + 16 * n), bri = *(const f32x4*)(b_ri + ch0 + 16 * n), l = *(const f32x4*)(lam + ch0 + 16 * n);
;             f32x4 sp;
; #pragma unroll
;             for (int j = 0; j < 4; ++j) sp[j] = -8.0f * log1pf(__expf(-l[j]));
; #pragma unroll
;             for (int ai = 0; ai < 2; ++ai)
; #pragma unroll
;                 for (int m = 0; m < 4; ++m) { const size_t off = (size_t)(row0 + ai * HALF + m * 16) * DM + ch0 + 16 * n;
;                     const f32x4 rp = acc[ai][0][m][n] + bra, ip = acc[ai][1][m][n] + bri;
;                     const u32x2 w = xw[ai][m]; const float xv[4] = {bf_lo(w.x), bf_hi(w.x), bf_lo(w.y), bf_hi(w.y)};
;                     u32x4 o;
; #pragma unroll
;                     for (int j = 0; j < 4; ++j) { const float r = __builtin_amdgcn_rcpf(1.0f + __expf(-rp[j])), ig = __builtin_amdgcn_rcpf(1.0f + __expf(-ip[j])); const float la = sp[j] * r; const float d = 1.0f - __expf(la);
;                         o[j] = cvt_pk_bf16(d, __builtin_amdgcn_sqrtf(fmaxf(d * (2.0f - d), 0.f)) * (ig * xv[j])); }
;                     *(u32x4*)(AU + off) = o; }
	v_sub_f32_e32 v106, 2.0, v104
	v_mul_f32_e32 v106, v104, v106
	v_max_f32_e32 v106, 0, v106
	v_sqrt_f32_e32 v106, v106
	v_mul_f32_e32 v80, v80, v136
	v_mul_f32_e32 v80, 0x3fb8aa3b, v80
	v_add_f32_e32 v84, v84, v72
	v_mul_f32_e32 v105, v105, v106
	v_cvt_pk_bf16_f32 v110, v104, v105
	v_add_f32_e32 v104, v107, v79
	v_mul_f32_e32 v104, 0xbfb8aa3b, v104
	v_exp_f32_e32 v104, v104
	v_add_f32_e32 v105, v111, v75
	v_mul_f32_e32 v105, 0xbfb8aa3b, v105
	v_exp_f32_e32 v105, v105
	v_add_f32_e32 v104, 1.0, v104
	v_rcp_f32_e32 v104, v104
	v_and_b32_e32 v107, 0xffff0000, v194
	v_add_f32_e32 v105, 1.0, v105
	v_rcp_f32_e32 v105, v105
	v_mul_f32_e32 v104, v104, v139
	v_mul_f32_e32 v104, 0x3fb8aa3b, v104
	v_exp_f32_e32 v104, v104
	v_mul_f32_e32 v105, v105, v117
	v_exp_f32_e32 v80, v80
	v_mul_f32_e32 v84, 0xbfb8aa3b, v84
	v_sub_f32_e32 v104, 1.0, v104
	v_sub_f32_e32 v106, 2.0, v104
	v_mul_f32_e32 v106, v104, v106
	v_max_f32_e32 v106, 0, v106
	v_sqrt_f32_e32 v106, v106
	v_exp_f32_e32 v84, v84
	v_sub_f32_e32 v80, 1.0, v80
	v_add_f32_e32 v64, v64, v76
	v_mul_f32_e32 v105, v105, v106
	v_cvt_pk_bf16_f32 v111, v104, v105
	v_lshlrev_b64 v[104:105], 13, v[192:193]
	v_lshl_add_u64 v[104:105], s[42:43], 0, v[104:105]
	v_lshl_add_u64 v[104:105], v[104:105], 0, v[174:175]
	global_store_dwordx4 v[104:105], v[108:111], off
	global_load_dwordx2 v[114:115], v[154:155], off offset:32
	global_load_dwordx2 v[122:123], v[156:157], off offset:32
	global_load_dwordx2 v[148:149], v[158:159], off offset:32
	global_load_dwordx2 v[192:193], v[160:161], off offset:32
	global_load_dwordx2 v[202:203], v[162:163], off offset:32
	global_load_dwordx2 v[208:209], v[164:165], off offset:32
	global_load_dwordx2 v[210:211], v[166:167], off offset:32
	global_load_dwordx2 v[224:225], v[168:169], off offset:32
	global_load_dwordx4 v[116:119], v[176:177], off offset:64
	global_load_dwordx4 v[196:199], v[178:179], off offset:64
	global_load_dwordx4 v[204:207], v[172:173], off offset:64
	v_lshlrev_b32_e32 v106, 16, v194
	v_mul_f32_e32 v100, v100, v106
	v_sub_f32_e32 v110, 2.0, v96
	v_mul_f32_e32 v110, v96, v110
	v_max_f32_e32 v110, 0, v110
	v_sqrt_f32_e32 v110, v110
	v_lshlrev_b32_e32 v108, 16, v195
	v_and_b32_e32 v109, 0xffff0000, v195
	v_add_f32_e32 v84, 1.0, v84
	v_mul_f32_e32 v100, v100, v110
	v_cvt_pk_bf16_f32 v100, v96, v100
	v_add_f32_e32 v96, v97, v77
	v_mul_f32_e32 v96, 0xbfb8aa3b, v96
	v_exp_f32_e32 v96, v96
	v_add_f32_e32 v97, v101, v73
	v_mul_f32_e32 v97, 0xbfb8aa3b, v97
	v_exp_f32_e32 v97, v97
	v_add_f32_e32 v96, 1.0, v96
	v_rcp_f32_e32 v96, v96
	v_rcp_f32_e32 v84, v84
	v_add_f32_e32 v97, 1.0, v97
	v_rcp_f32_e32 v97, v97
	v_mul_f32_e32 v96, v96, v137
	v_mul_f32_e32 v96, 0x3fb8aa3b, v96
	v_exp_f32_e32 v96, v96
	v_mul_f32_e32 v97, v97, v107
	v_mul_f32_e32 v64, 0xbfb8aa3b, v64
	v_exp_f32_e32 v64, v64
	v_sub_f32_e32 v96, 1.0, v96
	v_sub_f32_e32 v101, 2.0, v96
	v_mul_f32_e32 v101, v96, v101
	v_max_f32_e32 v101, 0, v101
	v_sqrt_f32_e32 v101, v101
	v_add_f32_e32 v64, 1.0, v64
	v_rcp_f32_e32 v64, v64
	v_add_f32_e32 v68, v68, v72
	v_mul_f32_e32 v97, v97, v101
	v_cvt_pk_bf16_f32 v101, v96, v97
	v_add_f32_e32 v96, v98, v78
	v_mul_f32_e32 v96, 0xbfb8aa3b, v96
	v_exp_f32_e32 v96, v96
	v_add_f32_e32 v97, v102, v74
	v_mul_f32_e32 v97, 0xbfb8aa3b, v97
	v_exp_f32_e32 v97, v97
	v_add_f32_e32 v96, 1.0, v96
	v_rcp_f32_e32 v96, v96
	v_mul_f32_e32 v64, v64, v136
	v_add_f32_e32 v97, 1.0, v97
	v_rcp_f32_e32 v97, v97
	v_mul_f32_e32 v96, v96, v138
	v_mul_f32_e32 v96, 0x3fb8aa3b, v96
	v_exp_f32_e32 v96, v96
	v_mul_f32_e32 v97, v97, v108
	v_mul_f32_e32 v64, 0x3fb8aa3b, v64
	v_exp_f32_e32 v64, v64
	v_sub_f32_e32 v96, 1.0, v96
	v_sub_f32_e32 v98, 2.0, v96
	v_mul_f32_e32 v98, v96, v98
	v_max_f32_e32 v98, 0, v98
	v_sqrt_f32_e32 v98, v98
	v_add_f32_e32 v65, v65, v77
	v_mul_f32_e32 v68, 0xbfb8aa3b, v68
	v_mul_f32_e32 v65, 0xbfb8aa3b, v65
	v_mul_f32_e32 v97, v97, v98
	v_cvt_pk_bf16_f32 v102, v96, v97
	v_add_f32_e32 v96, v99, v79
	v_mul_f32_e32 v96, 0xbfb8aa3b, v96
	v_exp_f32_e32 v96, v96
	v_add_f32_e32 v97, v103, v75
	v_mul_f32_e32 v97, 0xbfb8aa3b, v97
	v_exp_f32_e32 v97, v97
	v_add_f32_e32 v96, 1.0, v96
	v_rcp_f32_e32 v96, v96
	v_and_b32_e32 v99, 0xffff0000, v190
	v_add_f32_e32 v97, 1.0, v97
	v_rcp_f32_e32 v97, v97
	v_mul_f32_e32 v96, v96, v139
	v_mul_f32_e32 v96, 0x3fb8aa3b, v96
	v_exp_f32_e32 v96, v96
	v_mul_f32_e32 v97, v97, v109
	v_exp_f32_e32 v68, v68
	v_exp_f32_e32 v65, v65
	v_sub_f32_e32 v96, 1.0, v96
	v_sub_f32_e32 v98, 2.0, v96
	v_mul_f32_e32 v98, v96, v98
	v_max_f32_e32 v98, 0, v98
	v_sqrt_f32_e32 v98, v98
	v_sub_f32_e32 v64, 1.0, v64
	v_sub_f32_e32 v72, 2.0, v64
	v_add_f32_e32 v68, 1.0, v68
	v_mul_f32_e32 v97, v97, v98
	v_cvt_pk_bf16_f32 v103, v96, v97
	v_lshlrev_b64 v[96:97], 13, v[188:189]
	v_lshl_add_u64 v[96:97], s[42:43], 0, v[96:97]
	v_lshl_add_u64 v[96:97], v[96:97], 0, v[174:175]
	global_store_dwordx4 v[96:97], v[100:103], off
	v_lshlrev_b32_e32 v98, 16, v190
	v_mul_f32_e32 v92, v92, v98
	v_sub_f32_e32 v102, 2.0, v88
	v_mul_f32_e32 v102, v88, v102
	v_max_f32_e32 v102, 0, v102
	v_sqrt_f32_e32 v102, v102
	v_lshlrev_b32_e32 v100, 16, v191
	v_and_b32_e32 v101, 0xffff0000, v191
	v_mul_f32_e32 v72, v64, v72
	v_mul_f32_e32 v92, v92, v102
	v_cvt_pk_bf16_f32 v92, v88, v92
	v_add_f32_e32 v88, v89, v77
	v_mul_f32_e32 v88, 0xbfb8aa3b, v88
	v_exp_f32_e32 v88, v88
	v_add_f32_e32 v89, v93, v73
	v_mul_f32_e32 v89, 0xbfb8aa3b, v89
	v_exp_f32_e32 v89, v89
	v_add_f32_e32 v88, 1.0, v88
	v_rcp_f32_e32 v88, v88
	v_add_f32_e32 v65, 1.0, v65
	v_add_f32_e32 v89, 1.0, v89
	v_rcp_f32_e32 v89, v89
	v_mul_f32_e32 v88, v88, v137
	v_mul_f32_e32 v88, 0x3fb8aa3b, v88
	v_exp_f32_e32 v88, v88
	v_mul_f32_e32 v89, v89, v99
; __device__ __forceinline__ unsigned cvt_pk_bf16(float lo, float hi) { const bf16x2_t r = __builtin_convertvector((f32x2){lo, hi}, bf16x2_t); return __builtin_bit_cast(unsigned, r); }
; __device__ __forceinline__ float bf_lo(unsigned w) { return __uint_as_float(w << 16); }
; __device__ __forceinline__ float bf_hi(unsigned w) { return __uint_as_float(w & 0xffff0000u); }
;     __device__ __forceinline__ void operator()(const AccT& acc, const Unit& u, int wr, int wc, int fr, int fq) const {
;     ...
;                 for (int m = 0; m < 4; ++m) { const size_t off = (size_t)(row0 + ai * HALF + m * 16) * DM + ch0 + 16 * n;
;                     const f32x4 rp = acc[ai][0][m][n] + bra, ip = acc[ai][1][m][n] + bri;
;                     const u32x2 w = xw[ai][m]; const float xv[4] = {bf_lo(w.x), bf_hi(w.x), bf_lo(w.y), bf_hi(w.y)};
;                     u32x4 o;
; #pragma unroll
;                     for (int j = 0; j < 4; ++j) { const float r = __builtin_amdgcn_rcpf(1.0f + __expf(-rp[j])), ig = __builtin_amdgcn_rcpf(1.0f + __expf(-ip[j])); const float la = sp[j] * r; const float d = 1.0f - __expf(la);
;                         o[j] = cvt_pk_bf16(d, __builtin_amdgcn_sqrtf(fmaxf(d * (2.0f - d), 0.f)) * (ig * xv[j])); }
;                     *(u32x4*)(AU + off) = o; }
	v_rcp_f32_e32 v68, v68
	v_max_f32_e32 v72, 0, v72
	v_sub_f32_e32 v88, 1.0, v88
	v_sub_f32_e32 v93, 2.0, v88
	v_mul_f32_e32 v93, v88, v93
	v_max_f32_e32 v93, 0, v93
	v_sqrt_f32_e32 v93, v93
	v_rcp_f32_e32 v65, v65
	v_sqrt_f32_e32 v72, v72
	v_add_f32_e32 v66, v66, v78
	v_mul_f32_e32 v89, v89, v93
	v_cvt_pk_bf16_f32 v93, v88, v89
	v_add_f32_e32 v88, v90, v78
	v_mul_f32_e32 v88, 0xbfb8aa3b, v88
	v_exp_f32_e32 v88, v88
	v_add_f32_e32 v89, v94, v74
	v_mul_f32_e32 v89, 0xbfb8aa3b, v89
	v_exp_f32_e32 v89, v89
	v_add_f32_e32 v88, 1.0, v88
	v_rcp_f32_e32 v88, v88
	v_mul_f32_e32 v65, v65, v137
	v_add_f32_e32 v89, 1.0, v89
	v_rcp_f32_e32 v89, v89
	v_mul_f32_e32 v88, v88, v138
	v_mul_f32_e32 v88, 0x3fb8aa3b, v88
	v_exp_f32_e32 v88, v88
	v_mul_f32_e32 v89, v89, v100
	v_mul_f32_e32 v65, 0x3fb8aa3b, v65
	v_exp_f32_e32 v65, v65
	v_sub_f32_e32 v88, 1.0, v88
	v_sub_f32_e32 v90, 2.0, v88
	v_mul_f32_e32 v90, v88, v90
	v_max_f32_e32 v90, 0, v90
	v_sqrt_f32_e32 v90, v90
	v_mul_f32_e32 v66, 0xbfb8aa3b, v66
	v_exp_f32_e32 v66, v66
	v_sub_f32_e32 v65, 1.0, v65
	v_mul_f32_e32 v89, v89, v90
	v_cvt_pk_bf16_f32 v94, v88, v89
	v_add_f32_e32 v88, v91, v79
	v_mul_f32_e32 v88, 0xbfb8aa3b, v88
	v_exp_f32_e32 v88, v88
	v_add_f32_e32 v89, v95, v75
	v_mul_f32_e32 v89, 0xbfb8aa3b, v89
	v_exp_f32_e32 v89, v89
	v_add_f32_e32 v88, 1.0, v88
	v_rcp_f32_e32 v88, v88
	v_and_b32_e32 v91, 0xffff0000, v186
	v_add_f32_e32 v89, 1.0, v89
	v_rcp_f32_e32 v89, v89
	v_mul_f32_e32 v88, v88, v139
	v_mul_f32_e32 v88, 0x3fb8aa3b, v88
	v_exp_f32_e32 v88, v88
	v_mul_f32_e32 v89, v89, v101
	v_add_f32_e32 v66, 1.0, v66
	v_rcp_f32_e32 v66, v66
	v_sub_f32_e32 v88, 1.0, v88
	v_sub_f32_e32 v90, 2.0, v88
	v_mul_f32_e32 v90, v88, v90
	v_max_f32_e32 v90, 0, v90
	v_sqrt_f32_e32 v90, v90
	v_mul_f32_e32 v66, v66, v138
	v_mul_f32_e32 v66, 0x3fb8aa3b, v66
	v_exp_f32_e32 v66, v66
	v_mul_f32_e32 v89, v89, v90
	v_cvt_pk_bf16_f32 v95, v88, v89
	v_lshlrev_b64 v[88:89], 13, v[184:185]
	v_lshl_add_u64 v[88:89], s[42:43], 0, v[88:89]
	v_lshl_add_u64 v[88:89], v[88:89], 0, v[174:175]
	global_store_dwordx4 v[88:89], v[92:95], off
	v_lshlrev_b32_e32 v90, 16, v186
	v_mul_f32_e32 v84, v84, v90
	v_sub_f32_e32 v94, 2.0, v80
	v_mul_f32_e32 v94, v80, v94
	v_max_f32_e32 v94, 0, v94
	v_sqrt_f32_e32 v94, v94
	v_lshlrev_b32_e32 v92, 16, v187
	v_and_b32_e32 v93, 0xffff0000, v187
	v_add_f32_e32 v67, v67, v79
	v_mul_f32_e32 v84, v84, v94
	v_cvt_pk_bf16_f32 v84, v80, v84
	v_add_f32_e32 v80, v81, v77
	v_mul_f32_e32 v80, 0xbfb8aa3b, v80
	v_exp_f32_e32 v80, v80
	v_add_f32_e32 v81, v85, v73
	v_mul_f32_e32 v81, 0xbfb8aa3b, v81
	v_exp_f32_e32 v81, v81
	v_add_f32_e32 v80, 1.0, v80
	v_rcp_f32_e32 v80, v80
	v_mul_f32_e32 v67, 0xbfb8aa3b, v67
	v_add_f32_e32 v81, 1.0, v81
	v_rcp_f32_e32 v81, v81
	v_mul_f32_e32 v80, v80, v137
	v_mul_f32_e32 v80, 0x3fb8aa3b, v80
	v_exp_f32_e32 v80, v80
	v_mul_f32_e32 v81, v81, v91
	v_exp_f32_e32 v67, v67
	v_sub_f32_e32 v66, 1.0, v66
	v_sub_f32_e32 v80, 1.0, v80
	v_sub_f32_e32 v85, 2.0, v80
	v_mul_f32_e32 v85, v80, v85
	v_max_f32_e32 v85, 0, v85
	v_sqrt_f32_e32 v85, v85
	v_add_f32_e32 v67, 1.0, v67
	v_rcp_f32_e32 v67, v67
	v_mul_f32_e32 v81, v81, v85
	v_cvt_pk_bf16_f32 v85, v80, v81
	v_add_f32_e32 v80, v82, v78
	v_mul_f32_e32 v80, 0xbfb8aa3b, v80
	v_exp_f32_e32 v80, v80
	v_add_f32_e32 v81, v86, v74
	v_mul_f32_e32 v81, 0xbfb8aa3b, v81
	v_exp_f32_e32 v81, v81
	v_add_f32_e32 v80, 1.0, v80
	v_rcp_f32_e32 v80, v80
	v_mul_f32_e32 v67, v67, v139
	v_add_f32_e32 v81, 1.0, v81
	v_rcp_f32_e32 v81, v81
	v_mul_f32_e32 v80, v80, v138
	v_mul_f32_e32 v80, 0x3fb8aa3b, v80
	v_exp_f32_e32 v80, v80
	v_mul_f32_e32 v81, v81, v92
	v_mul_f32_e32 v67, 0x3fb8aa3b, v67
	v_exp_f32_e32 v67, v67
	v_sub_f32_e32 v80, 1.0, v80
	v_sub_f32_e32 v82, 2.0, v80
	v_mul_f32_e32 v82, v80, v82
	v_max_f32_e32 v82, 0, v82
	v_sqrt_f32_e32 v82, v82
	v_sub_f32_e32 v67, 1.0, v67
	v_mul_f32_e32 v81, v81, v82
	v_cvt_pk_bf16_f32 v86, v80, v81
	v_add_f32_e32 v80, v83, v79
	v_mul_f32_e32 v80, 0xbfb8aa3b, v80
	v_exp_f32_e32 v80, v80
	v_add_f32_e32 v81, v87, v75
	v_mul_f32_e32 v81, 0xbfb8aa3b, v81
	v_exp_f32_e32 v81, v81
	v_add_f32_e32 v80, 1.0, v80
	v_rcp_f32_e32 v80, v80
	v_and_b32_e32 v83, 0xffff0000, v182
	v_add_f32_e32 v81, 1.0, v81
	v_rcp_f32_e32 v81, v81
	v_mul_f32_e32 v80, v80, v139
	v_mul_f32_e32 v80, 0x3fb8aa3b, v80
	v_exp_f32_e32 v80, v80
	v_mul_f32_e32 v81, v81, v93
	v_sub_f32_e32 v80, 1.0, v80
	v_sub_f32_e32 v82, 2.0, v80
	v_mul_f32_e32 v82, v80, v82
	v_max_f32_e32 v82, 0, v82
	v_sqrt_f32_e32 v82, v82
	s_nop 0
	v_mul_f32_e32 v81, v81, v82
	v_lshlrev_b32_e32 v82, 16, v182
	v_mul_f32_e32 v68, v68, v82
	v_mul_f32_e32 v68, v68, v72
	v_cvt_pk_bf16_f32 v64, v64, v68
	v_add_f32_e32 v68, v69, v73
	v_mul_f32_e32 v68, 0xbfb8aa3b, v68
	v_exp_f32_e32 v68, v68
	v_sub_f32_e32 v69, 2.0, v65
	v_mul_f32_e32 v69, v65, v69
	v_max_f32_e32 v69, 0, v69
	v_add_f32_e32 v68, 1.0, v68
	v_rcp_f32_e32 v68, v68
	v_sqrt_f32_e32 v69, v69
	v_cvt_pk_bf16_f32 v87, v80, v81
	v_lshlrev_b64 v[80:81], 13, v[180:181]
	v_mul_f32_e32 v68, v68, v83
	v_mul_f32_e32 v68, v68, v69
	v_cvt_pk_bf16_f32 v65, v65, v68
	v_add_f32_e32 v68, v70, v74
	v_mul_f32_e32 v68, 0xbfb8aa3b, v68
	v_exp_f32_e32 v68, v68
	v_sub_f32_e32 v69, 2.0, v66
	v_mul_f32_e32 v69, v66, v69
	v_max_f32_e32 v69, 0, v69
	v_add_f32_e32 v68, 1.0, v68
	v_rcp_f32_e32 v68, v68
	v_lshl_add_u64 v[80:81], s[42:43], 0, v[80:81]
	v_sqrt_f32_e32 v69, v69
	v_lshl_add_u64 v[80:81], v[80:81], 0, v[174:175]
	global_store_dwordx4 v[80:81], v[84:87], off
	s_nop 1
	v_lshlrev_b32_e32 v84, 16, v183
	v_mul_f32_e32 v68, v68, v84
	v_mul_f32_e32 v68, v68, v69
	v_cvt_pk_bf16_f32 v66, v66, v68
	v_add_f32_e32 v68, v71, v75
	v_mul_f32_e32 v68, 0xbfb8aa3b, v68
	v_exp_f32_e32 v68, v68
	v_sub_f32_e32 v69, 2.0, v67
	v_mul_f32_e32 v69, v67, v69
	v_max_f32_e32 v69, 0, v69
	v_add_f32_e32 v68, 1.0, v68
	v_rcp_f32_e32 v68, v68
	v_sqrt_f32_e32 v69, v69
	v_and_b32_e32 v85, 0xffff0000, v183
	v_mul_f32_e32 v68, v68, v85
	v_mul_f32_e32 v68, v68, v69
	v_cvt_pk_bf16_f32 v67, v67, v68
	v_lshlrev_b64 v[68:69], 13, v[170:171]
	v_lshl_add_u64 v[68:69], s[42:43], 0, v[68:69]
	v_lshl_add_u64 v[76:77], v[68:69], 0, v[174:175]
	global_store_dwordx4 v[76:77], v[64:67], off
	s_waitcnt vmcnt(4)
; __device__ __forceinline__ unsigned cvt_pk_bf16(float lo, float hi) { const bf16x2_t r = __builtin_convertvector((f32x2){lo, hi}, bf16x2_t); return __builtin_bit_cast(unsigned, r); }
; __device__ __forceinline__ float bf_lo(unsigned w) { return __uint_as_float(w << 16); }
; __device__ __forceinline__ float bf_hi(unsigned w) { return __uint_as_float(w & 0xffff0000u); }
;     __device__ __forceinline__ void operator()(const AccT& acc, const Unit& u, int wr, int wc, int fr, int fq) const {
;     ...
;                 for (int m = 0; m < 4; ++m) xw[ai][m] = *(const u32x2*)(XC + (size_t)(row0 + ai * HALF + m * 16) * DM + ch0 + 16 * n);
;             const f32x4 bra = *(const f32x4*)(b_ra + ch0 + 16 * n), bri = *(const f32x4*)(b_ri + ch0 + 16 * n), l = *(const f32x4*)(lam + ch0 + 16 * n);
;             f32x4 sp;
; #pragma unroll
;             for (int j = 0; j < 4; ++j) sp[j] = -8.0f * log1pf(__expf(-l[j]));
; #pragma unroll
;             for (int ai = 0; ai < 2; ++ai)
; #pragma unroll
;                 for (int m = 0; m < 4; ++m) { const size_t off = (size_t)(row0 + ai * HALF + m * 16) * DM + ch0 + 16 * n;
;                     const f32x4 rp = acc[ai][0][m][n] + bra, ip = acc[ai][1][m][n] + bri;
;                     const u32x2 w = xw[ai][m]; const float xv[4] = {bf_lo(w.x), bf_hi(w.x), bf_lo(w.y), bf_hi(w.y)};
;                     u32x4 o;
; #pragma unroll
;                     for (int j = 0; j < 4; ++j) { const float r = __builtin_amdgcn_rcpf(1.0f + __expf(-rp[j])), ig = __builtin_amdgcn_rcpf(1.0f + __expf(-ip[j])); const float la = sp[j] * r; const float d = 1.0f - __expf(la);
;                         o[j] = cvt_pk_bf16(d, __builtin_amdgcn_sqrtf(fmaxf(d * (2.0f - d), 0.f)) * (ig * xv[j])); }
	v_mov_b64_e32 v[98:99], v[114:115]
	v_mov_b64_e32 v[94:95], v[122:123]
	v_mov_b64_e32 v[92:93], v[148:149]
	v_mov_b64_e32 v[90:91], v[192:193]
	v_mov_b64_e32 v[86:87], v[202:203]
	v_mov_b64_e32 v[84:85], v[208:209]
	v_mov_b64_e32 v[82:83], v[210:211]
	v_mov_b64_e32 v[78:79], v[224:225]
	v_mov_b64_e32 v[68:69], v[116:117]
	v_mov_b64_e32 v[70:71], v[118:119]
	v_mov_b64_e32 v[64:65], v[196:197]
	v_mov_b64_e32 v[66:67], v[198:199]
	v_mov_b64_e32 v[72:73], v[204:205]
	v_mov_b64_e32 v[74:75], v[206:207]
	v_add_f32_e32 v56, v56, v68
	v_mul_f32_e32 v56, 0xbfb8aa3b, v56
	v_mul_f32_e32 v72, 0xbfb8aa3b, v72
	v_exp_f32_e32 v72, v72
	v_mul_f32_e32 v73, 0xbfb8aa3b, v73
	v_exp_f32_e32 v73, v73
	v_mul_f32_e32 v74, 0xbfb8aa3b, v74
	v_add_f32_e32 v102, 1.0, v72
	v_add_f32_e32 v100, -1.0, v102
	v_sub_f32_e32 v101, v100, v102
	v_add_f32_e32 v101, 1.0, v101
	v_sub_f32_e32 v100, v72, v100
	v_add_f32_e32 v103, v100, v101
	v_frexp_mant_f32_e32 v100, v102
	v_cmp_gt_f32_e32 vcc, s76, v100
	v_cvt_f64_f32_e32 v[100:101], v102
	v_frexp_exp_i32_f64_e32 v100, v[100:101]
	v_subbrev_co_u32_e32 v110, vcc, 0, v100, vcc
	v_sub_u32_e32 v100, 0, v110
	v_ldexp_f32 v101, v102, v100
	v_add_f32_e32 v102, -1.0, v101
	v_add_f32_e32 v106, 1.0, v101
	v_ldexp_f32 v100, v103, v100
	v_add_f32_e32 v103, 1.0, v102
	v_add_f32_e32 v107, -1.0, v106
	v_sub_f32_e32 v103, v101, v103
	v_sub_f32_e32 v101, v101, v107
	v_add_f32_e32 v103, v100, v103
	v_add_f32_e32 v100, v100, v101
	v_add_f32_e32 v111, v106, v100
	v_rcp_f32_e32 v115, v111
	v_sub_f32_e32 v101, v111, v106
	v_sub_f32_e32 v114, v100, v101
	v_add_f32_e32 v101, v102, v103
	v_mul_f32_e32 v117, v101, v115
	v_sub_f32_e32 v100, v101, v102
	v_mul_f32_e32 v102, v111, v117
	v_fma_f32 v106, v117, v111, -v102
	v_fmac_f32_e32 v106, v117, v114
	v_sub_f32_e32 v116, v103, v100
	v_add_f32_e32 v100, v102, v106
	v_sub_f32_e32 v103, v101, v100
	v_pk_add_f32 v[108:109], v[100:101], v[102:103] neg_lo:[0,1] neg_hi:[0,1]
	v_mov_b32_e32 v107, v100
	v_pk_add_f32 v[100:101], v[108:109], v[106:107] neg_lo:[0,1] neg_hi:[0,1]
	v_cmp_neq_f32_e32 vcc, s78, v72
	v_add_f32_e32 v101, v116, v101
	v_add_f32_e32 v100, v100, v101
	v_add_f32_e32 v101, v103, v100
	v_mul_f32_e32 v116, v115, v101
	v_mul_f32_e32 v102, v111, v116
	v_fma_f32 v106, v116, v111, -v102
	v_fmac_f32_e32 v106, v116, v114
	v_sub_f32_e32 v103, v103, v101
	v_add_f32_e32 v111, v100, v103
	v_add_f32_e32 v100, v102, v106
	v_sub_f32_e32 v103, v101, v100
	v_pk_add_f32 v[108:109], v[100:101], v[102:103] neg_lo:[0,1] neg_hi:[0,1]
	v_mov_b32_e32 v107, v100
	v_pk_add_f32 v[100:101], v[108:109], v[106:107] neg_lo:[0,1] neg_hi:[0,1]
	v_exp_f32_e32 v74, v74
	v_add_f32_e32 v101, v111, v101
	v_add_f32_e32 v100, v100, v101
	v_add_f32_e32 v101, v117, v116
	v_add_f32_e32 v100, v103, v100
	v_sub_f32_e32 v102, v101, v117
	v_mul_f32_e32 v100, v115, v100
	v_sub_f32_e32 v102, v116, v102
	v_add_f32_e32 v102, v102, v100
	v_add_f32_e32 v106, v101, v102
	v_mul_f32_e32 v107, v106, v106
	v_fmamk_f32 v100, v107, 0x3e9b6dac, v218
	v_fmaak_f32 v153, v107, v100, 0x3f2aaada
	v_cvt_f32_i32_e32 v100, v110
	v_sub_f32_e32 v101, v106, v101
	v_sub_f32_e32 v101, v102, v101
	v_ldexp_f32 v108, v101, 1
	v_mul_f32_e32 v101, v106, v107
	v_ldexp_f32 v103, v106, 1
	v_pk_mul_f32 v[106:107], v[100:101], v[152:153]
	v_mul_f32_e32 v75, 0xbfb8aa3b, v75
	v_fma_f32 v102, v100, s77, -v106
	v_fmac_f32_e32 v102, 0xb102e308, v100
	v_pk_add_f32 v[100:101], v[106:107], v[102:103]
	v_exp_f32_e32 v75, v75
	v_sub_f32_e32 v103, v101, v103
	v_sub_f32_e32 v103, v107, v103
	v_add_f32_e32 v109, v108, v103
	v_mov_b32_e32 v108, v106
	v_pk_add_f32 v[106:107], v[100:101], v[106:107] neg_lo:[0,1] neg_hi:[0,1]
	v_pk_add_f32 v[110:111], v[100:101], v[108:109]
	v_mov_b32_e32 v103, v100
	v_mov_b32_e32 v107, v111
	v_pk_add_f32 v[114:115], v[102:103], v[106:107] neg_lo:[0,1] neg_hi:[0,1]
	v_pk_add_f32 v[102:103], v[102:103], v[106:107]
	v_mov_b32_e32 v108, v109
	v_pk_add_f32 v[106:107], v[102:103], v[100:101] op_sel:[1,0] op_sel_hi:[0,1] neg_lo:[0,1] neg_hi:[0,1]
	v_pk_add_f32 v[116:117], v[110:111], v[106:107] op_sel_hi:[1,0] neg_lo:[0,1] neg_hi:[0,1]
	v_mov_b32_e32 v110, v111
	v_mov_b32_e32 v111, v103
	v_pk_mov_b32 v[106:107], v[100:101], v[106:107] op_sel:[1,0]
	v_mov_b32_e32 v109, v100
	v_pk_add_f32 v[106:107], v[110:111], v[106:107] neg_lo:[0,1] neg_hi:[0,1]
	v_mov_b32_e32 v116, v114
	v_pk_add_f32 v[100:101], v[108:109], v[106:107] neg_lo:[0,1] neg_hi:[0,1]
	v_mov_b32_e32 v115, v103
	v_pk_add_f32 v[106:107], v[116:117], v[100:101]
	v_exp_f32_e32 v56, v56
	v_pk_add_f32 v[108:109], v[106:107], v[106:107] op_sel:[0,1] op_sel_hi:[1,0]
	v_add_f32_e32 v60, v60, v64
	v_pk_add_f32 v[102:103], v[102:103], v[108:109] op_sel:[1,0] op_sel_hi:[0,1]
	v_mov_b32_e32 v107, v102
	v_pk_add_f32 v[110:111], v[106:107], v[114:115] neg_lo:[0,1] neg_hi:[0,1]
	v_mov_b32_e32 v101, v108
	v_sub_f32_e32 v103, v106, v110
	v_pk_add_f32 v[100:101], v[100:101], v[110:111] neg_lo:[0,1] neg_hi:[0,1]
	v_sub_f32_e32 v103, v114, v103
	v_add_f32_e32 v100, v100, v103
	v_add_f32_e32 v100, v100, v101
	v_add_f32_e32 v100, v102, v100
	v_cndmask_b32_e32 v100, v219, v100, vcc
	v_cmp_ngt_f32_e32 vcc, -1.0, v72
	v_add_f32_e32 v102, 1.0, v73
	v_add_f32_e32 v56, 1.0, v56
	v_cndmask_b32_e32 v100, v220, v100, vcc
	v_cmp_neq_f32_e32 vcc, -1.0, v72
	v_rcp_f32_e32 v56, v56
	v_add_f32_e32 v57, v57, v69
	v_cndmask_b32_e32 v100, v221, v100, vcc
	v_cmp_lt_f32_e64 vcc, |v72|, s79
	v_mul_f32_e32 v60, 0xbfb8aa3b, v60
	v_mul_f32_e32 v57, 0xbfb8aa3b, v57
	v_cndmask_b32_e32 v72, v100, v72, vcc
	v_add_f32_e32 v100, -1.0, v102
	v_sub_f32_e32 v101, v100, v102
	v_add_f32_e32 v101, 1.0, v101
	v_sub_f32_e32 v100, v73, v100
	v_add_f32_e32 v103, v100, v101
; __device__ __forceinline__ unsigned cvt_pk_bf16(float lo, float hi) { const bf16x2_t r = __builtin_convertvector((f32x2){lo, hi}, bf16x2_t); return __builtin_bit_cast(unsigned, r); }
; __device__ __forceinline__ float bf_lo(unsigned w) { return __uint_as_float(w << 16); }
; __device__ __forceinline__ float bf_hi(unsigned w) { return __uint_as_float(w & 0xffff0000u); }
;     __device__ __forceinline__ void operator()(const AccT& acc, const Unit& u, int wr, int wc, int fr, int fq) const {
;     ...
;             for (int j = 0; j < 4; ++j) sp[j] = -8.0f * log1pf(__expf(-l[j]));
; #pragma unroll
;             for (int ai = 0; ai < 2; ++ai)
; #pragma unroll
;                 for (int m = 0; m < 4; ++m) { const size_t off = (size_t)(row0 + ai * HALF + m * 16) * DM + ch0 + 16 * n;
;                     const f32x4 rp = acc[ai][0][m][n] + bra, ip = acc[ai][1][m][n] + bri;
;                     const u32x2 w = xw[ai][m]; const float xv[4] = {bf_lo(w.x), bf_hi(w.x), bf_lo(w.y), bf_hi(w.y)};
;                     u32x4 o;
; #pragma unroll
;                     for (int j = 0; j < 4; ++j) { const float r = __builtin_amdgcn_rcpf(1.0f + __expf(-rp[j])), ig = __builtin_amdgcn_rcpf(1.0f + __expf(-ip[j])); const float la = sp[j] * r; const float d = 1.0f - __expf(la);
;                         o[j] = cvt_pk_bf16(d, __builtin_amdgcn_sqrtf(fmaxf(d * (2.0f - d), 0.f)) * (ig * xv[j])); }
	v_frexp_mant_f32_e32 v100, v102
	v_cmp_gt_f32_e32 vcc, s76, v100
	v_cvt_f64_f32_e32 v[100:101], v102
	v_frexp_exp_i32_f64_e32 v100, v[100:101]
	v_subbrev_co_u32_e32 v110, vcc, 0, v100, vcc
	v_sub_u32_e32 v100, 0, v110
	v_ldexp_f32 v101, v102, v100
	v_add_f32_e32 v102, -1.0, v101
	v_add_f32_e32 v106, 1.0, v101
	v_ldexp_f32 v100, v103, v100
	v_add_f32_e32 v103, 1.0, v102
	v_add_f32_e32 v107, -1.0, v106
	v_sub_f32_e32 v103, v101, v103
	v_sub_f32_e32 v101, v101, v107
	v_add_f32_e32 v103, v100, v103
	v_add_f32_e32 v100, v100, v101
	v_add_f32_e32 v111, v106, v100
	v_rcp_f32_e32 v115, v111
	v_sub_f32_e32 v101, v111, v106
	v_sub_f32_e32 v114, v100, v101
	v_add_f32_e32 v101, v102, v103
	v_mul_f32_e32 v117, v101, v115
	v_sub_f32_e32 v100, v101, v102
	v_mul_f32_e32 v102, v111, v117
	v_fma_f32 v106, v117, v111, -v102
	v_fmac_f32_e32 v106, v117, v114
	v_sub_f32_e32 v116, v103, v100
	v_add_f32_e32 v100, v102, v106
	v_sub_f32_e32 v103, v101, v100
	v_pk_add_f32 v[108:109], v[100:101], v[102:103] neg_lo:[0,1] neg_hi:[0,1]
	v_mov_b32_e32 v107, v100
	v_pk_add_f32 v[100:101], v[108:109], v[106:107] neg_lo:[0,1] neg_hi:[0,1]
	v_cmp_neq_f32_e32 vcc, s78, v73
	v_add_f32_e32 v101, v116, v101
	v_add_f32_e32 v100, v100, v101
	v_add_f32_e32 v101, v103, v100
	v_mul_f32_e32 v116, v115, v101
	v_mul_f32_e32 v102, v111, v116
	v_fma_f32 v106, v116, v111, -v102
	v_fmac_f32_e32 v106, v116, v114
	v_sub_f32_e32 v103, v103, v101
	v_add_f32_e32 v111, v100, v103
	v_add_f32_e32 v100, v102, v106
	v_sub_f32_e32 v103, v101, v100
	v_pk_add_f32 v[108:109], v[100:101], v[102:103] neg_lo:[0,1] neg_hi:[0,1]
	v_mov_b32_e32 v107, v100
	v_pk_add_f32 v[100:101], v[108:109], v[106:107] neg_lo:[0,1] neg_hi:[0,1]
	v_mul_f32_e32 v72, 0xc1000000, v72
	v_add_f32_e32 v101, v111, v101
	v_add_f32_e32 v100, v100, v101
	v_add_f32_e32 v101, v117, v116
	v_add_f32_e32 v100, v103, v100
	v_sub_f32_e32 v102, v101, v117
	v_mul_f32_e32 v100, v115, v100
	v_sub_f32_e32 v102, v116, v102
	v_add_f32_e32 v102, v102, v100
	v_add_f32_e32 v106, v101, v102
	v_mul_f32_e32 v107, v106, v106
	v_fmamk_f32 v100, v107, 0x3e9b6dac, v218
	v_fmaak_f32 v153, v107, v100, 0x3f2aaada
	v_cvt_f32_i32_e32 v100, v110
	v_sub_f32_e32 v101, v106, v101
	v_sub_f32_e32 v101, v102, v101
	v_ldexp_f32 v108, v101, 1
	v_mul_f32_e32 v101, v106, v107
	v_ldexp_f32 v103, v106, 1
	v_pk_mul_f32 v[106:107], v[100:101], v[152:153]
	v_mul_f32_e32 v56, v56, v72
	v_fma_f32 v102, v100, s77, -v106
	v_fmac_f32_e32 v102, 0xb102e308, v100
	v_pk_add_f32 v[100:101], v[106:107], v[102:103]
	v_mul_f32_e32 v56, 0x3fb8aa3b, v56
	v_sub_f32_e32 v103, v101, v103
	v_sub_f32_e32 v103, v107, v103
	v_add_f32_e32 v109, v108, v103
	v_mov_b32_e32 v108, v106
	v_pk_add_f32 v[106:107], v[100:101], v[106:107] neg_lo:[0,1] neg_hi:[0,1]
	v_pk_add_f32 v[110:111], v[100:101], v[108:109]
	v_mov_b32_e32 v103, v100
	v_mov_b32_e32 v107, v111
	v_pk_add_f32 v[114:115], v[102:103], v[106:107] neg_lo:[0,1] neg_hi:[0,1]
	v_pk_add_f32 v[102:103], v[102:103], v[106:107]
	v_mov_b32_e32 v108, v109
	v_pk_add_f32 v[106:107], v[102:103], v[100:101] op_sel:[1,0] op_sel_hi:[0,1] neg_lo:[0,1] neg_hi:[0,1]
	v_pk_add_f32 v[116:117], v[110:111], v[106:107] op_sel_hi:[1,0] neg_lo:[0,1] neg_hi:[0,1]
	v_mov_b32_e32 v110, v111
	v_mov_b32_e32 v111, v103
	v_pk_mov_b32 v[106:107], v[100:101], v[106:107] op_sel:[1,0]
	v_mov_b32_e32 v109, v100
	v_pk_add_f32 v[106:107], v[110:111], v[106:107] neg_lo:[0,1] neg_hi:[0,1]
	v_mov_b32_e32 v116, v114
	v_pk_add_f32 v[100:101], v[108:109], v[106:107] neg_lo:[0,1] neg_hi:[0,1]
	v_mov_b32_e32 v115, v103
	v_pk_add_f32 v[106:107], v[116:117], v[100:101]
	v_exp_f32_e32 v56, v56
	v_pk_add_f32 v[108:109], v[106:107], v[106:107] op_sel:[0,1] op_sel_hi:[1,0]
	v_exp_f32_e32 v60, v60
	v_pk_add_f32 v[102:103], v[102:103], v[108:109] op_sel:[1,0] op_sel_hi:[0,1]
	v_mov_b32_e32 v107, v102
	v_pk_add_f32 v[110:111], v[106:107], v[114:115] neg_lo:[0,1] neg_hi:[0,1]
	v_mov_b32_e32 v101, v108
	v_sub_f32_e32 v103, v106, v110
	v_pk_add_f32 v[100:101], v[100:101], v[110:111] neg_lo:[0,1] neg_hi:[0,1]
	v_sub_f32_e32 v103, v114, v103
	v_add_f32_e32 v100, v100, v103
	v_add_f32_e32 v100, v100, v101
	v_add_f32_e32 v100, v102, v100
	v_cndmask_b32_e32 v100, v219, v100, vcc
	v_cmp_ngt_f32_e32 vcc, -1.0, v73
	v_add_f32_e32 v102, 1.0, v74
	v_exp_f32_e32 v57, v57
	v_cndmask_b32_e32 v100, v220, v100, vcc
	v_cmp_neq_f32_e32 vcc, -1.0, v73
	v_sub_f32_e32 v56, 1.0, v56
	v_add_f32_e32 v60, 1.0, v60
	v_cndmask_b32_e32 v100, v221, v100, vcc
	v_cmp_lt_f32_e64 vcc, |v73|, s79
	v_add_f32_e32 v57, 1.0, v57
	v_rcp_f32_e32 v60, v60
	v_cndmask_b32_e32 v73, v100, v73, vcc
	v_add_f32_e32 v100, -1.0, v102
	v_sub_f32_e32 v101, v100, v102
	v_add_f32_e32 v101, 1.0, v101
	v_sub_f32_e32 v100, v74, v100
	v_add_f32_e32 v103, v100, v101
	v_frexp_mant_f32_e32 v100, v102
	v_cmp_gt_f32_e32 vcc, s76, v100
	v_cvt_f64_f32_e32 v[100:101], v102
	v_frexp_exp_i32_f64_e32 v100, v[100:101]
	v_subbrev_co_u32_e32 v110, vcc, 0, v100, vcc
	v_sub_u32_e32 v100, 0, v110
	v_ldexp_f32 v101, v102, v100
	v_add_f32_e32 v102, -1.0, v101
	v_add_f32_e32 v106, 1.0, v101
	v_ldexp_f32 v100, v103, v100
	v_add_f32_e32 v103, 1.0, v102
	v_add_f32_e32 v107, -1.0, v106
	v_sub_f32_e32 v103, v101, v103
	v_sub_f32_e32 v101, v101, v107
	v_add_f32_e32 v103, v100, v103
	v_add_f32_e32 v100, v100, v101
	v_add_f32_e32 v111, v106, v100
	v_rcp_f32_e32 v115, v111
	v_sub_f32_e32 v101, v111, v106
	v_sub_f32_e32 v114, v100, v101
	v_add_f32_e32 v101, v102, v103
	v_mul_f32_e32 v117, v101, v115
	v_sub_f32_e32 v100, v101, v102
	v_mul_f32_e32 v102, v111, v117
	v_fma_f32 v106, v117, v111, -v102
	v_fmac_f32_e32 v106, v117, v114
	v_sub_f32_e32 v116, v103, v100
	v_add_f32_e32 v100, v102, v106
; __device__ __forceinline__ unsigned cvt_pk_bf16(float lo, float hi) { const bf16x2_t r = __builtin_convertvector((f32x2){lo, hi}, bf16x2_t); return __builtin_bit_cast(unsigned, r); }
; __device__ __forceinline__ float bf_lo(unsigned w) { return __uint_as_float(w << 16); }
; __device__ __forceinline__ float bf_hi(unsigned w) { return __uint_as_float(w & 0xffff0000u); }
;     __device__ __forceinline__ void operator()(const AccT& acc, const Unit& u, int wr, int wc, int fr, int fq) const {
;     ...
;             for (int j = 0; j < 4; ++j) sp[j] = -8.0f * log1pf(__expf(-l[j]));
; #pragma unroll
;             for (int ai = 0; ai < 2; ++ai)
; #pragma unroll
;                 for (int m = 0; m < 4; ++m) { const size_t off = (size_t)(row0 + ai * HALF + m * 16) * DM + ch0 + 16 * n;
;                     const f32x4 rp = acc[ai][0][m][n] + bra, ip = acc[ai][1][m][n] + bri;
;                     const u32x2 w = xw[ai][m]; const float xv[4] = {bf_lo(w.x), bf_hi(w.x), bf_lo(w.y), bf_hi(w.y)};
;                     u32x4 o;
; #pragma unroll
;                     for (int j = 0; j < 4; ++j) { const float r = __builtin_amdgcn_rcpf(1.0f + __expf(-rp[j])), ig = __builtin_amdgcn_rcpf(1.0f + __expf(-ip[j])); const float la = sp[j] * r; const float d = 1.0f - __expf(la);
;                         o[j] = cvt_pk_bf16(d, __builtin_amdgcn_sqrtf(fmaxf(d * (2.0f - d), 0.f)) * (ig * xv[j])); }
	v_sub_f32_e32 v103, v101, v100
	v_pk_add_f32 v[108:109], v[100:101], v[102:103] neg_lo:[0,1] neg_hi:[0,1]
	v_mov_b32_e32 v107, v100
	v_pk_add_f32 v[100:101], v[108:109], v[106:107] neg_lo:[0,1] neg_hi:[0,1]
	v_cmp_neq_f32_e32 vcc, s78, v74
	v_add_f32_e32 v101, v116, v101
	v_add_f32_e32 v100, v100, v101
	v_add_f32_e32 v101, v103, v100
	v_mul_f32_e32 v116, v115, v101
	v_mul_f32_e32 v102, v111, v116
	v_fma_f32 v106, v116, v111, -v102
	v_fmac_f32_e32 v106, v116, v114
	v_sub_f32_e32 v103, v103, v101
	v_add_f32_e32 v111, v100, v103
	v_add_f32_e32 v100, v102, v106
	v_sub_f32_e32 v103, v101, v100
	v_pk_add_f32 v[108:109], v[100:101], v[102:103] neg_lo:[0,1] neg_hi:[0,1]
	v_mov_b32_e32 v107, v100
	v_pk_add_f32 v[100:101], v[108:109], v[106:107] neg_lo:[0,1] neg_hi:[0,1]
	v_rcp_f32_e32 v57, v57
	v_add_f32_e32 v101, v111, v101
	v_add_f32_e32 v100, v100, v101
	v_add_f32_e32 v101, v117, v116
	v_add_f32_e32 v100, v103, v100
	v_sub_f32_e32 v102, v101, v117
	v_mul_f32_e32 v100, v115, v100
	v_sub_f32_e32 v102, v116, v102
	v_add_f32_e32 v102, v102, v100
	v_add_f32_e32 v106, v101, v102
	v_mul_f32_e32 v107, v106, v106
	v_fmamk_f32 v100, v107, 0x3e9b6dac, v218
	v_fmaak_f32 v153, v107, v100, 0x3f2aaada
	v_cvt_f32_i32_e32 v100, v110
	v_sub_f32_e32 v101, v106, v101
	v_sub_f32_e32 v101, v102, v101
	v_ldexp_f32 v108, v101, 1
	v_mul_f32_e32 v101, v106, v107
	v_ldexp_f32 v103, v106, 1
	v_pk_mul_f32 v[106:107], v[100:101], v[152:153]
	v_mul_f32_e32 v73, 0xc1000000, v73
	v_fma_f32 v102, v100, s77, -v106
	v_fmac_f32_e32 v102, 0xb102e308, v100
	v_pk_add_f32 v[100:101], v[106:107], v[102:103]
	v_mul_f32_e32 v57, v57, v73
	v_sub_f32_e32 v103, v101, v103
	v_sub_f32_e32 v103, v107, v103
	v_add_f32_e32 v109, v108, v103
	v_mov_b32_e32 v108, v106
	v_pk_add_f32 v[106:107], v[100:101], v[106:107] neg_lo:[0,1] neg_hi:[0,1]
	v_pk_add_f32 v[110:111], v[100:101], v[108:109]
	v_mov_b32_e32 v103, v100
	v_mov_b32_e32 v107, v111
	v_pk_add_f32 v[114:115], v[102:103], v[106:107] neg_lo:[0,1] neg_hi:[0,1]
	v_pk_add_f32 v[102:103], v[102:103], v[106:107]
	v_mov_b32_e32 v108, v109
	v_pk_add_f32 v[106:107], v[102:103], v[100:101] op_sel:[1,0] op_sel_hi:[0,1] neg_lo:[0,1] neg_hi:[0,1]
	v_pk_add_f32 v[116:117], v[110:111], v[106:107] op_sel_hi:[1,0] neg_lo:[0,1] neg_hi:[0,1]
	v_mov_b32_e32 v110, v111
	v_mov_b32_e32 v111, v103
	v_pk_mov_b32 v[106:107], v[100:101], v[106:107] op_sel:[1,0]
	v_mov_b32_e32 v109, v100
	v_pk_add_f32 v[106:107], v[110:111], v[106:107] neg_lo:[0,1] neg_hi:[0,1]
	v_mov_b32_e32 v116, v114
	v_pk_add_f32 v[100:101], v[108:109], v[106:107] neg_lo:[0,1] neg_hi:[0,1]
	v_mov_b32_e32 v115, v103
	v_pk_add_f32 v[106:107], v[116:117], v[100:101]
	v_mul_f32_e32 v57, 0x3fb8aa3b, v57
	v_pk_add_f32 v[108:109], v[106:107], v[106:107] op_sel:[0,1] op_sel_hi:[1,0]
	v_exp_f32_e32 v57, v57
	v_pk_add_f32 v[102:103], v[102:103], v[108:109] op_sel:[1,0] op_sel_hi:[0,1]
	v_mov_b32_e32 v107, v102
	v_pk_add_f32 v[110:111], v[106:107], v[114:115] neg_lo:[0,1] neg_hi:[0,1]
	v_mov_b32_e32 v101, v108
	v_sub_f32_e32 v103, v106, v110
	v_pk_add_f32 v[100:101], v[100:101], v[110:111] neg_lo:[0,1] neg_hi:[0,1]
	v_sub_f32_e32 v103, v114, v103
	v_add_f32_e32 v100, v100, v103
	v_add_f32_e32 v100, v100, v101
	v_add_f32_e32 v100, v102, v100
	v_cndmask_b32_e32 v100, v219, v100, vcc
	v_cmp_ngt_f32_e32 vcc, -1.0, v74
	v_add_f32_e32 v102, 1.0, v75
	v_add_f32_e32 v58, v58, v70
	v_cndmask_b32_e32 v100, v220, v100, vcc
	v_cmp_neq_f32_e32 vcc, -1.0, v74
	v_mul_f32_e32 v58, 0xbfb8aa3b, v58
	v_exp_f32_e32 v58, v58
	v_cndmask_b32_e32 v100, v221, v100, vcc
	v_cmp_lt_f32_e64 vcc, |v74|, s79
	v_sub_f32_e32 v57, 1.0, v57
	v_add_f32_e32 v58, 1.0, v58
	v_cndmask_b32_e32 v74, v100, v74, vcc
	v_add_f32_e32 v100, -1.0, v102
	v_sub_f32_e32 v101, v100, v102
	v_add_f32_e32 v101, 1.0, v101
	v_sub_f32_e32 v100, v75, v100
	v_add_f32_e32 v103, v100, v101
	v_frexp_mant_f32_e32 v100, v102
	v_cmp_gt_f32_e32 vcc, s76, v100
	v_cvt_f64_f32_e32 v[100:101], v102
	v_frexp_exp_i32_f64_e32 v100, v[100:101]
	v_subbrev_co_u32_e32 v110, vcc, 0, v100, vcc
	v_sub_u32_e32 v100, 0, v110
	v_ldexp_f32 v101, v102, v100
	v_add_f32_e32 v102, -1.0, v101
	v_add_f32_e32 v106, 1.0, v101
	v_ldexp_f32 v100, v103, v100
	v_add_f32_e32 v103, 1.0, v102
	v_add_f32_e32 v107, -1.0, v106
	v_sub_f32_e32 v103, v101, v103
	v_sub_f32_e32 v101, v101, v107
	v_add_f32_e32 v103, v100, v103
	v_add_f32_e32 v100, v100, v101
	v_add_f32_e32 v111, v106, v100
	v_rcp_f32_e32 v115, v111
	v_sub_f32_e32 v101, v111, v106
	v_sub_f32_e32 v114, v100, v101
	v_add_f32_e32 v101, v102, v103
	v_mul_f32_e32 v117, v101, v115
	v_sub_f32_e32 v100, v101, v102
	v_mul_f32_e32 v102, v111, v117
	v_fma_f32 v106, v117, v111, -v102
	v_fmac_f32_e32 v106, v117, v114
	v_sub_f32_e32 v116, v103, v100
	v_add_f32_e32 v100, v102, v106
	v_sub_f32_e32 v103, v101, v100
	v_pk_add_f32 v[108:109], v[100:101], v[102:103] neg_lo:[0,1] neg_hi:[0,1]
	v_mov_b32_e32 v107, v100
	v_pk_add_f32 v[100:101], v[108:109], v[106:107] neg_lo:[0,1] neg_hi:[0,1]
	v_cmp_neq_f32_e32 vcc, s78, v75
	v_add_f32_e32 v101, v116, v101
	v_add_f32_e32 v100, v100, v101
	v_add_f32_e32 v101, v103, v100
	v_mul_f32_e32 v116, v115, v101
	v_mul_f32_e32 v102, v111, v116
	v_fma_f32 v106, v116, v111, -v102
	v_fmac_f32_e32 v106, v116, v114
	v_sub_f32_e32 v103, v103, v101
	v_add_f32_e32 v111, v100, v103
	v_add_f32_e32 v100, v102, v106
	v_sub_f32_e32 v103, v101, v100
	v_pk_add_f32 v[108:109], v[100:101], v[102:103] neg_lo:[0,1] neg_hi:[0,1]
	v_mov_b32_e32 v107, v100
	v_pk_add_f32 v[100:101], v[108:109], v[106:107] neg_lo:[0,1] neg_hi:[0,1]
	v_rcp_f32_e32 v58, v58
	v_add_f32_e32 v101, v111, v101
	v_add_f32_e32 v100, v100, v101
	v_add_f32_e32 v101, v117, v116
; __device__ __forceinline__ unsigned cvt_pk_bf16(float lo, float hi) { const bf16x2_t r = __builtin_convertvector((f32x2){lo, hi}, bf16x2_t); return __builtin_bit_cast(unsigned, r); }
; __device__ __forceinline__ float bf_lo(unsigned w) { return __uint_as_float(w << 16); }
; __device__ __forceinline__ float bf_hi(unsigned w) { return __uint_as_float(w & 0xffff0000u); }
;     __device__ __forceinline__ void operator()(const AccT& acc, const Unit& u, int wr, int wc, int fr, int fq) const {
;     ...
;             for (int j = 0; j < 4; ++j) sp[j] = -8.0f * log1pf(__expf(-l[j]));
; #pragma unroll
;             for (int ai = 0; ai < 2; ++ai)
; #pragma unroll
;                 for (int m = 0; m < 4; ++m) { const size_t off = (size_t)(row0 + ai * HALF + m * 16) * DM + ch0 + 16 * n;
;                     const f32x4 rp = acc[ai][0][m][n] + bra, ip = acc[ai][1][m][n] + bri;
;                     const u32x2 w = xw[ai][m]; const float xv[4] = {bf_lo(w.x), bf_hi(w.x), bf_lo(w.y), bf_hi(w.y)};
;                     u32x4 o;
; #pragma unroll
;                     for (int j = 0; j < 4; ++j) { const float r = __builtin_amdgcn_rcpf(1.0f + __expf(-rp[j])), ig = __builtin_amdgcn_rcpf(1.0f + __expf(-ip[j])); const float la = sp[j] * r; const float d = 1.0f - __expf(la);
;                         o[j] = cvt_pk_bf16(d, __builtin_amdgcn_sqrtf(fmaxf(d * (2.0f - d), 0.f)) * (ig * xv[j])); }
;                     *(u32x4*)(AU + off) = o; }
	v_add_f32_e32 v100, v103, v100
	v_sub_f32_e32 v102, v101, v117
	v_mul_f32_e32 v100, v115, v100
	v_sub_f32_e32 v102, v116, v102
	v_add_f32_e32 v102, v102, v100
	v_add_f32_e32 v106, v101, v102
	v_mul_f32_e32 v107, v106, v106
	v_fmamk_f32 v100, v107, 0x3e9b6dac, v218
	v_fmaak_f32 v153, v107, v100, 0x3f2aaada
	v_cvt_f32_i32_e32 v100, v110
	v_sub_f32_e32 v101, v106, v101
	v_sub_f32_e32 v101, v102, v101
	v_ldexp_f32 v108, v101, 1
	v_mul_f32_e32 v101, v106, v107
	v_ldexp_f32 v103, v106, 1
	v_pk_mul_f32 v[106:107], v[100:101], v[152:153]
	v_mul_f32_e32 v74, 0xc1000000, v74
	v_fma_f32 v102, v100, s77, -v106
	v_fmac_f32_e32 v102, 0xb102e308, v100
	v_pk_add_f32 v[100:101], v[106:107], v[102:103]
	v_mul_f32_e32 v58, v58, v74
	v_sub_f32_e32 v103, v101, v103
	v_sub_f32_e32 v103, v107, v103
	v_add_f32_e32 v109, v108, v103
	v_mov_b32_e32 v108, v106
	v_pk_add_f32 v[106:107], v[100:101], v[106:107] neg_lo:[0,1] neg_hi:[0,1]
	v_pk_add_f32 v[110:111], v[100:101], v[108:109]
	v_mov_b32_e32 v103, v100
	v_mov_b32_e32 v107, v111
	v_pk_add_f32 v[114:115], v[102:103], v[106:107] neg_lo:[0,1] neg_hi:[0,1]
	v_pk_add_f32 v[102:103], v[102:103], v[106:107]
	v_mov_b32_e32 v108, v109
	v_pk_add_f32 v[106:107], v[102:103], v[100:101] op_sel:[1,0] op_sel_hi:[0,1] neg_lo:[0,1] neg_hi:[0,1]
	v_pk_add_f32 v[116:117], v[110:111], v[106:107] op_sel_hi:[1,0] neg_lo:[0,1] neg_hi:[0,1]
	v_mov_b32_e32 v110, v111
	v_mov_b32_e32 v111, v103
	v_pk_mov_b32 v[106:107], v[100:101], v[106:107] op_sel:[1,0]
	v_mov_b32_e32 v109, v100
	v_pk_add_f32 v[106:107], v[110:111], v[106:107] neg_lo:[0,1] neg_hi:[0,1]
	v_mov_b32_e32 v116, v114
	v_pk_add_f32 v[100:101], v[108:109], v[106:107] neg_lo:[0,1] neg_hi:[0,1]
	v_mov_b32_e32 v115, v103
	v_pk_add_f32 v[106:107], v[116:117], v[100:101]
	v_mul_f32_e32 v58, 0x3fb8aa3b, v58
	v_pk_add_f32 v[108:109], v[106:107], v[106:107] op_sel:[0,1] op_sel_hi:[1,0]
	v_exp_f32_e32 v58, v58
	v_pk_add_f32 v[102:103], v[102:103], v[108:109] op_sel:[1,0] op_sel_hi:[0,1]
	v_mov_b32_e32 v107, v102
	v_pk_add_f32 v[110:111], v[106:107], v[114:115] neg_lo:[0,1] neg_hi:[0,1]
	v_mov_b32_e32 v101, v108
	v_sub_f32_e32 v103, v106, v110
	v_pk_add_f32 v[100:101], v[100:101], v[110:111] neg_lo:[0,1] neg_hi:[0,1]
	v_sub_f32_e32 v103, v114, v103
	v_add_f32_e32 v100, v100, v103
	v_add_f32_e32 v100, v100, v101
	v_add_f32_e32 v100, v102, v100
	v_sub_f32_e32 v102, 2.0, v56
	v_mul_f32_e32 v102, v56, v102
	v_cndmask_b32_e32 v100, v219, v100, vcc
	v_cmp_ngt_f32_e32 vcc, -1.0, v75
	v_max_f32_e32 v102, 0, v102
	v_sqrt_f32_e32 v102, v102
	v_cndmask_b32_e32 v100, v220, v100, vcc
	v_cmp_neq_f32_e32 vcc, -1.0, v75
	v_add_f32_e32 v59, v59, v71
	v_mul_f32_e32 v59, 0xbfb8aa3b, v59
	v_cndmask_b32_e32 v100, v221, v100, vcc
	v_cmp_lt_f32_e64 vcc, |v75|, s79
	v_exp_f32_e32 v59, v59
	v_sub_f32_e32 v58, 1.0, v58
	v_cndmask_b32_e32 v75, v100, v75, vcc
	v_lshlrev_b32_e32 v100, 16, v98
	v_mul_f32_e32 v60, v60, v100
	v_mul_f32_e32 v60, v60, v102
	v_cvt_pk_bf16_f32 v56, v56, v60
	v_add_f32_e32 v60, v61, v65
	v_mul_f32_e32 v60, 0xbfb8aa3b, v60
	v_exp_f32_e32 v60, v60
	v_sub_f32_e32 v61, 2.0, v57
	v_mul_f32_e32 v61, v57, v61
	v_max_f32_e32 v61, 0, v61
	v_add_f32_e32 v60, 1.0, v60
	v_rcp_f32_e32 v60, v60
	v_sqrt_f32_e32 v61, v61
	v_and_b32_e32 v98, 0xffff0000, v98
	v_add_f32_e32 v59, 1.0, v59
	v_mul_f32_e32 v60, v60, v98
	v_mul_f32_e32 v60, v60, v61
	v_cvt_pk_bf16_f32 v57, v57, v60
	v_add_f32_e32 v60, v62, v66
	v_mul_f32_e32 v60, 0xbfb8aa3b, v60
	v_exp_f32_e32 v60, v60
	v_sub_f32_e32 v61, 2.0, v58
	v_mul_f32_e32 v61, v58, v61
	v_max_f32_e32 v61, 0, v61
	v_add_f32_e32 v60, 1.0, v60
	v_rcp_f32_e32 v60, v60
	v_rcp_f32_e32 v59, v59
	v_sqrt_f32_e32 v61, v61
	v_add_f32_e32 v48, v48, v68
	v_mul_f32_e32 v48, 0xbfb8aa3b, v48
	v_mul_f32_e32 v75, 0xc1000000, v75
	v_lshlrev_b32_e32 v101, 16, v99
	v_exp_f32_e32 v48, v48
	v_mul_f32_e32 v60, v60, v101
	v_mul_f32_e32 v59, v59, v75
	v_mul_f32_e32 v60, v60, v61
	v_mul_f32_e32 v59, 0x3fb8aa3b, v59
	v_cvt_pk_bf16_f32 v58, v58, v60
	v_add_f32_e32 v60, v63, v67
	v_exp_f32_e32 v59, v59
	v_mul_f32_e32 v60, 0xbfb8aa3b, v60
	v_add_f32_e32 v48, 1.0, v48
	v_exp_f32_e32 v60, v60
	v_rcp_f32_e32 v48, v48
	v_sub_f32_e32 v59, 1.0, v59
	v_sub_f32_e32 v61, 2.0, v59
	v_add_f32_e32 v60, 1.0, v60
	v_mul_f32_e32 v61, v59, v61
	v_mul_f32_e32 v48, v48, v72
	v_rcp_f32_e32 v60, v60
	v_max_f32_e32 v61, 0, v61
	v_mul_f32_e32 v48, 0x3fb8aa3b, v48
	v_sqrt_f32_e32 v61, v61
	v_add_f32_e32 v52, v52, v64
	v_exp_f32_e32 v48, v48
	v_add_f32_e32 v49, v49, v69
	v_mul_f32_e32 v52, 0xbfb8aa3b, v52
	v_mul_f32_e32 v49, 0xbfb8aa3b, v49
	v_and_b32_e32 v99, 0xffff0000, v99
	v_exp_f32_e32 v52, v52
	v_exp_f32_e32 v49, v49
	v_mul_f32_e32 v60, v60, v99
	v_mul_f32_e32 v60, v60, v61
	v_sub_f32_e32 v48, 1.0, v48
	v_cvt_pk_bf16_f32 v59, v59, v60
	v_sub_f32_e32 v60, 2.0, v48
	v_add_f32_e32 v52, 1.0, v52
	v_mul_f32_e32 v60, v48, v60
	v_add_f32_e32 v49, 1.0, v49
	v_rcp_f32_e32 v52, v52
	v_max_f32_e32 v60, 0, v60
	v_rcp_f32_e32 v49, v49
	v_sqrt_f32_e32 v60, v60
	global_store_dwordx4 v[128:129], v[56:59], off offset:64
	v_add_f32_e32 v50, v50, v70
	v_mul_f32_e32 v49, v49, v73
	v_lshlrev_b32_e32 v56, 16, v94
	v_mul_f32_e32 v52, v52, v56
	v_mul_f32_e32 v52, v52, v60
	v_mul_f32_e32 v49, 0x3fb8aa3b, v49
	v_cvt_pk_bf16_f32 v48, v48, v52
	v_add_f32_e32 v52, v53, v65
	v_exp_f32_e32 v49, v49
	v_mul_f32_e32 v52, 0xbfb8aa3b, v52
	v_mul_f32_e32 v50, 0xbfb8aa3b, v50
	v_exp_f32_e32 v52, v52
	v_exp_f32_e32 v50, v50
	v_sub_f32_e32 v49, 1.0, v49
	v_sub_f32_e32 v53, 2.0, v49
	v_add_f32_e32 v52, 1.0, v52
	v_mul_f32_e32 v53, v49, v53
	v_add_f32_e32 v50, 1.0, v50
	v_rcp_f32_e32 v52, v52
	v_max_f32_e32 v53, 0, v53
	v_rcp_f32_e32 v50, v50
	v_sqrt_f32_e32 v53, v53
; __device__ __forceinline__ unsigned cvt_pk_bf16(float lo, float hi) { const bf16x2_t r = __builtin_convertvector((f32x2){lo, hi}, bf16x2_t); return __builtin_bit_cast(unsigned, r); }
; __device__ __forceinline__ float bf_lo(unsigned w) { return __uint_as_float(w << 16); }
; __device__ __forceinline__ float bf_hi(unsigned w) { return __uint_as_float(w & 0xffff0000u); }
;     __device__ __forceinline__ void operator()(const AccT& acc, const Unit& u, int wr, int wc, int fr, int fq) const {
;     ...
;                 for (int m = 0; m < 4; ++m) { const size_t off = (size_t)(row0 + ai * HALF + m * 16) * DM + ch0 + 16 * n;
;                     const f32x4 rp = acc[ai][0][m][n] + bra, ip = acc[ai][1][m][n] + bri;
;                     const u32x2 w = xw[ai][m]; const float xv[4] = {bf_lo(w.x), bf_hi(w.x), bf_lo(w.y), bf_hi(w.y)};
;                     u32x4 o;
; #pragma unroll
;                     for (int j = 0; j < 4; ++j) { const float r = __builtin_amdgcn_rcpf(1.0f + __expf(-rp[j])), ig = __builtin_amdgcn_rcpf(1.0f + __expf(-ip[j])); const float la = sp[j] * r; const float d = 1.0f - __expf(la);
;                         o[j] = cvt_pk_bf16(d, __builtin_amdgcn_sqrtf(fmaxf(d * (2.0f - d), 0.f)) * (ig * xv[j])); }
;                     *(u32x4*)(AU + off) = o; }
	v_and_b32_e32 v57, 0xffff0000, v94
	v_mul_f32_e32 v52, v52, v57
	v_mul_f32_e32 v50, v50, v74
	v_mul_f32_e32 v52, v52, v53
	v_mul_f32_e32 v50, 0x3fb8aa3b, v50
	v_cvt_pk_bf16_f32 v49, v49, v52
	v_add_f32_e32 v52, v54, v66
	v_exp_f32_e32 v50, v50
	v_add_f32_e32 v51, v51, v71
	v_mul_f32_e32 v52, 0xbfb8aa3b, v52
	v_mul_f32_e32 v51, 0xbfb8aa3b, v51
	v_exp_f32_e32 v52, v52
	v_exp_f32_e32 v51, v51
	v_sub_f32_e32 v50, 1.0, v50
	v_sub_f32_e32 v53, 2.0, v50
	v_add_f32_e32 v52, 1.0, v52
	v_mul_f32_e32 v53, v50, v53
	v_add_f32_e32 v51, 1.0, v51
	v_rcp_f32_e32 v52, v52
	v_max_f32_e32 v53, 0, v53
	v_rcp_f32_e32 v51, v51
	v_sqrt_f32_e32 v53, v53
	v_add_f32_e32 v40, v40, v68
	v_mul_f32_e32 v40, 0xbfb8aa3b, v40
	v_lshlrev_b32_e32 v58, 16, v95
	v_exp_f32_e32 v40, v40
	v_mul_f32_e32 v52, v52, v58
	v_mul_f32_e32 v51, v51, v75
	v_mul_f32_e32 v52, v52, v53
	v_mul_f32_e32 v51, 0x3fb8aa3b, v51
	v_cvt_pk_bf16_f32 v50, v50, v52
	v_add_f32_e32 v52, v55, v67
	v_exp_f32_e32 v51, v51
	v_mul_f32_e32 v52, 0xbfb8aa3b, v52
	v_add_f32_e32 v40, 1.0, v40
	v_exp_f32_e32 v52, v52
	v_rcp_f32_e32 v40, v40
	v_sub_f32_e32 v51, 1.0, v51
	v_sub_f32_e32 v53, 2.0, v51
	v_add_f32_e32 v52, 1.0, v52
	v_mul_f32_e32 v53, v51, v53
	v_mul_f32_e32 v40, v40, v72
	v_rcp_f32_e32 v52, v52
	v_max_f32_e32 v53, 0, v53
	v_mul_f32_e32 v40, 0x3fb8aa3b, v40
	v_sqrt_f32_e32 v53, v53
	v_add_f32_e32 v44, v44, v64
	v_exp_f32_e32 v40, v40
	v_add_f32_e32 v41, v41, v69
	v_mul_f32_e32 v44, 0xbfb8aa3b, v44
	v_mul_f32_e32 v41, 0xbfb8aa3b, v41
	v_and_b32_e32 v59, 0xffff0000, v95
	v_exp_f32_e32 v44, v44
	v_exp_f32_e32 v41, v41
	v_mul_f32_e32 v52, v52, v59
	v_mul_f32_e32 v52, v52, v53
	v_sub_f32_e32 v40, 1.0, v40
	v_cvt_pk_bf16_f32 v51, v51, v52
	v_sub_f32_e32 v52, 2.0, v40
	v_add_f32_e32 v44, 1.0, v44
	v_mul_f32_e32 v52, v40, v52
	v_add_f32_e32 v41, 1.0, v41
	v_rcp_f32_e32 v44, v44
	v_max_f32_e32 v52, 0, v52
	v_rcp_f32_e32 v41, v41
	v_sqrt_f32_e32 v52, v52
	global_store_dwordx4 v[120:121], v[48:51], off offset:64
	v_add_f32_e32 v42, v42, v70
	v_mul_f32_e32 v41, v41, v73
	v_lshlrev_b32_e32 v48, 16, v92
	v_mul_f32_e32 v44, v44, v48
	v_mul_f32_e32 v44, v44, v52
	v_mul_f32_e32 v41, 0x3fb8aa3b, v41
	v_cvt_pk_bf16_f32 v40, v40, v44
	v_add_f32_e32 v44, v45, v65
	v_exp_f32_e32 v41, v41
	v_mul_f32_e32 v44, 0xbfb8aa3b, v44
	v_mul_f32_e32 v42, 0xbfb8aa3b, v42
	v_exp_f32_e32 v44, v44
	v_exp_f32_e32 v42, v42
	v_sub_f32_e32 v41, 1.0, v41
	v_sub_f32_e32 v45, 2.0, v41
	v_add_f32_e32 v44, 1.0, v44
	v_mul_f32_e32 v45, v41, v45
	v_add_f32_e32 v42, 1.0, v42
	v_rcp_f32_e32 v44, v44
	v_max_f32_e32 v45, 0, v45
	v_rcp_f32_e32 v42, v42
	v_sqrt_f32_e32 v45, v45
	v_and_b32_e32 v49, 0xffff0000, v92
	v_mul_f32_e32 v44, v44, v49
	v_mul_f32_e32 v42, v42, v74
	v_mul_f32_e32 v44, v44, v45
	v_mul_f32_e32 v42, 0x3fb8aa3b, v42
	v_cvt_pk_bf16_f32 v41, v41, v44
	v_add_f32_e32 v44, v46, v66
	v_exp_f32_e32 v42, v42
	v_add_f32_e32 v43, v43, v71
	v_mul_f32_e32 v44, 0xbfb8aa3b, v44
	v_mul_f32_e32 v43, 0xbfb8aa3b, v43
	v_exp_f32_e32 v44, v44
	v_exp_f32_e32 v43, v43
	v_sub_f32_e32 v42, 1.0, v42
	v_sub_f32_e32 v45, 2.0, v42
	v_add_f32_e32 v44, 1.0, v44
	v_mul_f32_e32 v45, v42, v45
	v_add_f32_e32 v43, 1.0, v43
	v_rcp_f32_e32 v44, v44
	v_max_f32_e32 v45, 0, v45
	v_rcp_f32_e32 v43, v43
	v_sqrt_f32_e32 v45, v45
	v_add_f32_e32 v32, v32, v68
	v_mul_f32_e32 v32, 0xbfb8aa3b, v32
	v_lshlrev_b32_e32 v50, 16, v93
	v_exp_f32_e32 v32, v32
	v_mul_f32_e32 v44, v44, v50
	v_mul_f32_e32 v43, v43, v75
	v_mul_f32_e32 v44, v44, v45
	v_mul_f32_e32 v43, 0x3fb8aa3b, v43
	v_cvt_pk_bf16_f32 v42, v42, v44
	v_add_f32_e32 v44, v47, v67
	v_exp_f32_e32 v43, v43
	v_mul_f32_e32 v44, 0xbfb8aa3b, v44
	v_add_f32_e32 v32, 1.0, v32
	v_exp_f32_e32 v44, v44
	v_rcp_f32_e32 v32, v32
	v_sub_f32_e32 v43, 1.0, v43
	v_sub_f32_e32 v45, 2.0, v43
	v_add_f32_e32 v44, 1.0, v44
	v_mul_f32_e32 v45, v43, v45
	v_mul_f32_e32 v32, v32, v72
	v_rcp_f32_e32 v44, v44
	v_max_f32_e32 v45, 0, v45
	v_mul_f32_e32 v32, 0x3fb8aa3b, v32
	v_sqrt_f32_e32 v45, v45
	v_add_f32_e32 v36, v36, v64
	v_exp_f32_e32 v32, v32
	v_add_f32_e32 v33, v33, v69
	v_mul_f32_e32 v36, 0xbfb8aa3b, v36
	v_mul_f32_e32 v33, 0xbfb8aa3b, v33
	v_and_b32_e32 v51, 0xffff0000, v93
	v_exp_f32_e32 v36, v36
	v_exp_f32_e32 v33, v33
	v_mul_f32_e32 v44, v44, v51
	v_mul_f32_e32 v44, v44, v45
	v_sub_f32_e32 v32, 1.0, v32
	v_cvt_pk_bf16_f32 v43, v43, v44
	v_sub_f32_e32 v44, 2.0, v32
	v_add_f32_e32 v36, 1.0, v36
	v_mul_f32_e32 v44, v32, v44
	v_add_f32_e32 v33, 1.0, v33
	v_rcp_f32_e32 v36, v36
	v_max_f32_e32 v44, 0, v44
	v_rcp_f32_e32 v33, v33
	v_sqrt_f32_e32 v44, v44
	global_store_dwordx4 v[112:113], v[40:43], off offset:64
	v_add_f32_e32 v34, v34, v70
	v_mul_f32_e32 v33, v33, v73
	v_lshlrev_b32_e32 v40, 16, v90
	v_mul_f32_e32 v36, v36, v40
	v_mul_f32_e32 v36, v36, v44
	v_mul_f32_e32 v33, 0x3fb8aa3b, v33
	v_cvt_pk_bf16_f32 v32, v32, v36
	v_add_f32_e32 v36, v37, v65
	v_exp_f32_e32 v33, v33
	v_mul_f32_e32 v36, 0xbfb8aa3b, v36
	v_mul_f32_e32 v34, 0xbfb8aa3b, v34
	v_exp_f32_e32 v36, v36
	v_exp_f32_e32 v34, v34
	v_sub_f32_e32 v33, 1.0, v33
	v_sub_f32_e32 v37, 2.0, v33
	v_add_f32_e32 v36, 1.0, v36
	v_mul_f32_e32 v37, v33, v37
	v_add_f32_e32 v34, 1.0, v34
	v_rcp_f32_e32 v36, v36
	v_max_f32_e32 v37, 0, v37
	v_rcp_f32_e32 v34, v34
	v_sqrt_f32_e32 v37, v37
	v_and_b32_e32 v41, 0xffff0000, v90
	v_mul_f32_e32 v36, v36, v41
	v_mul_f32_e32 v34, v34, v74
	v_mul_f32_e32 v36, v36, v37
	v_mul_f32_e32 v34, 0x3fb8aa3b, v34
	v_cvt_pk_bf16_f32 v33, v33, v36
	v_add_f32_e32 v36, v38, v66
	v_exp_f32_e32 v34, v34
	v_add_f32_e32 v35, v35, v71
	v_mul_f32_e32 v36, 0xbfb8aa3b, v36
	v_mul_f32_e32 v35, 0xbfb8aa3b, v35
	v_exp_f32_e32 v36, v36
	v_exp_f32_e32 v35, v35
	v_sub_f32_e32 v34, 1.0, v34
; __device__ __forceinline__ unsigned cvt_pk_bf16(float lo, float hi) { const bf16x2_t r = __builtin_convertvector((f32x2){lo, hi}, bf16x2_t); return __builtin_bit_cast(unsigned, r); }
; __device__ __forceinline__ float bf_lo(unsigned w) { return __uint_as_float(w << 16); }
; __device__ __forceinline__ float bf_hi(unsigned w) { return __uint_as_float(w & 0xffff0000u); }
;     __device__ __forceinline__ void operator()(const AccT& acc, const Unit& u, int wr, int wc, int fr, int fq) const {
;     ...
;                 for (int m = 0; m < 4; ++m) { const size_t off = (size_t)(row0 + ai * HALF + m * 16) * DM + ch0 + 16 * n;
;                     const f32x4 rp = acc[ai][0][m][n] + bra, ip = acc[ai][1][m][n] + bri;
;                     const u32x2 w = xw[ai][m]; const float xv[4] = {bf_lo(w.x), bf_hi(w.x), bf_lo(w.y), bf_hi(w.y)};
;                     u32x4 o;
; #pragma unroll
;                     for (int j = 0; j < 4; ++j) { const float r = __builtin_amdgcn_rcpf(1.0f + __expf(-rp[j])), ig = __builtin_amdgcn_rcpf(1.0f + __expf(-ip[j])); const float la = sp[j] * r; const float d = 1.0f - __expf(la);
;                         o[j] = cvt_pk_bf16(d, __builtin_amdgcn_sqrtf(fmaxf(d * (2.0f - d), 0.f)) * (ig * xv[j])); }
;                     *(u32x4*)(AU + off) = o; }
	v_sub_f32_e32 v37, 2.0, v34
	v_add_f32_e32 v36, 1.0, v36
	v_mul_f32_e32 v37, v34, v37
	v_add_f32_e32 v35, 1.0, v35
	v_rcp_f32_e32 v36, v36
	v_max_f32_e32 v37, 0, v37
	v_rcp_f32_e32 v35, v35
	v_sqrt_f32_e32 v37, v37
	v_add_f32_e32 v24, v24, v68
	v_mul_f32_e32 v24, 0xbfb8aa3b, v24
	v_lshlrev_b32_e32 v42, 16, v91
	v_exp_f32_e32 v24, v24
	v_mul_f32_e32 v36, v36, v42
	v_mul_f32_e32 v35, v35, v75
	v_mul_f32_e32 v36, v36, v37
	v_mul_f32_e32 v35, 0x3fb8aa3b, v35
	v_cvt_pk_bf16_f32 v34, v34, v36
	v_add_f32_e32 v36, v39, v67
	v_exp_f32_e32 v35, v35
	v_mul_f32_e32 v36, 0xbfb8aa3b, v36
	v_add_f32_e32 v24, 1.0, v24
	v_exp_f32_e32 v36, v36
	v_rcp_f32_e32 v24, v24
	v_sub_f32_e32 v35, 1.0, v35
	v_sub_f32_e32 v37, 2.0, v35
	v_add_f32_e32 v36, 1.0, v36
	v_mul_f32_e32 v37, v35, v37
	v_mul_f32_e32 v24, v24, v72
	v_rcp_f32_e32 v36, v36
	v_max_f32_e32 v37, 0, v37
	v_mul_f32_e32 v24, 0x3fb8aa3b, v24
	v_sqrt_f32_e32 v37, v37
	v_add_f32_e32 v28, v28, v64
	v_exp_f32_e32 v24, v24
	v_add_f32_e32 v25, v25, v69
	v_mul_f32_e32 v28, 0xbfb8aa3b, v28
	v_mul_f32_e32 v25, 0xbfb8aa3b, v25
	v_and_b32_e32 v43, 0xffff0000, v91
	v_exp_f32_e32 v28, v28
	v_exp_f32_e32 v25, v25
	v_mul_f32_e32 v36, v36, v43
	v_mul_f32_e32 v36, v36, v37
	v_sub_f32_e32 v24, 1.0, v24
	v_cvt_pk_bf16_f32 v35, v35, v36
	v_sub_f32_e32 v36, 2.0, v24
	v_add_f32_e32 v28, 1.0, v28
	v_mul_f32_e32 v36, v24, v36
	v_add_f32_e32 v25, 1.0, v25
	v_rcp_f32_e32 v28, v28
	v_max_f32_e32 v36, 0, v36
	v_rcp_f32_e32 v25, v25
	v_sqrt_f32_e32 v36, v36
	global_store_dwordx4 v[104:105], v[32:35], off offset:64
	v_add_f32_e32 v26, v26, v70
	v_mul_f32_e32 v25, v25, v73
	v_lshlrev_b32_e32 v32, 16, v86
	v_mul_f32_e32 v28, v28, v32
	v_mul_f32_e32 v28, v28, v36
	v_mul_f32_e32 v25, 0x3fb8aa3b, v25
	v_cvt_pk_bf16_f32 v24, v24, v28
	v_add_f32_e32 v28, v29, v65
	v_exp_f32_e32 v25, v25
	v_mul_f32_e32 v28, 0xbfb8aa3b, v28
	v_mul_f32_e32 v26, 0xbfb8aa3b, v26
	v_exp_f32_e32 v28, v28
	v_exp_f32_e32 v26, v26
	v_sub_f32_e32 v25, 1.0, v25
	v_sub_f32_e32 v29, 2.0, v25
	v_add_f32_e32 v28, 1.0, v28
	v_mul_f32_e32 v29, v25, v29
	v_add_f32_e32 v26, 1.0, v26
	v_rcp_f32_e32 v28, v28
	v_max_f32_e32 v29, 0, v29
	v_rcp_f32_e32 v26, v26
	v_sqrt_f32_e32 v29, v29
	v_and_b32_e32 v33, 0xffff0000, v86
	v_mul_f32_e32 v28, v28, v33
	v_mul_f32_e32 v26, v26, v74
	v_mul_f32_e32 v28, v28, v29
	v_mul_f32_e32 v26, 0x3fb8aa3b, v26
	v_cvt_pk_bf16_f32 v25, v25, v28
	v_add_f32_e32 v28, v30, v66
	v_exp_f32_e32 v26, v26
	v_add_f32_e32 v27, v27, v71
	v_mul_f32_e32 v28, 0xbfb8aa3b, v28
	v_mul_f32_e32 v27, 0xbfb8aa3b, v27
	v_exp_f32_e32 v28, v28
	v_exp_f32_e32 v27, v27
	v_sub_f32_e32 v26, 1.0, v26
	v_sub_f32_e32 v29, 2.0, v26
	v_add_f32_e32 v28, 1.0, v28
	v_mul_f32_e32 v29, v26, v29
	v_add_f32_e32 v27, 1.0, v27
	v_rcp_f32_e32 v28, v28
	v_max_f32_e32 v29, 0, v29
	v_rcp_f32_e32 v27, v27
	v_sqrt_f32_e32 v29, v29
	v_add_f32_e32 v16, v16, v68
	v_mul_f32_e32 v16, 0xbfb8aa3b, v16
	v_lshlrev_b32_e32 v34, 16, v87
	v_exp_f32_e32 v16, v16
	v_mul_f32_e32 v28, v28, v34
	v_mul_f32_e32 v27, v27, v75
	v_mul_f32_e32 v28, v28, v29
	v_mul_f32_e32 v27, 0x3fb8aa3b, v27
	v_cvt_pk_bf16_f32 v26, v26, v28
	v_add_f32_e32 v28, v31, v67
	v_exp_f32_e32 v27, v27
	v_mul_f32_e32 v28, 0xbfb8aa3b, v28
	v_add_f32_e32 v16, 1.0, v16
	v_exp_f32_e32 v28, v28
	v_rcp_f32_e32 v16, v16
	v_sub_f32_e32 v27, 1.0, v27
	v_sub_f32_e32 v29, 2.0, v27
	v_add_f32_e32 v28, 1.0, v28
	v_mul_f32_e32 v29, v27, v29
	v_mul_f32_e32 v16, v16, v72
	v_rcp_f32_e32 v28, v28
	v_max_f32_e32 v29, 0, v29
	v_mul_f32_e32 v16, 0x3fb8aa3b, v16
	v_sqrt_f32_e32 v29, v29
	v_add_f32_e32 v20, v20, v64
	v_exp_f32_e32 v16, v16
	v_add_f32_e32 v17, v17, v69
	v_mul_f32_e32 v20, 0xbfb8aa3b, v20
	v_mul_f32_e32 v17, 0xbfb8aa3b, v17
	v_and_b32_e32 v35, 0xffff0000, v87
	v_exp_f32_e32 v20, v20
	v_exp_f32_e32 v17, v17
	v_mul_f32_e32 v28, v28, v35
	v_mul_f32_e32 v28, v28, v29
	v_sub_f32_e32 v16, 1.0, v16
	v_cvt_pk_bf16_f32 v27, v27, v28
	v_sub_f32_e32 v28, 2.0, v16
	v_add_f32_e32 v20, 1.0, v20
	v_mul_f32_e32 v28, v16, v28
	v_add_f32_e32 v17, 1.0, v17
	v_rcp_f32_e32 v20, v20
	v_max_f32_e32 v28, 0, v28
	v_rcp_f32_e32 v17, v17
	v_sqrt_f32_e32 v28, v28
	global_store_dwordx4 v[96:97], v[24:27], off offset:64
	v_add_f32_e32 v18, v18, v70
	v_mul_f32_e32 v17, v17, v73
	v_lshlrev_b32_e32 v24, 16, v84
	v_mul_f32_e32 v20, v20, v24
	v_mul_f32_e32 v20, v20, v28
	v_mul_f32_e32 v17, 0x3fb8aa3b, v17
	v_cvt_pk_bf16_f32 v16, v16, v20
	v_add_f32_e32 v20, v21, v65
	v_exp_f32_e32 v17, v17
	v_mul_f32_e32 v20, 0xbfb8aa3b, v20
	v_mul_f32_e32 v18, 0xbfb8aa3b, v18
	v_exp_f32_e32 v20, v20
	v_exp_f32_e32 v18, v18
	v_sub_f32_e32 v17, 1.0, v17
	v_sub_f32_e32 v21, 2.0, v17
	v_add_f32_e32 v20, 1.0, v20
	v_mul_f32_e32 v21, v17, v21
	v_add_f32_e32 v18, 1.0, v18
	v_rcp_f32_e32 v20, v20
	v_max_f32_e32 v21, 0, v21
	v_rcp_f32_e32 v18, v18
	v_sqrt_f32_e32 v21, v21
	v_and_b32_e32 v25, 0xffff0000, v84
	v_mul_f32_e32 v20, v20, v25
	v_mul_f32_e32 v18, v18, v74
	v_mul_f32_e32 v20, v20, v21
	v_mul_f32_e32 v18, 0x3fb8aa3b, v18
	v_cvt_pk_bf16_f32 v17, v17, v20
	v_add_f32_e32 v20, v22, v66
	v_exp_f32_e32 v18, v18
	v_add_f32_e32 v19, v19, v71
	v_mul_f32_e32 v20, 0xbfb8aa3b, v20
	v_mul_f32_e32 v19, 0xbfb8aa3b, v19
	v_exp_f32_e32 v20, v20
	v_exp_f32_e32 v19, v19
	v_sub_f32_e32 v18, 1.0, v18
	v_sub_f32_e32 v21, 2.0, v18
	v_add_f32_e32 v20, 1.0, v20
	v_mul_f32_e32 v21, v18, v21
	v_add_f32_e32 v19, 1.0, v19
	v_rcp_f32_e32 v20, v20
	v_max_f32_e32 v21, 0, v21
	v_rcp_f32_e32 v19, v19
	v_sqrt_f32_e32 v21, v21
	v_add_f32_e32 v8, v8, v68
	v_mul_f32_e32 v8, 0xbfb8aa3b, v8
	v_lshlrev_b32_e32 v26, 16, v85
	v_exp_f32_e32 v8, v8
	v_mul_f32_e32 v20, v20, v26
; __device__ __forceinline__ unsigned cvt_pk_bf16(float lo, float hi) { const bf16x2_t r = __builtin_convertvector((f32x2){lo, hi}, bf16x2_t); return __builtin_bit_cast(unsigned, r); }
; __device__ __forceinline__ float bf_lo(unsigned w) { return __uint_as_float(w << 16); }
; __device__ __forceinline__ float bf_hi(unsigned w) { return __uint_as_float(w & 0xffff0000u); }
; template <class Epi>
; __device__ __forceinline__ void gemm_phase(LAS unsigned char* lds, const bf16_t* A, int lda, const bf16_t* Bt, int ldb, int M, int N, int K, int asel, const Epi& E, const int fixed_round = -1) {
;     ...
;         if (!has_next) break;
;     __device__ __forceinline__ void operator()(const AccT& acc, const Unit& u, int wr, int wc, int fr, int fq) const {
;     ...
;                 for (int m = 0; m < 4; ++m) { const size_t off = (size_t)(row0 + ai * HALF + m * 16) * DM + ch0 + 16 * n;
;                     const f32x4 rp = acc[ai][0][m][n] + bra, ip = acc[ai][1][m][n] + bri;
;                     const u32x2 w = xw[ai][m]; const float xv[4] = {bf_lo(w.x), bf_hi(w.x), bf_lo(w.y), bf_hi(w.y)};
;                     u32x4 o;
; #pragma unroll
;                     for (int j = 0; j < 4; ++j) { const float r = __builtin_amdgcn_rcpf(1.0f + __expf(-rp[j])), ig = __builtin_amdgcn_rcpf(1.0f + __expf(-ip[j])); const float la = sp[j] * r; const float d = 1.0f - __expf(la);
;                         o[j] = cvt_pk_bf16(d, __builtin_amdgcn_sqrtf(fmaxf(d * (2.0f - d), 0.f)) * (ig * xv[j])); }
;                     *(u32x4*)(AU + off) = o; }
	v_mul_f32_e32 v19, v19, v75
	v_mul_f32_e32 v20, v20, v21
	v_mul_f32_e32 v19, 0x3fb8aa3b, v19
	v_cvt_pk_bf16_f32 v18, v18, v20
	v_add_f32_e32 v20, v23, v67
	v_exp_f32_e32 v19, v19
	v_mul_f32_e32 v20, 0xbfb8aa3b, v20
	v_add_f32_e32 v8, 1.0, v8
	v_exp_f32_e32 v20, v20
	v_rcp_f32_e32 v8, v8
	v_sub_f32_e32 v19, 1.0, v19
	v_sub_f32_e32 v21, 2.0, v19
	v_add_f32_e32 v20, 1.0, v20
	v_mul_f32_e32 v21, v19, v21
	v_mul_f32_e32 v8, v8, v72
	v_rcp_f32_e32 v20, v20
	v_max_f32_e32 v21, 0, v21
	v_mul_f32_e32 v8, 0x3fb8aa3b, v8
	v_sqrt_f32_e32 v21, v21
	v_add_f32_e32 v12, v12, v64
	v_exp_f32_e32 v8, v8
	v_add_f32_e32 v9, v9, v69
	v_mul_f32_e32 v12, 0xbfb8aa3b, v12
	v_mul_f32_e32 v9, 0xbfb8aa3b, v9
	v_and_b32_e32 v27, 0xffff0000, v85
	v_exp_f32_e32 v12, v12
	v_exp_f32_e32 v9, v9
	v_mul_f32_e32 v20, v20, v27
	v_mul_f32_e32 v20, v20, v21
	v_sub_f32_e32 v8, 1.0, v8
	v_cvt_pk_bf16_f32 v19, v19, v20
	v_sub_f32_e32 v20, 2.0, v8
	v_add_f32_e32 v12, 1.0, v12
	v_mul_f32_e32 v20, v8, v20
	v_add_f32_e32 v9, 1.0, v9
	v_rcp_f32_e32 v12, v12
	v_max_f32_e32 v20, 0, v20
	v_rcp_f32_e32 v9, v9
	v_sqrt_f32_e32 v20, v20
	global_store_dwordx4 v[88:89], v[16:19], off offset:64
	v_add_f32_e32 v10, v10, v70
	v_mul_f32_e32 v9, v9, v73
	v_lshlrev_b32_e32 v16, 16, v82
	v_mul_f32_e32 v12, v12, v16
	v_mul_f32_e32 v12, v12, v20
	v_mul_f32_e32 v9, 0x3fb8aa3b, v9
	v_cvt_pk_bf16_f32 v8, v8, v12
	v_add_f32_e32 v12, v13, v65
	v_exp_f32_e32 v9, v9
	v_mul_f32_e32 v12, 0xbfb8aa3b, v12
	v_mul_f32_e32 v10, 0xbfb8aa3b, v10
	v_exp_f32_e32 v12, v12
	v_exp_f32_e32 v10, v10
	v_sub_f32_e32 v9, 1.0, v9
	v_sub_f32_e32 v13, 2.0, v9
	v_add_f32_e32 v12, 1.0, v12
	v_mul_f32_e32 v13, v9, v13
	v_add_f32_e32 v10, 1.0, v10
	v_rcp_f32_e32 v12, v12
	v_max_f32_e32 v13, 0, v13
	v_rcp_f32_e32 v10, v10
	v_sqrt_f32_e32 v13, v13
	v_and_b32_e32 v17, 0xffff0000, v82
	v_mul_f32_e32 v12, v12, v17
	v_mul_f32_e32 v10, v10, v74
	v_mul_f32_e32 v12, v12, v13
	v_mul_f32_e32 v10, 0x3fb8aa3b, v10
	v_cvt_pk_bf16_f32 v9, v9, v12
	v_add_f32_e32 v12, v14, v66
	v_exp_f32_e32 v10, v10
	v_add_f32_e32 v11, v11, v71
	v_mul_f32_e32 v12, 0xbfb8aa3b, v12
	v_mul_f32_e32 v11, 0xbfb8aa3b, v11
	v_exp_f32_e32 v12, v12
	v_exp_f32_e32 v11, v11
	v_sub_f32_e32 v10, 1.0, v10
	v_sub_f32_e32 v13, 2.0, v10
	v_add_f32_e32 v12, 1.0, v12
	v_mul_f32_e32 v13, v10, v13
	v_add_f32_e32 v11, 1.0, v11
	v_rcp_f32_e32 v12, v12
	v_max_f32_e32 v13, 0, v13
	v_rcp_f32_e32 v11, v11
	v_sqrt_f32_e32 v13, v13
	v_add_f32_e32 v0, v0, v68
	v_mul_f32_e32 v0, 0xbfb8aa3b, v0
	v_lshlrev_b32_e32 v18, 16, v83
	v_exp_f32_e32 v0, v0
	v_mul_f32_e32 v12, v12, v18
	v_mul_f32_e32 v11, v11, v75
	v_mul_f32_e32 v12, v12, v13
	v_mul_f32_e32 v11, 0x3fb8aa3b, v11
	v_cvt_pk_bf16_f32 v10, v10, v12
	v_add_f32_e32 v12, v15, v67
	v_exp_f32_e32 v11, v11
	v_mul_f32_e32 v12, 0xbfb8aa3b, v12
	v_add_f32_e32 v0, 1.0, v0
	v_exp_f32_e32 v12, v12
	v_rcp_f32_e32 v0, v0
	v_sub_f32_e32 v11, 1.0, v11
	v_sub_f32_e32 v13, 2.0, v11
	v_add_f32_e32 v12, 1.0, v12
	v_mul_f32_e32 v13, v11, v13
	v_mul_f32_e32 v0, v0, v72
	v_rcp_f32_e32 v12, v12
	v_max_f32_e32 v13, 0, v13
	v_mul_f32_e32 v0, 0x3fb8aa3b, v0
	v_sqrt_f32_e32 v13, v13
	v_add_f32_e32 v4, v4, v64
	v_exp_f32_e32 v0, v0
	v_add_f32_e32 v1, v1, v69
	v_mul_f32_e32 v4, 0xbfb8aa3b, v4
	v_mul_f32_e32 v1, 0xbfb8aa3b, v1
	v_and_b32_e32 v19, 0xffff0000, v83
	v_exp_f32_e32 v4, v4
	v_exp_f32_e32 v1, v1
	v_mul_f32_e32 v12, v12, v19
	v_mul_f32_e32 v12, v12, v13
	v_sub_f32_e32 v0, 1.0, v0
	v_cvt_pk_bf16_f32 v11, v11, v12
	v_sub_f32_e32 v12, 2.0, v0
	v_add_f32_e32 v4, 1.0, v4
	v_mul_f32_e32 v12, v0, v12
	v_add_f32_e32 v1, 1.0, v1
	v_rcp_f32_e32 v4, v4
	v_max_f32_e32 v12, 0, v12
	v_rcp_f32_e32 v1, v1
	v_sqrt_f32_e32 v12, v12
	global_store_dwordx4 v[80:81], v[8:11], off offset:64
	v_add_f32_e32 v2, v2, v70
	v_mul_f32_e32 v1, v1, v73
	v_lshlrev_b32_e32 v8, 16, v78
	v_mul_f32_e32 v4, v4, v8
	v_mul_f32_e32 v4, v4, v12
	v_mul_f32_e32 v1, 0x3fb8aa3b, v1
	v_cvt_pk_bf16_f32 v0, v0, v4
	v_add_f32_e32 v4, v5, v65
	v_exp_f32_e32 v1, v1
	v_mul_f32_e32 v4, 0xbfb8aa3b, v4
	v_mul_f32_e32 v2, 0xbfb8aa3b, v2
	v_exp_f32_e32 v4, v4
	v_exp_f32_e32 v2, v2
	v_sub_f32_e32 v1, 1.0, v1
	v_sub_f32_e32 v5, 2.0, v1
	v_add_f32_e32 v4, 1.0, v4
	v_mul_f32_e32 v5, v1, v5
	v_add_f32_e32 v2, 1.0, v2
	v_rcp_f32_e32 v4, v4
	v_max_f32_e32 v5, 0, v5
	v_rcp_f32_e32 v2, v2
	v_sqrt_f32_e32 v5, v5
	v_and_b32_e32 v9, 0xffff0000, v78
	v_mul_f32_e32 v4, v4, v9
	v_mul_f32_e32 v2, v2, v74
	v_mul_f32_e32 v4, v4, v5
	v_mul_f32_e32 v2, 0x3fb8aa3b, v2
	v_cvt_pk_bf16_f32 v1, v1, v4
	v_add_f32_e32 v4, v6, v66
	v_exp_f32_e32 v2, v2
	v_add_f32_e32 v3, v3, v71
	v_mul_f32_e32 v4, 0xbfb8aa3b, v4
	v_mul_f32_e32 v3, 0xbfb8aa3b, v3
	v_exp_f32_e32 v4, v4
	v_exp_f32_e32 v3, v3
	v_sub_f32_e32 v2, 1.0, v2
	v_sub_f32_e32 v5, 2.0, v2
	v_add_f32_e32 v4, 1.0, v4
	v_mul_f32_e32 v5, v2, v5
	v_add_f32_e32 v3, 1.0, v3
	v_rcp_f32_e32 v4, v4
	v_max_f32_e32 v5, 0, v5
	v_rcp_f32_e32 v3, v3
	v_sqrt_f32_e32 v5, v5
	v_lshlrev_b32_e32 v10, 16, v79
	v_mul_f32_e32 v4, v4, v10
	v_mul_f32_e32 v3, v3, v75
	v_mul_f32_e32 v4, v4, v5
	v_mul_f32_e32 v3, 0x3fb8aa3b, v3
	v_cvt_pk_bf16_f32 v2, v2, v4
	v_add_f32_e32 v4, v7, v67
	v_exp_f32_e32 v3, v3
	v_mul_f32_e32 v4, 0xbfb8aa3b, v4
	v_exp_f32_e32 v4, v4
	v_and_b32_e32 v11, 0xffff0000, v79
	v_sub_f32_e32 v3, 1.0, v3
	v_sub_f32_e32 v5, 2.0, v3
	v_add_f32_e32 v4, 1.0, v4
	v_mul_f32_e32 v5, v3, v5
	v_rcp_f32_e32 v4, v4
	v_max_f32_e32 v5, 0, v5
	v_sqrt_f32_e32 v5, v5
	s_andn2_b64 vcc, exec, s[4:5]
	v_mul_f32_e32 v4, v4, v11
	v_mul_f32_e32 v4, v4, v5
	v_cvt_pk_bf16_f32 v3, v3, v4
	global_store_dwordx4 v[76:77], v[0:3], off offset:64
	s_cbranch_vccz .LBB0_946

; template <class Epi>
; __device__ __forceinline__ void gemm_phase(LAS unsigned char* lds, const bf16_t* A, int lda, const bf16_t* Bt, int ldb, int M, int N, int K, int asel, const Epi& E, const int fixed_round = -1) {
;     ...
;         const bool has_next = (fixed_round < 0) && S.next(ui + 1, nxt);
;         const char* nA = has_next ? PG8_ABASE(nxt) : cA; const char* nB = has_next ? (const char*)Bt + (size_t)nxt.pn * tstepB : cB;
;     ...
; #pragma unroll
;         for (int a = 0; a < 2; ++a)
; #pragma unroll
;             for (int b = 0; b < 2; ++b)
; #pragma unroll
;                 for (int m = 0; m < 4; ++m)
; #pragma unroll
;                     for (int n = 0; n < 2; ++n) acc[a][b][m][n] = (f32x4){0.f, 0.f, 0.f, 0.f};
;         cur = nxt; cA = nA; cB = nB; ++ui;
.LBB0_1222:
	s_ashr_i32 s29, s28, 31
	v_cmp_lt_i64_e32 vcc, s[40:41], v[140:141]
	s_lshl_b64 s[40:41], s[28:29], 20
	s_add_u32 s40, s38, s40
	s_addc_u32 s41, s39, s41
	s_and_b64 s[42:43], vcc, exec
	s_cselect_b32 s29, s41, s47
	s_cselect_b32 s66, s40, s46
	s_ashr_i32 s25, s24, 31
	s_lshl_b64 s[42:43], s[24:25], 20
	s_add_u32 s42, s52, s42
	s_addc_u32 s43, s53, s43
	s_and_b64 s[50:51], vcc, exec
	s_cselect_b32 s25, s43, s49
	s_cselect_b32 s67, s42, s48
	s_add_u32 s46, s46, 0x80080
	s_addc_u32 s47, s47, 0
	s_add_u32 s68, s48, 0x100
	v_mov_b32_e32 v0, 0
	s_addc_u32 s69, s49, 0
	s_mov_b32 s70, -2
	v_mov_b32_e32 v1, v0
	v_mov_b64_e32 v[2:3], 0
	v_mov_b64_e32 v[4:5], 0
	v_mov_b64_e32 v[6:7], 0
	v_mov_b64_e32 v[16:17], 0
	v_mov_b64_e32 v[18:19], 0
	v_mov_b64_e32 v[20:21], 0
	v_mov_b64_e32 v[22:23], 0
	v_mov_b64_e32 v[32:33], 0
	v_mov_b64_e32 v[34:35], 0
	v_mov_b64_e32 v[36:37], 0
	v_mov_b64_e32 v[38:39], 0
	v_mov_b64_e32 v[48:49], 0
	v_mov_b64_e32 v[50:51], 0
	v_mov_b64_e32 v[52:53], 0
	v_mov_b64_e32 v[54:55], 0
	v_mov_b64_e32 v[8:9], 0
	v_mov_b64_e32 v[10:11], 0
	v_mov_b64_e32 v[12:13], 0
	v_mov_b64_e32 v[14:15], 0
	v_mov_b64_e32 v[24:25], 0
	v_mov_b64_e32 v[26:27], 0
	v_mov_b64_e32 v[28:29], 0
	v_mov_b64_e32 v[30:31], 0
	v_mov_b64_e32 v[40:41], 0
	v_mov_b64_e32 v[42:43], 0
	v_mov_b64_e32 v[44:45], 0
	v_mov_b64_e32 v[46:47], 0
	v_mov_b64_e32 v[56:57], 0
	v_mov_b64_e32 v[58:59], 0
	v_mov_b64_e32 v[60:61], 0
	v_mov_b64_e32 v[62:63], 0
	v_mov_b64_e32 v[64:65], 0
	v_mov_b64_e32 v[66:67], 0
	v_mov_b64_e32 v[68:69], 0
	v_mov_b64_e32 v[70:71], 0
	v_mov_b64_e32 v[80:81], 0
	v_mov_b64_e32 v[82:83], 0
	v_mov_b64_e32 v[84:85], 0
	v_mov_b64_e32 v[86:87], 0
	v_mov_b64_e32 v[96:97], 0
	v_mov_b64_e32 v[98:99], 0
	v_mov_b64_e32 v[100:101], 0
	v_mov_b64_e32 v[102:103], 0
	v_mov_b64_e32 v[112:113], 0
	v_mov_b64_e32 v[114:115], 0
	v_mov_b64_e32 v[116:117], 0
	v_mov_b64_e32 v[118:119], 0
	v_mov_b64_e32 v[72:73], 0
	v_mov_b64_e32 v[74:75], 0
	v_mov_b64_e32 v[76:77], 0
	v_mov_b64_e32 v[78:79], 0
	v_mov_b64_e32 v[88:89], 0
	v_mov_b64_e32 v[90:91], 0
	v_mov_b64_e32 v[92:93], 0
	v_mov_b64_e32 v[94:95], 0
	v_mov_b64_e32 v[104:105], 0
	v_mov_b64_e32 v[106:107], 0
	v_mov_b64_e32 v[108:109], 0
	v_mov_b64_e32 v[110:111], 0
	v_mov_b64_e32 v[120:121], 0
	v_mov_b64_e32 v[122:123], 0
	v_mov_b64_e32 v[124:125], 0
	v_mov_b64_e32 v[126:127], 0
	s_branch .LBB0_1223
